# GEMM unit boundary: trailing half takes its re-offset barrier after S.next + preheader (flag in s32) so that work overlaps the leading half's first load phase
# baseline (speedup 1.0000x reference)
_Z10fwd_kernel4Args:
	s_load_dword s33, s[0:1], 0xc8
	s_load_dwordx8 s[36:43], s[0:1], 0xa8
	s_add_u32 s30, s0, 0xc0
	v_and_b32_e32 v1, 0x3ff, v0
	s_addc_u32 s31, s1, 0
	s_mov_b32 s3, 0
	s_mov_b32 s32, 0
	v_cmp_eq_u32_e64 s[26:27], 0, v1
	s_and_saveexec_b64 s[4:5], s[26:27]
	s_cbranch_execz .LBB0_2
	s_add_i32 s6, 0, 0x257f0
	v_mov_b32_e32 v2, 0
	v_mov_b32_e32 v3, s6
	s_add_i32 s6, 0, 0x257f4
	ds_write_b32 v3, v2
	v_mov_b32_e32 v3, s6
	ds_write_b32 v3, v2

.LBB0_169:
	v_cmp_gt_i32_e32 vcc, 1, v138
	s_cbranch_vccnz .LBB0_231
	v_lshl_add_u64 v[152:153], v[2:3], 0, s[22:23]
	v_add_u32_e32 v154, -2, v138
	s_waitcnt lgkmcnt(0)
	v_lshl_add_u64 v[150:151], v[4:5], 0, s[28:29]
	s_mov_b32 s7, 0
	s_cmp_eq_u32 s32, 1
	s_cbranch_scc0 .Lmy_nb_0
	s_mov_b32 s32, 0
	s_barrier
.Lmy_nb_0:
	s_nop 0
	v_readfirstlane_b32 s86, v152
	v_readfirstlane_b32 s87, v153
	v_readfirstlane_b32 s88, v150
	v_readfirstlane_b32 s89, v151
	v_readfirstlane_b32 s90, v146
	v_readfirstlane_b32 s91, v147
	v_readfirstlane_b32 s92, v148
	v_readfirstlane_b32 s93, v149
	v_readfirstlane_b32 s100, v154
	v_readfirstlane_b32 s101, v138
	v_add_u32_e32 v230, s76, v141
	v_add_u32_e32 v231, s77, v141
	v_add_u32_e32 v232, 0x18000, v141
	v_add_u32_e32 v233, 0x1c000, v141
	s_add_u32 s98, s86, 0xfffc0080
	s_addc_u32 s99, s87, -1
	s_cmp_eq_u32 s7, s100
	s_cselect_b64 s[94:95], s[90:91], s[98:99]
	s_cselect_b64 s[96:97], s[92:93], s[88:89]
	s_add_i32 s51, s7, 2
	s_nop 0
	s_mov_b32 m0, s78
	s_nop 0
	global_load_lds_dwordx4 v144, s[86:87]
	s_mov_b32 m0, s79
	s_nop 0
	global_load_lds_dwordx4 v142, s[86:87]
	ds_read_b128 v[164:167], v230
	ds_read_b128 v[168:171], v230 offset:1024
	ds_read_b128 v[172:175], v230 offset:2048
	ds_read_b128 v[176:179], v230 offset:3072
	ds_read_b128 v[180:183], v231
	ds_read_b128 v[184:187], v231 offset:1024
	ds_read_b128 v[188:191], v231 offset:2048
	ds_read_b128 v[192:195], v231 offset:3072
	ds_read_b128 v[196:199], v160
	ds_read_b128 v[200:203], v160 offset:1024
	ds_read_b128 v[204:207], v160 offset:2048
	ds_read_b128 v[208:211], v160 offset:3072
	ds_read_b128 v[212:215], v160 offset:4096
	ds_read_b128 v[216:219], v160 offset:5120
	ds_read_b128 v[220:223], v160 offset:6144
	ds_read_b128 v[224:227], v160 offset:7168
	s_waitcnt vmcnt(8)
	s_waitcnt lgkmcnt(0)
	s_setprio 1
	s_barrier
	v_mfma_f32_16x16x32_bf16 v[122:125], v[164:167], v[196:199], 0
	v_mfma_f32_16x16x32_bf16 v[118:121], v[172:175], v[196:199], 0
	v_mfma_f32_16x16x32_bf16 v[110:113], v[164:167], v[204:207], 0
	v_mfma_f32_16x16x32_bf16 v[102:105], v[172:175], v[204:207], 0
	v_mfma_f32_16x16x32_bf16 v[94:97], v[164:167], v[212:215], 0
	v_mfma_f32_16x16x32_bf16 v[86:89], v[172:175], v[212:215], 0
	v_mfma_f32_16x16x32_bf16 v[78:81], v[164:167], v[220:223], 0
	v_mfma_f32_16x16x32_bf16 v[70:73], v[172:175], v[220:223], 0
	v_mfma_f32_16x16x32_bf16 v[122:125], v[168:171], v[200:203], v[122:125]
	v_mfma_f32_16x16x32_bf16 v[118:121], v[176:179], v[200:203], v[118:121]
	v_mfma_f32_16x16x32_bf16 v[110:113], v[168:171], v[208:211], v[110:113]
	v_mfma_f32_16x16x32_bf16 v[102:105], v[176:179], v[208:211], v[102:105]
	v_mfma_f32_16x16x32_bf16 v[94:97], v[168:171], v[216:219], v[94:97]
	v_mfma_f32_16x16x32_bf16 v[86:89], v[176:179], v[216:219], v[86:89]
	v_mfma_f32_16x16x32_bf16 v[78:81], v[168:171], v[224:227], v[78:81]
	v_mfma_f32_16x16x32_bf16 v[70:73], v[176:179], v[224:227], v[70:73]
	s_setprio 0
	s_setprio 1
	v_mfma_f32_16x16x32_bf16 v[126:129], v[180:183], v[196:199], 0
	v_mfma_f32_16x16x32_bf16 v[114:117], v[188:191], v[196:199], 0
	v_mfma_f32_16x16x32_bf16 v[106:109], v[180:183], v[204:207], 0
	v_mfma_f32_16x16x32_bf16 v[98:101], v[188:191], v[204:207], 0
	v_mfma_f32_16x16x32_bf16 v[90:93], v[180:183], v[212:215], 0
	v_mfma_f32_16x16x32_bf16 v[82:85], v[188:191], v[212:215], 0
	v_mfma_f32_16x16x32_bf16 v[74:77], v[180:183], v[220:223], 0
	v_mfma_f32_16x16x32_bf16 v[66:69], v[188:191], v[220:223], 0
	v_mfma_f32_16x16x32_bf16 v[126:129], v[184:187], v[200:203], v[126:129]
	v_mfma_f32_16x16x32_bf16 v[114:117], v[192:195], v[200:203], v[114:117]
	v_mfma_f32_16x16x32_bf16 v[106:109], v[184:187], v[208:211], v[106:109]
	v_mfma_f32_16x16x32_bf16 v[98:101], v[192:195], v[208:211], v[98:101]
	v_mfma_f32_16x16x32_bf16 v[90:93], v[184:187], v[216:219], v[90:93]
	v_mfma_f32_16x16x32_bf16 v[82:85], v[192:195], v[216:219], v[82:85]
	v_mfma_f32_16x16x32_bf16 v[74:77], v[184:187], v[224:227], v[74:77]
	v_mfma_f32_16x16x32_bf16 v[66:69], v[192:195], v[224:227], v[66:69]
	s_barrier
	s_setprio 0
	s_add_u32 s98, s96, 0x40000
	s_addc_u32 s99, s97, 0
	s_mov_b32 m0, s80
	s_nop 0
	global_load_lds_dwordx4 v132, s[96:97]
	s_mov_b32 m0, s81
	s_add_i32 s7, s77, s47
	global_load_lds_dwordx4 v136, s[96:97]
	s_mov_b32 m0, s7
	s_nop 0
	global_load_lds_dwordx4 v132, s[98:99]
	s_add_i32 m0, s7, 0x2000
	s_nop 0
	global_load_lds_dwordx4 v136, s[98:99]
	s_mov_b32 m0, s57
	s_nop 0
	global_load_lds_dwordx4 v130, s[94:95]
	s_mov_b32 m0, s62
	s_nop 0
	global_load_lds_dwordx4 v134, s[94:95]
	ds_read_b128 v[196:199], v160 offset:16384
	ds_read_b128 v[200:203], v160 offset:17408
	ds_read_b128 v[204:207], v160 offset:18432
	ds_read_b128 v[208:211], v160 offset:19456
	ds_read_b128 v[212:215], v160 offset:20480
	ds_read_b128 v[216:219], v160 offset:21504
	ds_read_b128 v[220:223], v160 offset:22528
	ds_read_b128 v[224:227], v160 offset:23552
	s_waitcnt vmcnt(8)
	s_waitcnt lgkmcnt(0)
	s_setprio 1
	s_barrier
	v_mfma_f32_16x16x32_bf16 v[62:65], v[164:167], v[196:199], 0
	v_mfma_f32_16x16x32_bf16 v[54:57], v[172:175], v[196:199], 0
	v_mfma_f32_16x16x32_bf16 v[46:49], v[164:167], v[204:207], 0
	v_mfma_f32_16x16x32_bf16 v[38:41], v[172:175], v[204:207], 0
	v_mfma_f32_16x16x32_bf16 v[30:33], v[164:167], v[212:215], 0
	v_mfma_f32_16x16x32_bf16 v[22:25], v[172:175], v[212:215], 0
	v_mfma_f32_16x16x32_bf16 v[14:17], v[164:167], v[220:223], 0
	v_mfma_f32_16x16x32_bf16 v[6:9], v[172:175], v[220:223], 0
	v_mfma_f32_16x16x32_bf16 v[62:65], v[168:171], v[200:203], v[62:65]
	v_mfma_f32_16x16x32_bf16 v[54:57], v[176:179], v[200:203], v[54:57]
	v_mfma_f32_16x16x32_bf16 v[46:49], v[168:171], v[208:211], v[46:49]
	v_mfma_f32_16x16x32_bf16 v[38:41], v[176:179], v[208:211], v[38:41]
	v_mfma_f32_16x16x32_bf16 v[30:33], v[168:171], v[216:219], v[30:33]
	v_mfma_f32_16x16x32_bf16 v[22:25], v[176:179], v[216:219], v[22:25]
	v_mfma_f32_16x16x32_bf16 v[14:17], v[168:171], v[224:227], v[14:17]
	v_mfma_f32_16x16x32_bf16 v[6:9], v[176:179], v[224:227], v[6:9]
	s_setprio 0
	s_setprio 1
	v_mfma_f32_16x16x32_bf16 v[58:61], v[180:183], v[196:199], 0
	v_mfma_f32_16x16x32_bf16 v[50:53], v[188:191], v[196:199], 0
	v_mfma_f32_16x16x32_bf16 v[42:45], v[180:183], v[204:207], 0
	v_mfma_f32_16x16x32_bf16 v[34:37], v[188:191], v[204:207], 0
	v_mfma_f32_16x16x32_bf16 v[26:29], v[180:183], v[212:215], 0
	v_mfma_f32_16x16x32_bf16 v[18:21], v[188:191], v[212:215], 0
	v_mfma_f32_16x16x32_bf16 v[10:13], v[180:183], v[220:223], 0
	v_mfma_f32_16x16x32_bf16 v[2:5], v[188:191], v[220:223], 0
	v_mfma_f32_16x16x32_bf16 v[58:61], v[184:187], v[200:203], v[58:61]
	v_mfma_f32_16x16x32_bf16 v[50:53], v[192:195], v[200:203], v[50:53]
	v_mfma_f32_16x16x32_bf16 v[42:45], v[184:187], v[208:211], v[42:45]
	v_mfma_f32_16x16x32_bf16 v[34:37], v[192:195], v[208:211], v[34:37]
	v_mfma_f32_16x16x32_bf16 v[26:29], v[184:187], v[216:219], v[26:29]
	v_mfma_f32_16x16x32_bf16 v[18:21], v[192:195], v[216:219], v[18:21]
	v_mfma_f32_16x16x32_bf16 v[10:13], v[184:187], v[224:227], v[10:13]
	v_mfma_f32_16x16x32_bf16 v[2:5], v[192:195], v[224:227], v[2:5]
	s_barrier
	s_setprio 0
	s_add_u32 s98, s94, 0x40000
	s_addc_u32 s99, s95, 0
	s_add_i32 s7, 0, 0x18000
	s_add_i32 s55, 0, 0x1c000
	s_mov_b32 m0, s63
	s_nop 0
	global_load_lds_dwordx4 v130, s[98:99]
	s_mov_b32 m0, s64
	s_nop 0
	global_load_lds_dwordx4 v134, s[98:99]
	ds_read_b128 v[164:167], v232
	ds_read_b128 v[168:171], v232 offset:1024
	ds_read_b128 v[172:175], v232 offset:2048
	ds_read_b128 v[176:179], v232 offset:3072
	ds_read_b128 v[180:183], v233
	ds_read_b128 v[184:187], v233 offset:1024
	ds_read_b128 v[188:191], v233 offset:2048
	ds_read_b128 v[192:195], v233 offset:3072
	ds_read_b128 v[196:199], v160 offset:32768
	ds_read_b128 v[200:203], v160 offset:33792
	ds_read_b128 v[204:207], v160 offset:34816
	ds_read_b128 v[208:211], v160 offset:35840
	ds_read_b128 v[212:215], v160 offset:36864
	ds_read_b128 v[216:219], v160 offset:37888
	ds_read_b128 v[220:223], v160 offset:38912
	ds_read_b128 v[224:227], v160 offset:39936
	s_waitcnt vmcnt(8)
	s_waitcnt lgkmcnt(0)
	s_setprio 1
	s_barrier
	v_mfma_f32_16x16x32_bf16 v[122:125], v[164:167], v[196:199], v[122:125]
	v_mfma_f32_16x16x32_bf16 v[118:121], v[172:175], v[196:199], v[118:121]
	v_mfma_f32_16x16x32_bf16 v[110:113], v[164:167], v[204:207], v[110:113]
	v_mfma_f32_16x16x32_bf16 v[102:105], v[172:175], v[204:207], v[102:105]
	v_mfma_f32_16x16x32_bf16 v[94:97], v[164:167], v[212:215], v[94:97]
	v_mfma_f32_16x16x32_bf16 v[86:89], v[172:175], v[212:215], v[86:89]
	v_mfma_f32_16x16x32_bf16 v[78:81], v[164:167], v[220:223], v[78:81]
	v_mfma_f32_16x16x32_bf16 v[70:73], v[172:175], v[220:223], v[70:73]
	v_mfma_f32_16x16x32_bf16 v[122:125], v[168:171], v[200:203], v[122:125]
	v_mfma_f32_16x16x32_bf16 v[118:121], v[176:179], v[200:203], v[118:121]
	v_mfma_f32_16x16x32_bf16 v[110:113], v[168:171], v[208:211], v[110:113]
	v_mfma_f32_16x16x32_bf16 v[102:105], v[176:179], v[208:211], v[102:105]
	v_mfma_f32_16x16x32_bf16 v[94:97], v[168:171], v[216:219], v[94:97]
	v_mfma_f32_16x16x32_bf16 v[86:89], v[176:179], v[216:219], v[86:89]
	v_mfma_f32_16x16x32_bf16 v[78:81], v[168:171], v[224:227], v[78:81]
	v_mfma_f32_16x16x32_bf16 v[70:73], v[176:179], v[224:227], v[70:73]
	s_setprio 0
	s_setprio 1
	v_mfma_f32_16x16x32_bf16 v[126:129], v[180:183], v[196:199], v[126:129]
	v_mfma_f32_16x16x32_bf16 v[114:117], v[188:191], v[196:199], v[114:117]
	v_mfma_f32_16x16x32_bf16 v[106:109], v[180:183], v[204:207], v[106:109]
	v_mfma_f32_16x16x32_bf16 v[98:101], v[188:191], v[204:207], v[98:101]
	v_mfma_f32_16x16x32_bf16 v[90:93], v[180:183], v[212:215], v[90:93]
	v_mfma_f32_16x16x32_bf16 v[82:85], v[188:191], v[212:215], v[82:85]
	v_mfma_f32_16x16x32_bf16 v[74:77], v[180:183], v[220:223], v[74:77]
	v_mfma_f32_16x16x32_bf16 v[66:69], v[188:191], v[220:223], v[66:69]
	v_mfma_f32_16x16x32_bf16 v[126:129], v[184:187], v[200:203], v[126:129]
	v_mfma_f32_16x16x32_bf16 v[114:117], v[192:195], v[200:203], v[114:117]
	v_mfma_f32_16x16x32_bf16 v[106:109], v[184:187], v[208:211], v[106:109]
	v_mfma_f32_16x16x32_bf16 v[98:101], v[192:195], v[208:211], v[98:101]
	v_mfma_f32_16x16x32_bf16 v[90:93], v[184:187], v[216:219], v[90:93]
	v_mfma_f32_16x16x32_bf16 v[82:85], v[192:195], v[216:219], v[82:85]
	v_mfma_f32_16x16x32_bf16 v[74:77], v[184:187], v[224:227], v[74:77]
	v_mfma_f32_16x16x32_bf16 v[66:69], v[192:195], v[224:227], v[66:69]
	s_barrier
	s_setprio 0
	s_add_u32 s96, s96, 0x80
	s_addc_u32 s97, s97, 0
	s_add_u32 s98, s96, 0x40000
	s_addc_u32 s99, s97, 0
	s_add_u32 s94, s94, 0x80
	s_addc_u32 s95, s95, 0
	s_add_i32 s7, s7, s47
	s_mov_b32 m0, s7
	s_nop 0
	global_load_lds_dwordx4 v132, s[96:97]
	s_add_i32 m0, s7, 0x2000
	s_add_i32 s7, s55, s47
	global_load_lds_dwordx4 v136, s[96:97]
	s_mov_b32 m0, s7
	s_nop 0
	global_load_lds_dwordx4 v132, s[98:99]
	s_add_i32 m0, s7, 0x2000
	s_nop 0
	global_load_lds_dwordx4 v136, s[98:99]
	s_mov_b32 m0, s65
	s_nop 0
	global_load_lds_dwordx4 v130, s[94:95]
	s_mov_b32 m0, s66
	s_nop 0
	global_load_lds_dwordx4 v134, s[94:95]
	ds_read_b128 v[196:199], v160 offset:49152
	ds_read_b128 v[200:203], v160 offset:50176
	ds_read_b128 v[204:207], v160 offset:51200
	ds_read_b128 v[208:211], v160 offset:52224
	ds_read_b128 v[212:215], v160 offset:53248
	ds_read_b128 v[216:219], v160 offset:54272
	ds_read_b128 v[220:223], v160 offset:55296
	ds_read_b128 v[224:227], v160 offset:56320
	s_waitcnt vmcnt(8)
	s_waitcnt lgkmcnt(0)
	s_setprio 1
	s_barrier
	v_mfma_f32_16x16x32_bf16 v[62:65], v[164:167], v[196:199], v[62:65]
	v_mfma_f32_16x16x32_bf16 v[54:57], v[172:175], v[196:199], v[54:57]
	v_mfma_f32_16x16x32_bf16 v[46:49], v[164:167], v[204:207], v[46:49]
	v_mfma_f32_16x16x32_bf16 v[38:41], v[172:175], v[204:207], v[38:41]
	v_mfma_f32_16x16x32_bf16 v[30:33], v[164:167], v[212:215], v[30:33]
	v_mfma_f32_16x16x32_bf16 v[22:25], v[172:175], v[212:215], v[22:25]
	v_mfma_f32_16x16x32_bf16 v[14:17], v[164:167], v[220:223], v[14:17]
	v_mfma_f32_16x16x32_bf16 v[6:9], v[172:175], v[220:223], v[6:9]
	v_mfma_f32_16x16x32_bf16 v[62:65], v[168:171], v[200:203], v[62:65]
	v_mfma_f32_16x16x32_bf16 v[54:57], v[176:179], v[200:203], v[54:57]
	v_mfma_f32_16x16x32_bf16 v[46:49], v[168:171], v[208:211], v[46:49]
	v_mfma_f32_16x16x32_bf16 v[38:41], v[176:179], v[208:211], v[38:41]
	v_mfma_f32_16x16x32_bf16 v[30:33], v[168:171], v[216:219], v[30:33]
	v_mfma_f32_16x16x32_bf16 v[22:25], v[176:179], v[216:219], v[22:25]
	v_mfma_f32_16x16x32_bf16 v[14:17], v[168:171], v[224:227], v[14:17]
	v_mfma_f32_16x16x32_bf16 v[6:9], v[176:179], v[224:227], v[6:9]
	s_setprio 0
	s_setprio 1
	v_mfma_f32_16x16x32_bf16 v[58:61], v[180:183], v[196:199], v[58:61]
	v_mfma_f32_16x16x32_bf16 v[50:53], v[188:191], v[196:199], v[50:53]
	v_mfma_f32_16x16x32_bf16 v[42:45], v[180:183], v[204:207], v[42:45]
	v_mfma_f32_16x16x32_bf16 v[34:37], v[188:191], v[204:207], v[34:37]
	v_mfma_f32_16x16x32_bf16 v[26:29], v[180:183], v[212:215], v[26:29]
	v_mfma_f32_16x16x32_bf16 v[18:21], v[188:191], v[212:215], v[18:21]
	v_mfma_f32_16x16x32_bf16 v[10:13], v[180:183], v[220:223], v[10:13]
	v_mfma_f32_16x16x32_bf16 v[2:5], v[188:191], v[220:223], v[2:5]
	v_mfma_f32_16x16x32_bf16 v[58:61], v[184:187], v[200:203], v[58:61]
	v_mfma_f32_16x16x32_bf16 v[50:53], v[192:195], v[200:203], v[50:53]
	v_mfma_f32_16x16x32_bf16 v[42:45], v[184:187], v[208:211], v[42:45]
	v_mfma_f32_16x16x32_bf16 v[34:37], v[192:195], v[208:211], v[34:37]
	v_mfma_f32_16x16x32_bf16 v[26:29], v[184:187], v[216:219], v[26:29]
	v_mfma_f32_16x16x32_bf16 v[18:21], v[192:195], v[216:219], v[18:21]
	v_mfma_f32_16x16x32_bf16 v[10:13], v[184:187], v[224:227], v[10:13]
	v_mfma_f32_16x16x32_bf16 v[2:5], v[192:195], v[224:227], v[2:5]
	s_barrier
	s_setprio 0
	s_mov_b32 s7, s51
	s_add_u32 s88, s88, 0x100
	s_addc_u32 s89, s89, 0
	s_add_u32 s86, s86, 0x100
	s_addc_u32 s87, s87, 0
	s_cmp_ge_i32 s51, s101
	s_cbranch_scc1 .Lmy_kexit_0

.LBB0_229:
	s_andn2_b64 vcc, exec, s[18:19]
	s_cbranch_vccnz .LBB0_165
	s_mov_b32 s32, 1
	s_branch .LBB0_165

.LBB0_308:
	v_cmp_gt_i32_e32 vcc, 1, v141
	s_cbranch_vccnz .LBB0_370
	v_lshl_add_u64 v[154:155], v[2:3], 0, s[28:29]
	v_add_u32_e32 v138, -2, v141
	s_mov_b32 s8, 0
	s_cmp_eq_u32 s32, 1
	s_cbranch_scc0 .Lmy_nb_1
	s_mov_b32 s32, 0
	s_barrier
.Lmy_nb_1:
	s_nop 0
	v_readfirstlane_b32 s86, v152
	v_readfirstlane_b32 s87, v153
	v_readfirstlane_b32 s88, v154
	v_readfirstlane_b32 s89, v155
	v_readfirstlane_b32 s90, v148
	v_readfirstlane_b32 s91, v149
	v_readfirstlane_b32 s92, v150
	v_readfirstlane_b32 s93, v151
	v_readfirstlane_b32 s100, v138
	v_readfirstlane_b32 s101, v141
	v_add_u32_e32 v230, s69, v160
	v_add_u32_e32 v231, s72, v160
	v_add_u32_e32 v232, 0x18000, v160
	v_add_u32_e32 v233, 0x1c000, v160
	s_add_u32 s98, s86, 0x100
	s_addc_u32 s99, s87, 0
	s_cmp_eq_u32 s8, s100
	s_cselect_b64 s[94:95], s[90:91], s[98:99]
	s_cselect_b64 s[96:97], s[92:93], s[88:89]
	s_add_i32 s9, s8, 2
	s_nop 0
	s_add_i32 m0, s55, 0xc000
	s_nop 0
	global_load_lds_dwordx4 v144, s[86:87]
	s_add_i32 m0, s55, 0xe000
	s_nop 0
	global_load_lds_dwordx4 v142, s[86:87]
	ds_read_b128 v[166:169], v230
	ds_read_b128 v[170:173], v230 offset:1024
	ds_read_b128 v[174:177], v230 offset:2048
	ds_read_b128 v[178:181], v230 offset:3072
	ds_read_b128 v[182:185], v231
	ds_read_b128 v[186:189], v231 offset:1024
	ds_read_b128 v[190:193], v231 offset:2048
	ds_read_b128 v[194:197], v231 offset:3072
	ds_read_b128 v[198:201], v163
	ds_read_b128 v[202:205], v163 offset:1024
	ds_read_b128 v[206:209], v163 offset:2048
	ds_read_b128 v[210:213], v163 offset:3072
	ds_read_b128 v[214:217], v163 offset:4096
	ds_read_b128 v[218:221], v163 offset:5120
	ds_read_b128 v[222:225], v163 offset:6144
	ds_read_b128 v[226:229], v163 offset:7168
	s_waitcnt vmcnt(8)
	s_waitcnt lgkmcnt(0)
	s_setprio 1
	s_barrier
	v_mfma_f32_16x16x32_bf16 v[122:125], v[166:169], v[198:201], 0
	v_mfma_f32_16x16x32_bf16 v[118:121], v[174:177], v[198:201], 0
	v_mfma_f32_16x16x32_bf16 v[110:113], v[166:169], v[206:209], 0
	v_mfma_f32_16x16x32_bf16 v[102:105], v[174:177], v[206:209], 0
	v_mfma_f32_16x16x32_bf16 v[94:97], v[166:169], v[214:217], 0
	v_mfma_f32_16x16x32_bf16 v[86:89], v[174:177], v[214:217], 0
	v_mfma_f32_16x16x32_bf16 v[78:81], v[166:169], v[222:225], 0
	v_mfma_f32_16x16x32_bf16 v[70:73], v[174:177], v[222:225], 0
	v_mfma_f32_16x16x32_bf16 v[122:125], v[170:173], v[202:205], v[122:125]
	v_mfma_f32_16x16x32_bf16 v[118:121], v[178:181], v[202:205], v[118:121]
	v_mfma_f32_16x16x32_bf16 v[110:113], v[170:173], v[210:213], v[110:113]
	v_mfma_f32_16x16x32_bf16 v[102:105], v[178:181], v[210:213], v[102:105]
	v_mfma_f32_16x16x32_bf16 v[94:97], v[170:173], v[218:221], v[94:97]
	v_mfma_f32_16x16x32_bf16 v[86:89], v[178:181], v[218:221], v[86:89]
	v_mfma_f32_16x16x32_bf16 v[78:81], v[170:173], v[226:229], v[78:81]
	v_mfma_f32_16x16x32_bf16 v[70:73], v[178:181], v[226:229], v[70:73]
	s_setprio 0
	s_setprio 1
	v_mfma_f32_16x16x32_bf16 v[126:129], v[182:185], v[198:201], 0
	v_mfma_f32_16x16x32_bf16 v[114:117], v[190:193], v[198:201], 0
	v_mfma_f32_16x16x32_bf16 v[106:109], v[182:185], v[206:209], 0
	v_mfma_f32_16x16x32_bf16 v[98:101], v[190:193], v[206:209], 0
	v_mfma_f32_16x16x32_bf16 v[90:93], v[182:185], v[214:217], 0
	v_mfma_f32_16x16x32_bf16 v[82:85], v[190:193], v[214:217], 0
	v_mfma_f32_16x16x32_bf16 v[74:77], v[182:185], v[222:225], 0
	v_mfma_f32_16x16x32_bf16 v[66:69], v[190:193], v[222:225], 0
	v_mfma_f32_16x16x32_bf16 v[126:129], v[186:189], v[202:205], v[126:129]
	v_mfma_f32_16x16x32_bf16 v[114:117], v[194:197], v[202:205], v[114:117]
	v_mfma_f32_16x16x32_bf16 v[106:109], v[186:189], v[210:213], v[106:109]
	v_mfma_f32_16x16x32_bf16 v[98:101], v[194:197], v[210:213], v[98:101]
	v_mfma_f32_16x16x32_bf16 v[90:93], v[186:189], v[218:221], v[90:93]
	v_mfma_f32_16x16x32_bf16 v[82:85], v[194:197], v[218:221], v[82:85]
	v_mfma_f32_16x16x32_bf16 v[74:77], v[186:189], v[226:229], v[74:77]
	v_mfma_f32_16x16x32_bf16 v[66:69], v[194:197], v[226:229], v[66:69]
	s_barrier
	s_setprio 0
	s_add_u32 s98, s96, 0xb0000
	s_addc_u32 s99, s97, 0
	s_add_i32 s8, s69, s54
	s_mov_b32 m0, s8
	s_nop 0
	global_load_lds_dwordx4 v132, s[96:97]
	s_add_i32 m0, s8, 0x2000
	s_add_i32 s8, s72, s54
	global_load_lds_dwordx4 v136, s[96:97]
	s_mov_b32 m0, s8
	s_nop 0
	global_load_lds_dwordx4 v132, s[98:99]
	s_add_i32 m0, s8, 0x2000
	s_nop 0
	global_load_lds_dwordx4 v136, s[98:99]
	s_mov_b32 m0, s55
	s_nop 0
	global_load_lds_dwordx4 v130, s[94:95]
	s_mov_b32 m0, s56
	s_nop 0
	global_load_lds_dwordx4 v134, s[94:95]
	ds_read_b128 v[198:201], v163 offset:16384
	ds_read_b128 v[202:205], v163 offset:17408
	ds_read_b128 v[206:209], v163 offset:18432
	ds_read_b128 v[210:213], v163 offset:19456
	ds_read_b128 v[214:217], v163 offset:20480
	ds_read_b128 v[218:221], v163 offset:21504
	ds_read_b128 v[222:225], v163 offset:22528
	ds_read_b128 v[226:229], v163 offset:23552
	s_waitcnt vmcnt(8)
	s_waitcnt lgkmcnt(0)
	s_setprio 1
	s_barrier
	v_mfma_f32_16x16x32_bf16 v[62:65], v[166:169], v[198:201], 0
	v_mfma_f32_16x16x32_bf16 v[54:57], v[174:177], v[198:201], 0
	v_mfma_f32_16x16x32_bf16 v[46:49], v[166:169], v[206:209], 0
	v_mfma_f32_16x16x32_bf16 v[38:41], v[174:177], v[206:209], 0
	v_mfma_f32_16x16x32_bf16 v[30:33], v[166:169], v[214:217], 0
	v_mfma_f32_16x16x32_bf16 v[22:25], v[174:177], v[214:217], 0
	v_mfma_f32_16x16x32_bf16 v[14:17], v[166:169], v[222:225], 0
	v_mfma_f32_16x16x32_bf16 v[6:9], v[174:177], v[222:225], 0
	v_mfma_f32_16x16x32_bf16 v[62:65], v[170:173], v[202:205], v[62:65]
	v_mfma_f32_16x16x32_bf16 v[54:57], v[178:181], v[202:205], v[54:57]
	v_mfma_f32_16x16x32_bf16 v[46:49], v[170:173], v[210:213], v[46:49]
	v_mfma_f32_16x16x32_bf16 v[38:41], v[178:181], v[210:213], v[38:41]
	v_mfma_f32_16x16x32_bf16 v[30:33], v[170:173], v[218:221], v[30:33]
	v_mfma_f32_16x16x32_bf16 v[22:25], v[178:181], v[218:221], v[22:25]
	v_mfma_f32_16x16x32_bf16 v[14:17], v[170:173], v[226:229], v[14:17]
	v_mfma_f32_16x16x32_bf16 v[6:9], v[178:181], v[226:229], v[6:9]
	s_setprio 0
	s_setprio 1
	v_mfma_f32_16x16x32_bf16 v[58:61], v[182:185], v[198:201], 0
	v_mfma_f32_16x16x32_bf16 v[50:53], v[190:193], v[198:201], 0
	v_mfma_f32_16x16x32_bf16 v[42:45], v[182:185], v[206:209], 0
	v_mfma_f32_16x16x32_bf16 v[34:37], v[190:193], v[206:209], 0
	v_mfma_f32_16x16x32_bf16 v[26:29], v[182:185], v[214:217], 0
	v_mfma_f32_16x16x32_bf16 v[18:21], v[190:193], v[214:217], 0
	v_mfma_f32_16x16x32_bf16 v[10:13], v[182:185], v[222:225], 0
	v_mfma_f32_16x16x32_bf16 v[2:5], v[190:193], v[222:225], 0
	v_mfma_f32_16x16x32_bf16 v[58:61], v[186:189], v[202:205], v[58:61]
	v_mfma_f32_16x16x32_bf16 v[50:53], v[194:197], v[202:205], v[50:53]
	v_mfma_f32_16x16x32_bf16 v[42:45], v[186:189], v[210:213], v[42:45]
	v_mfma_f32_16x16x32_bf16 v[34:37], v[194:197], v[210:213], v[34:37]
	v_mfma_f32_16x16x32_bf16 v[26:29], v[186:189], v[218:221], v[26:29]
	v_mfma_f32_16x16x32_bf16 v[18:21], v[194:197], v[218:221], v[18:21]
	v_mfma_f32_16x16x32_bf16 v[10:13], v[186:189], v[226:229], v[10:13]
	v_mfma_f32_16x16x32_bf16 v[2:5], v[194:197], v[226:229], v[2:5]
	s_barrier
	s_setprio 0
	s_add_u32 s98, s94, 0xb0000
	s_addc_u32 s99, s95, 0
	s_add_i32 s8, 0, 0x18000
	s_add_i32 s50, 0, 0x1c000
	s_mov_b32 m0, s57
	s_nop 0
	global_load_lds_dwordx4 v130, s[98:99]
	s_mov_b32 m0, s58
	s_nop 0
	global_load_lds_dwordx4 v134, s[98:99]
	ds_read_b128 v[166:169], v232
	ds_read_b128 v[170:173], v232 offset:1024
	ds_read_b128 v[174:177], v232 offset:2048
	ds_read_b128 v[178:181], v232 offset:3072
	ds_read_b128 v[182:185], v233
	ds_read_b128 v[186:189], v233 offset:1024
	ds_read_b128 v[190:193], v233 offset:2048
	ds_read_b128 v[194:197], v233 offset:3072
	ds_read_b128 v[198:201], v163 offset:32768
	ds_read_b128 v[202:205], v163 offset:33792
	ds_read_b128 v[206:209], v163 offset:34816
	ds_read_b128 v[210:213], v163 offset:35840
	ds_read_b128 v[214:217], v163 offset:36864
	ds_read_b128 v[218:221], v163 offset:37888
	ds_read_b128 v[222:225], v163 offset:38912
	ds_read_b128 v[226:229], v163 offset:39936
	s_waitcnt vmcnt(8)
	s_waitcnt lgkmcnt(0)
	s_setprio 1
	s_barrier
	v_mfma_f32_16x16x32_bf16 v[122:125], v[166:169], v[198:201], v[122:125]
	v_mfma_f32_16x16x32_bf16 v[118:121], v[174:177], v[198:201], v[118:121]
	v_mfma_f32_16x16x32_bf16 v[110:113], v[166:169], v[206:209], v[110:113]
	v_mfma_f32_16x16x32_bf16 v[102:105], v[174:177], v[206:209], v[102:105]
	v_mfma_f32_16x16x32_bf16 v[94:97], v[166:169], v[214:217], v[94:97]
	v_mfma_f32_16x16x32_bf16 v[86:89], v[174:177], v[214:217], v[86:89]
	v_mfma_f32_16x16x32_bf16 v[78:81], v[166:169], v[222:225], v[78:81]
	v_mfma_f32_16x16x32_bf16 v[70:73], v[174:177], v[222:225], v[70:73]
	v_mfma_f32_16x16x32_bf16 v[122:125], v[170:173], v[202:205], v[122:125]
	v_mfma_f32_16x16x32_bf16 v[118:121], v[178:181], v[202:205], v[118:121]
	v_mfma_f32_16x16x32_bf16 v[110:113], v[170:173], v[210:213], v[110:113]
	v_mfma_f32_16x16x32_bf16 v[102:105], v[178:181], v[210:213], v[102:105]
	v_mfma_f32_16x16x32_bf16 v[94:97], v[170:173], v[218:221], v[94:97]
	v_mfma_f32_16x16x32_bf16 v[86:89], v[178:181], v[218:221], v[86:89]
	v_mfma_f32_16x16x32_bf16 v[78:81], v[170:173], v[226:229], v[78:81]
	v_mfma_f32_16x16x32_bf16 v[70:73], v[178:181], v[226:229], v[70:73]
	s_setprio 0
	s_setprio 1
	v_mfma_f32_16x16x32_bf16 v[126:129], v[182:185], v[198:201], v[126:129]
	v_mfma_f32_16x16x32_bf16 v[114:117], v[190:193], v[198:201], v[114:117]
	v_mfma_f32_16x16x32_bf16 v[106:109], v[182:185], v[206:209], v[106:109]
	v_mfma_f32_16x16x32_bf16 v[98:101], v[190:193], v[206:209], v[98:101]
	v_mfma_f32_16x16x32_bf16 v[90:93], v[182:185], v[214:217], v[90:93]
	v_mfma_f32_16x16x32_bf16 v[82:85], v[190:193], v[214:217], v[82:85]
	v_mfma_f32_16x16x32_bf16 v[74:77], v[182:185], v[222:225], v[74:77]
	v_mfma_f32_16x16x32_bf16 v[66:69], v[190:193], v[222:225], v[66:69]
	v_mfma_f32_16x16x32_bf16 v[126:129], v[186:189], v[202:205], v[126:129]
	v_mfma_f32_16x16x32_bf16 v[114:117], v[194:197], v[202:205], v[114:117]
	v_mfma_f32_16x16x32_bf16 v[106:109], v[186:189], v[210:213], v[106:109]
	v_mfma_f32_16x16x32_bf16 v[98:101], v[194:197], v[210:213], v[98:101]
	v_mfma_f32_16x16x32_bf16 v[90:93], v[186:189], v[218:221], v[90:93]
	v_mfma_f32_16x16x32_bf16 v[82:85], v[194:197], v[218:221], v[82:85]
	v_mfma_f32_16x16x32_bf16 v[74:77], v[186:189], v[226:229], v[74:77]
	v_mfma_f32_16x16x32_bf16 v[66:69], v[194:197], v[226:229], v[66:69]
	s_barrier
	s_setprio 0
	s_add_u32 s96, s96, 0x80
	s_addc_u32 s97, s97, 0
	s_add_u32 s98, s96, 0xb0000
	s_addc_u32 s99, s97, 0
	s_add_u32 s94, s94, 0x80
	s_addc_u32 s95, s95, 0
	s_add_i32 s8, s8, s54
	s_mov_b32 m0, s8
	s_nop 0
	global_load_lds_dwordx4 v132, s[96:97]
	s_add_i32 m0, s8, 0x2000
	s_add_i32 s8, s50, s54
	global_load_lds_dwordx4 v136, s[96:97]
	s_mov_b32 m0, s8
	s_nop 0
	global_load_lds_dwordx4 v132, s[98:99]
	s_add_i32 m0, s8, 0x2000
	s_nop 0
	global_load_lds_dwordx4 v136, s[98:99]
	s_mov_b32 m0, s64
	s_nop 0
	global_load_lds_dwordx4 v130, s[94:95]
	s_mov_b32 m0, s65
	s_nop 0
	global_load_lds_dwordx4 v134, s[94:95]
	ds_read_b128 v[198:201], v163 offset:49152
	ds_read_b128 v[202:205], v163 offset:50176
	ds_read_b128 v[206:209], v163 offset:51200
	ds_read_b128 v[210:213], v163 offset:52224
	ds_read_b128 v[214:217], v163 offset:53248
	ds_read_b128 v[218:221], v163 offset:54272
	ds_read_b128 v[222:225], v163 offset:55296
	ds_read_b128 v[226:229], v163 offset:56320
	s_waitcnt vmcnt(8)
	s_waitcnt lgkmcnt(0)
	s_setprio 1
	s_barrier
	v_mfma_f32_16x16x32_bf16 v[62:65], v[166:169], v[198:201], v[62:65]
	v_mfma_f32_16x16x32_bf16 v[54:57], v[174:177], v[198:201], v[54:57]
	v_mfma_f32_16x16x32_bf16 v[46:49], v[166:169], v[206:209], v[46:49]
	v_mfma_f32_16x16x32_bf16 v[38:41], v[174:177], v[206:209], v[38:41]
	v_mfma_f32_16x16x32_bf16 v[30:33], v[166:169], v[214:217], v[30:33]
	v_mfma_f32_16x16x32_bf16 v[22:25], v[174:177], v[214:217], v[22:25]
	v_mfma_f32_16x16x32_bf16 v[14:17], v[166:169], v[222:225], v[14:17]
	v_mfma_f32_16x16x32_bf16 v[6:9], v[174:177], v[222:225], v[6:9]
	v_mfma_f32_16x16x32_bf16 v[62:65], v[170:173], v[202:205], v[62:65]
	v_mfma_f32_16x16x32_bf16 v[54:57], v[178:181], v[202:205], v[54:57]
	v_mfma_f32_16x16x32_bf16 v[46:49], v[170:173], v[210:213], v[46:49]
	v_mfma_f32_16x16x32_bf16 v[38:41], v[178:181], v[210:213], v[38:41]
	v_mfma_f32_16x16x32_bf16 v[30:33], v[170:173], v[218:221], v[30:33]
	v_mfma_f32_16x16x32_bf16 v[22:25], v[178:181], v[218:221], v[22:25]
	v_mfma_f32_16x16x32_bf16 v[14:17], v[170:173], v[226:229], v[14:17]
	v_mfma_f32_16x16x32_bf16 v[6:9], v[178:181], v[226:229], v[6:9]
	s_setprio 0
	s_setprio 1
	v_mfma_f32_16x16x32_bf16 v[58:61], v[182:185], v[198:201], v[58:61]
	v_mfma_f32_16x16x32_bf16 v[50:53], v[190:193], v[198:201], v[50:53]
	v_mfma_f32_16x16x32_bf16 v[42:45], v[182:185], v[206:209], v[42:45]
	v_mfma_f32_16x16x32_bf16 v[34:37], v[190:193], v[206:209], v[34:37]
	v_mfma_f32_16x16x32_bf16 v[26:29], v[182:185], v[214:217], v[26:29]
	v_mfma_f32_16x16x32_bf16 v[18:21], v[190:193], v[214:217], v[18:21]
	v_mfma_f32_16x16x32_bf16 v[10:13], v[182:185], v[222:225], v[10:13]
	v_mfma_f32_16x16x32_bf16 v[2:5], v[190:193], v[222:225], v[2:5]
	v_mfma_f32_16x16x32_bf16 v[58:61], v[186:189], v[202:205], v[58:61]
	v_mfma_f32_16x16x32_bf16 v[50:53], v[194:197], v[202:205], v[50:53]
	v_mfma_f32_16x16x32_bf16 v[42:45], v[186:189], v[210:213], v[42:45]
	v_mfma_f32_16x16x32_bf16 v[34:37], v[194:197], v[210:213], v[34:37]
	v_mfma_f32_16x16x32_bf16 v[26:29], v[186:189], v[218:221], v[26:29]
	v_mfma_f32_16x16x32_bf16 v[18:21], v[194:197], v[218:221], v[18:21]
	v_mfma_f32_16x16x32_bf16 v[10:13], v[186:189], v[226:229], v[10:13]
	v_mfma_f32_16x16x32_bf16 v[2:5], v[194:197], v[226:229], v[2:5]
	s_barrier
	s_setprio 0
	s_mov_b32 s8, s9
	s_add_u32 s88, s88, 0x100
	s_addc_u32 s89, s89, 0
	s_add_u32 s86, s86, 0x100
	s_addc_u32 s87, s87, 0
	s_cmp_ge_i32 s9, s101
	s_cbranch_scc1 .Lmy_kexit_1

.LBB0_497:
	v_cmp_gt_i32_e32 vcc, 1, v141
	s_cbranch_vccnz .LBB0_559
	v_lshl_add_u64 v[154:155], v[2:3], 0, s[16:17]
	v_add_u32_e32 v138, -2, v141
	v_lshl_add_u64 v[152:153], v[4:5], 0, s[20:21]
	s_mov_b32 s7, 0
	s_cmp_eq_u32 s32, 1
	s_cbranch_scc0 .Lmy_nb_2
	s_mov_b32 s32, 0
	s_barrier
.Lmy_nb_2:
	s_nop 0
	v_readfirstlane_b32 s86, v154
	v_readfirstlane_b32 s87, v155
	v_readfirstlane_b32 s88, v152
	v_readfirstlane_b32 s89, v153
	v_readfirstlane_b32 s90, v148
	v_readfirstlane_b32 s91, v149
	v_readfirstlane_b32 s92, v150
	v_readfirstlane_b32 s93, v151
	v_readfirstlane_b32 s100, v138
	v_readfirstlane_b32 s101, v141
	v_add_u32_e32 v230, s77, v160
	v_add_u32_e32 v231, s78, v160
	v_add_u32_e32 v232, 0x18000, v160
	v_add_u32_e32 v233, 0x1c000, v160
	s_add_u32 s98, s86, 0xfffc0080
	s_addc_u32 s99, s87, -1
	s_cmp_eq_u32 s7, s100
	s_cselect_b64 s[94:95], s[90:91], s[98:99]
	s_cselect_b64 s[96:97], s[92:93], s[88:89]
	s_add_i32 s45, s7, 2
	s_nop 0
	s_add_i32 m0, s49, 0xc000
	s_nop 0
	global_load_lds_dwordx4 v144, s[86:87]
	s_add_i32 m0, s49, 0xe000
	s_nop 0
	global_load_lds_dwordx4 v142, s[86:87]
	ds_read_b128 v[156:159], v230
	ds_read_b128 v[166:169], v230 offset:1024
	ds_read_b128 v[170:173], v230 offset:2048
	ds_read_b128 v[174:177], v230 offset:3072
	ds_read_b128 v[178:181], v231
	ds_read_b128 v[182:185], v231 offset:1024
	ds_read_b128 v[186:189], v231 offset:2048
	ds_read_b128 v[190:193], v231 offset:3072
	ds_read_b128 v[194:197], v163
	ds_read_b128 v[198:201], v163 offset:1024
	ds_read_b128 v[202:205], v163 offset:2048
	ds_read_b128 v[206:209], v163 offset:3072
	ds_read_b128 v[210:213], v163 offset:4096
	ds_read_b128 v[214:217], v163 offset:5120
	ds_read_b128 v[218:221], v163 offset:6144
	ds_read_b128 v[222:225], v163 offset:7168
	s_waitcnt vmcnt(8)
	s_waitcnt lgkmcnt(0)
	s_setprio 1
	s_barrier
	v_mfma_f32_16x16x32_bf16 v[122:125], v[156:159], v[194:197], 0
	v_mfma_f32_16x16x32_bf16 v[118:121], v[170:173], v[194:197], 0
	v_mfma_f32_16x16x32_bf16 v[110:113], v[156:159], v[202:205], 0
	v_mfma_f32_16x16x32_bf16 v[102:105], v[170:173], v[202:205], 0
	v_mfma_f32_16x16x32_bf16 v[94:97], v[156:159], v[210:213], 0
	v_mfma_f32_16x16x32_bf16 v[86:89], v[170:173], v[210:213], 0
	v_mfma_f32_16x16x32_bf16 v[78:81], v[156:159], v[218:221], 0
	v_mfma_f32_16x16x32_bf16 v[70:73], v[170:173], v[218:221], 0
	v_mfma_f32_16x16x32_bf16 v[122:125], v[166:169], v[198:201], v[122:125]
	v_mfma_f32_16x16x32_bf16 v[118:121], v[174:177], v[198:201], v[118:121]
	v_mfma_f32_16x16x32_bf16 v[110:113], v[166:169], v[206:209], v[110:113]
	v_mfma_f32_16x16x32_bf16 v[102:105], v[174:177], v[206:209], v[102:105]
	v_mfma_f32_16x16x32_bf16 v[94:97], v[166:169], v[214:217], v[94:97]
	v_mfma_f32_16x16x32_bf16 v[86:89], v[174:177], v[214:217], v[86:89]
	v_mfma_f32_16x16x32_bf16 v[78:81], v[166:169], v[222:225], v[78:81]
	v_mfma_f32_16x16x32_bf16 v[70:73], v[174:177], v[222:225], v[70:73]
	s_setprio 0
	s_setprio 1
	v_mfma_f32_16x16x32_bf16 v[126:129], v[178:181], v[194:197], 0
	v_mfma_f32_16x16x32_bf16 v[114:117], v[186:189], v[194:197], 0
	v_mfma_f32_16x16x32_bf16 v[106:109], v[178:181], v[202:205], 0
	v_mfma_f32_16x16x32_bf16 v[98:101], v[186:189], v[202:205], 0
	v_mfma_f32_16x16x32_bf16 v[90:93], v[178:181], v[210:213], 0
	v_mfma_f32_16x16x32_bf16 v[82:85], v[186:189], v[210:213], 0
	v_mfma_f32_16x16x32_bf16 v[74:77], v[178:181], v[218:221], 0
	v_mfma_f32_16x16x32_bf16 v[66:69], v[186:189], v[218:221], 0
	v_mfma_f32_16x16x32_bf16 v[126:129], v[182:185], v[198:201], v[126:129]
	v_mfma_f32_16x16x32_bf16 v[114:117], v[190:193], v[198:201], v[114:117]
	v_mfma_f32_16x16x32_bf16 v[106:109], v[182:185], v[206:209], v[106:109]
	v_mfma_f32_16x16x32_bf16 v[98:101], v[190:193], v[206:209], v[98:101]
	v_mfma_f32_16x16x32_bf16 v[90:93], v[182:185], v[214:217], v[90:93]
	v_mfma_f32_16x16x32_bf16 v[82:85], v[190:193], v[214:217], v[82:85]
	v_mfma_f32_16x16x32_bf16 v[74:77], v[182:185], v[222:225], v[74:77]
	v_mfma_f32_16x16x32_bf16 v[66:69], v[190:193], v[222:225], v[66:69]
	s_barrier
	s_setprio 0
	s_add_u32 s98, s96, 0x40000
	s_addc_u32 s99, s97, 0
	s_add_i32 s7, s77, s25
	s_mov_b32 m0, s7
	s_nop 0
	global_load_lds_dwordx4 v132, s[96:97]
	s_add_i32 m0, s7, 0x2000
	s_add_i32 s7, s78, s25
	global_load_lds_dwordx4 v136, s[96:97]
	s_mov_b32 m0, s7
	s_nop 0
	global_load_lds_dwordx4 v132, s[98:99]
	s_add_i32 m0, s7, 0x2000
	s_nop 0
	global_load_lds_dwordx4 v136, s[98:99]
	s_mov_b32 m0, s49
	s_nop 0
	global_load_lds_dwordx4 v130, s[94:95]
	s_mov_b32 m0, s58
	s_nop 0
	global_load_lds_dwordx4 v134, s[94:95]
	ds_read_b128 v[194:197], v163 offset:16384
	ds_read_b128 v[198:201], v163 offset:17408
	ds_read_b128 v[202:205], v163 offset:18432
	ds_read_b128 v[206:209], v163 offset:19456
	ds_read_b128 v[210:213], v163 offset:20480
	ds_read_b128 v[214:217], v163 offset:21504
	ds_read_b128 v[218:221], v163 offset:22528
	ds_read_b128 v[222:225], v163 offset:23552
	s_waitcnt vmcnt(8)
	s_waitcnt lgkmcnt(0)
	s_setprio 1
	s_barrier
	v_mfma_f32_16x16x32_bf16 v[62:65], v[156:159], v[194:197], 0
	v_mfma_f32_16x16x32_bf16 v[54:57], v[170:173], v[194:197], 0
	v_mfma_f32_16x16x32_bf16 v[46:49], v[156:159], v[202:205], 0
	v_mfma_f32_16x16x32_bf16 v[38:41], v[170:173], v[202:205], 0
	v_mfma_f32_16x16x32_bf16 v[30:33], v[156:159], v[210:213], 0
	v_mfma_f32_16x16x32_bf16 v[22:25], v[170:173], v[210:213], 0
	v_mfma_f32_16x16x32_bf16 v[14:17], v[156:159], v[218:221], 0
	v_mfma_f32_16x16x32_bf16 v[6:9], v[170:173], v[218:221], 0
	v_mfma_f32_16x16x32_bf16 v[62:65], v[166:169], v[198:201], v[62:65]
	v_mfma_f32_16x16x32_bf16 v[54:57], v[174:177], v[198:201], v[54:57]
	v_mfma_f32_16x16x32_bf16 v[46:49], v[166:169], v[206:209], v[46:49]
	v_mfma_f32_16x16x32_bf16 v[38:41], v[174:177], v[206:209], v[38:41]
	v_mfma_f32_16x16x32_bf16 v[30:33], v[166:169], v[214:217], v[30:33]
	v_mfma_f32_16x16x32_bf16 v[22:25], v[174:177], v[214:217], v[22:25]
	v_mfma_f32_16x16x32_bf16 v[14:17], v[166:169], v[222:225], v[14:17]
	v_mfma_f32_16x16x32_bf16 v[6:9], v[174:177], v[222:225], v[6:9]
	s_setprio 0
	s_setprio 1
	v_mfma_f32_16x16x32_bf16 v[58:61], v[178:181], v[194:197], 0
	v_mfma_f32_16x16x32_bf16 v[50:53], v[186:189], v[194:197], 0
	v_mfma_f32_16x16x32_bf16 v[42:45], v[178:181], v[202:205], 0
	v_mfma_f32_16x16x32_bf16 v[34:37], v[186:189], v[202:205], 0
	v_mfma_f32_16x16x32_bf16 v[26:29], v[178:181], v[210:213], 0
	v_mfma_f32_16x16x32_bf16 v[18:21], v[186:189], v[210:213], 0
	v_mfma_f32_16x16x32_bf16 v[10:13], v[178:181], v[218:221], 0
	v_mfma_f32_16x16x32_bf16 v[2:5], v[186:189], v[218:221], 0
	v_mfma_f32_16x16x32_bf16 v[58:61], v[182:185], v[198:201], v[58:61]
	v_mfma_f32_16x16x32_bf16 v[50:53], v[190:193], v[198:201], v[50:53]
	v_mfma_f32_16x16x32_bf16 v[42:45], v[182:185], v[206:209], v[42:45]
	v_mfma_f32_16x16x32_bf16 v[34:37], v[190:193], v[206:209], v[34:37]
	v_mfma_f32_16x16x32_bf16 v[26:29], v[182:185], v[214:217], v[26:29]
	v_mfma_f32_16x16x32_bf16 v[18:21], v[190:193], v[214:217], v[18:21]
	v_mfma_f32_16x16x32_bf16 v[10:13], v[182:185], v[222:225], v[10:13]
	v_mfma_f32_16x16x32_bf16 v[2:5], v[190:193], v[222:225], v[2:5]
	s_barrier
	s_setprio 0
	s_add_u32 s98, s94, 0x40000
	s_addc_u32 s99, s95, 0
	s_add_i32 s7, 0, 0x18000
	s_add_i32 s47, 0, 0x1c000
	s_mov_b32 m0, s59
	s_nop 0
	global_load_lds_dwordx4 v130, s[98:99]
	s_mov_b32 m0, s60
	s_nop 0
	global_load_lds_dwordx4 v134, s[98:99]
	ds_read_b128 v[156:159], v232
	ds_read_b128 v[166:169], v232 offset:1024
	ds_read_b128 v[170:173], v232 offset:2048
	ds_read_b128 v[174:177], v232 offset:3072
	ds_read_b128 v[178:181], v233
	ds_read_b128 v[182:185], v233 offset:1024
	ds_read_b128 v[186:189], v233 offset:2048
	ds_read_b128 v[190:193], v233 offset:3072
	ds_read_b128 v[194:197], v163 offset:32768
	ds_read_b128 v[198:201], v163 offset:33792
	ds_read_b128 v[202:205], v163 offset:34816
	ds_read_b128 v[206:209], v163 offset:35840
	ds_read_b128 v[210:213], v163 offset:36864
	ds_read_b128 v[214:217], v163 offset:37888
	ds_read_b128 v[218:221], v163 offset:38912
	ds_read_b128 v[222:225], v163 offset:39936
	s_waitcnt vmcnt(8)
	s_waitcnt lgkmcnt(0)
	s_setprio 1
	s_barrier
	v_mfma_f32_16x16x32_bf16 v[122:125], v[156:159], v[194:197], v[122:125]
	v_mfma_f32_16x16x32_bf16 v[118:121], v[170:173], v[194:197], v[118:121]
	v_mfma_f32_16x16x32_bf16 v[110:113], v[156:159], v[202:205], v[110:113]
	v_mfma_f32_16x16x32_bf16 v[102:105], v[170:173], v[202:205], v[102:105]
	v_mfma_f32_16x16x32_bf16 v[94:97], v[156:159], v[210:213], v[94:97]
	v_mfma_f32_16x16x32_bf16 v[86:89], v[170:173], v[210:213], v[86:89]
	v_mfma_f32_16x16x32_bf16 v[78:81], v[156:159], v[218:221], v[78:81]
	v_mfma_f32_16x16x32_bf16 v[70:73], v[170:173], v[218:221], v[70:73]
	v_mfma_f32_16x16x32_bf16 v[122:125], v[166:169], v[198:201], v[122:125]
	v_mfma_f32_16x16x32_bf16 v[118:121], v[174:177], v[198:201], v[118:121]
	v_mfma_f32_16x16x32_bf16 v[110:113], v[166:169], v[206:209], v[110:113]
	v_mfma_f32_16x16x32_bf16 v[102:105], v[174:177], v[206:209], v[102:105]
	v_mfma_f32_16x16x32_bf16 v[94:97], v[166:169], v[214:217], v[94:97]
	v_mfma_f32_16x16x32_bf16 v[86:89], v[174:177], v[214:217], v[86:89]
	v_mfma_f32_16x16x32_bf16 v[78:81], v[166:169], v[222:225], v[78:81]
	v_mfma_f32_16x16x32_bf16 v[70:73], v[174:177], v[222:225], v[70:73]
	s_setprio 0
	s_setprio 1
	v_mfma_f32_16x16x32_bf16 v[126:129], v[178:181], v[194:197], v[126:129]
	v_mfma_f32_16x16x32_bf16 v[114:117], v[186:189], v[194:197], v[114:117]
	v_mfma_f32_16x16x32_bf16 v[106:109], v[178:181], v[202:205], v[106:109]
	v_mfma_f32_16x16x32_bf16 v[98:101], v[186:189], v[202:205], v[98:101]
	v_mfma_f32_16x16x32_bf16 v[90:93], v[178:181], v[210:213], v[90:93]
	v_mfma_f32_16x16x32_bf16 v[82:85], v[186:189], v[210:213], v[82:85]
	v_mfma_f32_16x16x32_bf16 v[74:77], v[178:181], v[218:221], v[74:77]
	v_mfma_f32_16x16x32_bf16 v[66:69], v[186:189], v[218:221], v[66:69]
	v_mfma_f32_16x16x32_bf16 v[126:129], v[182:185], v[198:201], v[126:129]
	v_mfma_f32_16x16x32_bf16 v[114:117], v[190:193], v[198:201], v[114:117]
	v_mfma_f32_16x16x32_bf16 v[106:109], v[182:185], v[206:209], v[106:109]
	v_mfma_f32_16x16x32_bf16 v[98:101], v[190:193], v[206:209], v[98:101]
	v_mfma_f32_16x16x32_bf16 v[90:93], v[182:185], v[214:217], v[90:93]
	v_mfma_f32_16x16x32_bf16 v[82:85], v[190:193], v[214:217], v[82:85]
	v_mfma_f32_16x16x32_bf16 v[74:77], v[182:185], v[222:225], v[74:77]
	v_mfma_f32_16x16x32_bf16 v[66:69], v[190:193], v[222:225], v[66:69]
	s_barrier
	s_setprio 0
	s_add_u32 s96, s96, 0x80
	s_addc_u32 s97, s97, 0
	s_add_u32 s98, s96, 0x40000
	s_addc_u32 s99, s97, 0
	s_add_u32 s94, s94, 0x80
	s_addc_u32 s95, s95, 0
	s_add_i32 s7, s7, s25
	s_mov_b32 m0, s7
	s_nop 0
	global_load_lds_dwordx4 v132, s[96:97]
	s_add_i32 m0, s7, 0x2000
	s_add_i32 s7, s47, s25
	global_load_lds_dwordx4 v136, s[96:97]
	s_mov_b32 m0, s7
	s_nop 0
	global_load_lds_dwordx4 v132, s[98:99]
	s_add_i32 m0, s7, 0x2000
	s_nop 0
	global_load_lds_dwordx4 v136, s[98:99]
	s_mov_b32 m0, s66
	s_nop 0
	global_load_lds_dwordx4 v130, s[94:95]
	s_mov_b32 m0, s67
	s_nop 0
	global_load_lds_dwordx4 v134, s[94:95]
	ds_read_b128 v[194:197], v163 offset:49152
	ds_read_b128 v[198:201], v163 offset:50176
	ds_read_b128 v[202:205], v163 offset:51200
	ds_read_b128 v[206:209], v163 offset:52224
	ds_read_b128 v[210:213], v163 offset:53248
	ds_read_b128 v[214:217], v163 offset:54272
	ds_read_b128 v[218:221], v163 offset:55296
	ds_read_b128 v[222:225], v163 offset:56320
	s_waitcnt vmcnt(8)
	s_waitcnt lgkmcnt(0)
	s_setprio 1
	s_barrier
	v_mfma_f32_16x16x32_bf16 v[62:65], v[156:159], v[194:197], v[62:65]
	v_mfma_f32_16x16x32_bf16 v[54:57], v[170:173], v[194:197], v[54:57]
	v_mfma_f32_16x16x32_bf16 v[46:49], v[156:159], v[202:205], v[46:49]
	v_mfma_f32_16x16x32_bf16 v[38:41], v[170:173], v[202:205], v[38:41]
	v_mfma_f32_16x16x32_bf16 v[30:33], v[156:159], v[210:213], v[30:33]
	v_mfma_f32_16x16x32_bf16 v[22:25], v[170:173], v[210:213], v[22:25]
	v_mfma_f32_16x16x32_bf16 v[14:17], v[156:159], v[218:221], v[14:17]
	v_mfma_f32_16x16x32_bf16 v[6:9], v[170:173], v[218:221], v[6:9]
	v_mfma_f32_16x16x32_bf16 v[62:65], v[166:169], v[198:201], v[62:65]
	v_mfma_f32_16x16x32_bf16 v[54:57], v[174:177], v[198:201], v[54:57]
	v_mfma_f32_16x16x32_bf16 v[46:49], v[166:169], v[206:209], v[46:49]
	v_mfma_f32_16x16x32_bf16 v[38:41], v[174:177], v[206:209], v[38:41]
	v_mfma_f32_16x16x32_bf16 v[30:33], v[166:169], v[214:217], v[30:33]
	v_mfma_f32_16x16x32_bf16 v[22:25], v[174:177], v[214:217], v[22:25]
	v_mfma_f32_16x16x32_bf16 v[14:17], v[166:169], v[222:225], v[14:17]
	v_mfma_f32_16x16x32_bf16 v[6:9], v[174:177], v[222:225], v[6:9]
	s_setprio 0
	s_setprio 1
	v_mfma_f32_16x16x32_bf16 v[58:61], v[178:181], v[194:197], v[58:61]
	v_mfma_f32_16x16x32_bf16 v[50:53], v[186:189], v[194:197], v[50:53]
	v_mfma_f32_16x16x32_bf16 v[42:45], v[178:181], v[202:205], v[42:45]
	v_mfma_f32_16x16x32_bf16 v[34:37], v[186:189], v[202:205], v[34:37]
	v_mfma_f32_16x16x32_bf16 v[26:29], v[178:181], v[210:213], v[26:29]
	v_mfma_f32_16x16x32_bf16 v[18:21], v[186:189], v[210:213], v[18:21]
	v_mfma_f32_16x16x32_bf16 v[10:13], v[178:181], v[218:221], v[10:13]
	v_mfma_f32_16x16x32_bf16 v[2:5], v[186:189], v[218:221], v[2:5]
	v_mfma_f32_16x16x32_bf16 v[58:61], v[182:185], v[198:201], v[58:61]
	v_mfma_f32_16x16x32_bf16 v[50:53], v[190:193], v[198:201], v[50:53]
	v_mfma_f32_16x16x32_bf16 v[42:45], v[182:185], v[206:209], v[42:45]
	v_mfma_f32_16x16x32_bf16 v[34:37], v[190:193], v[206:209], v[34:37]
	v_mfma_f32_16x16x32_bf16 v[26:29], v[182:185], v[214:217], v[26:29]
	v_mfma_f32_16x16x32_bf16 v[18:21], v[190:193], v[214:217], v[18:21]
	v_mfma_f32_16x16x32_bf16 v[10:13], v[182:185], v[222:225], v[10:13]
	v_mfma_f32_16x16x32_bf16 v[2:5], v[190:193], v[222:225], v[2:5]
	s_barrier
	s_setprio 0
	s_mov_b32 s7, s45
	s_add_u32 s88, s88, 0x100
	s_addc_u32 s89, s89, 0
	s_add_u32 s86, s86, 0x100
	s_addc_u32 s87, s87, 0
	s_cmp_ge_i32 s45, s101
	s_cbranch_scc1 .Lmy_kexit_2

.LBB0_557:
	s_andn2_b64 vcc, exec, s[12:13]
	s_cbranch_vccnz .LBB0_493
	s_mov_b32 s32, 1
	s_branch .LBB0_493

.LBB0_766:
	v_cmp_gt_i32_e32 vcc, 1, v138
	s_cbranch_vccnz .LBB0_828
	v_lshl_add_u64 v[152:153], v[2:3], 0, s[16:17]
	v_add_u32_e32 v154, -2, v138
	s_waitcnt lgkmcnt(0)
	v_lshl_add_u64 v[150:151], v[4:5], 0, s[20:21]
	s_mov_b32 s7, 0
	s_cmp_eq_u32 s32, 1
	s_cbranch_scc0 .Lmy_nb_3
	s_mov_b32 s32, 0
	s_barrier
.Lmy_nb_3:
	s_nop 0
	v_readfirstlane_b32 s86, v152
	v_readfirstlane_b32 s87, v153
	v_readfirstlane_b32 s88, v150
	v_readfirstlane_b32 s89, v151
	v_readfirstlane_b32 s90, v146
	v_readfirstlane_b32 s91, v147
	v_readfirstlane_b32 s92, v148
	v_readfirstlane_b32 s93, v149
	v_readfirstlane_b32 s100, v154
	v_readfirstlane_b32 s101, v138
	v_add_u32_e32 v230, s76, v141
	v_add_u32_e32 v231, s77, v141
	v_add_u32_e32 v232, 0x18000, v141
	v_add_u32_e32 v233, 0x1c000, v141
	s_add_u32 s98, s86, 0xfffc0080
	s_addc_u32 s99, s87, -1
	s_cmp_eq_u32 s7, s100
	s_cselect_b64 s[94:95], s[90:91], s[98:99]
	s_cselect_b64 s[96:97], s[92:93], s[88:89]
	s_add_i32 s45, s7, 2
	s_nop 0
	s_add_i32 m0, s49, 0xc000
	s_nop 0
	global_load_lds_dwordx4 v144, s[86:87]
	s_add_i32 m0, s49, 0xe000
	s_nop 0
	global_load_lds_dwordx4 v142, s[86:87]
	ds_read_b128 v[164:167], v230
	ds_read_b128 v[168:171], v230 offset:1024
	ds_read_b128 v[172:175], v230 offset:2048
	ds_read_b128 v[176:179], v230 offset:3072
	ds_read_b128 v[180:183], v231
	ds_read_b128 v[184:187], v231 offset:1024
	ds_read_b128 v[188:191], v231 offset:2048
	ds_read_b128 v[192:195], v231 offset:3072
	ds_read_b128 v[196:199], v160
	ds_read_b128 v[200:203], v160 offset:1024
	ds_read_b128 v[204:207], v160 offset:2048
	ds_read_b128 v[208:211], v160 offset:3072
	ds_read_b128 v[212:215], v160 offset:4096
	ds_read_b128 v[216:219], v160 offset:5120
	ds_read_b128 v[220:223], v160 offset:6144
	ds_read_b128 v[224:227], v160 offset:7168
	s_waitcnt vmcnt(8)
	s_waitcnt lgkmcnt(0)
	s_setprio 1
	s_barrier
	v_mfma_f32_16x16x32_bf16 v[122:125], v[164:167], v[196:199], 0
	v_mfma_f32_16x16x32_bf16 v[118:121], v[172:175], v[196:199], 0
	v_mfma_f32_16x16x32_bf16 v[110:113], v[164:167], v[204:207], 0
	v_mfma_f32_16x16x32_bf16 v[102:105], v[172:175], v[204:207], 0
	v_mfma_f32_16x16x32_bf16 v[94:97], v[164:167], v[212:215], 0
	v_mfma_f32_16x16x32_bf16 v[86:89], v[172:175], v[212:215], 0
	v_mfma_f32_16x16x32_bf16 v[78:81], v[164:167], v[220:223], 0
	v_mfma_f32_16x16x32_bf16 v[70:73], v[172:175], v[220:223], 0
	v_mfma_f32_16x16x32_bf16 v[122:125], v[168:171], v[200:203], v[122:125]
	v_mfma_f32_16x16x32_bf16 v[118:121], v[176:179], v[200:203], v[118:121]
	v_mfma_f32_16x16x32_bf16 v[110:113], v[168:171], v[208:211], v[110:113]
	v_mfma_f32_16x16x32_bf16 v[102:105], v[176:179], v[208:211], v[102:105]
	v_mfma_f32_16x16x32_bf16 v[94:97], v[168:171], v[216:219], v[94:97]
	v_mfma_f32_16x16x32_bf16 v[86:89], v[176:179], v[216:219], v[86:89]
	v_mfma_f32_16x16x32_bf16 v[78:81], v[168:171], v[224:227], v[78:81]
	v_mfma_f32_16x16x32_bf16 v[70:73], v[176:179], v[224:227], v[70:73]
	s_setprio 0
	s_setprio 1
	v_mfma_f32_16x16x32_bf16 v[126:129], v[180:183], v[196:199], 0
	v_mfma_f32_16x16x32_bf16 v[114:117], v[188:191], v[196:199], 0
	v_mfma_f32_16x16x32_bf16 v[106:109], v[180:183], v[204:207], 0
	v_mfma_f32_16x16x32_bf16 v[98:101], v[188:191], v[204:207], 0
	v_mfma_f32_16x16x32_bf16 v[90:93], v[180:183], v[212:215], 0
	v_mfma_f32_16x16x32_bf16 v[82:85], v[188:191], v[212:215], 0
	v_mfma_f32_16x16x32_bf16 v[74:77], v[180:183], v[220:223], 0
	v_mfma_f32_16x16x32_bf16 v[66:69], v[188:191], v[220:223], 0
	v_mfma_f32_16x16x32_bf16 v[126:129], v[184:187], v[200:203], v[126:129]
	v_mfma_f32_16x16x32_bf16 v[114:117], v[192:195], v[200:203], v[114:117]
	v_mfma_f32_16x16x32_bf16 v[106:109], v[184:187], v[208:211], v[106:109]
	v_mfma_f32_16x16x32_bf16 v[98:101], v[192:195], v[208:211], v[98:101]
	v_mfma_f32_16x16x32_bf16 v[90:93], v[184:187], v[216:219], v[90:93]
	v_mfma_f32_16x16x32_bf16 v[82:85], v[192:195], v[216:219], v[82:85]
	v_mfma_f32_16x16x32_bf16 v[74:77], v[184:187], v[224:227], v[74:77]
	v_mfma_f32_16x16x32_bf16 v[66:69], v[192:195], v[224:227], v[66:69]
	s_barrier
	s_setprio 0
	s_add_u32 s98, s96, 0x40000
	s_addc_u32 s99, s97, 0
	s_add_i32 s7, s76, s25
	s_mov_b32 m0, s7
	s_nop 0
	global_load_lds_dwordx4 v132, s[96:97]
	s_add_i32 m0, s7, 0x2000
	s_add_i32 s7, s77, s25
	global_load_lds_dwordx4 v136, s[96:97]
	s_mov_b32 m0, s7
	s_nop 0
	global_load_lds_dwordx4 v132, s[98:99]
	s_add_i32 m0, s7, 0x2000
	s_nop 0
	global_load_lds_dwordx4 v136, s[98:99]
	s_mov_b32 m0, s49
	s_nop 0
	global_load_lds_dwordx4 v130, s[94:95]
	s_mov_b32 m0, s58
	s_nop 0
	global_load_lds_dwordx4 v134, s[94:95]
	ds_read_b128 v[196:199], v160 offset:16384
	ds_read_b128 v[200:203], v160 offset:17408
	ds_read_b128 v[204:207], v160 offset:18432
	ds_read_b128 v[208:211], v160 offset:19456
	ds_read_b128 v[212:215], v160 offset:20480
	ds_read_b128 v[216:219], v160 offset:21504
	ds_read_b128 v[220:223], v160 offset:22528
	ds_read_b128 v[224:227], v160 offset:23552
	s_waitcnt vmcnt(8)
	s_waitcnt lgkmcnt(0)
	s_setprio 1
	s_barrier
	v_mfma_f32_16x16x32_bf16 v[62:65], v[164:167], v[196:199], 0
	v_mfma_f32_16x16x32_bf16 v[54:57], v[172:175], v[196:199], 0
	v_mfma_f32_16x16x32_bf16 v[46:49], v[164:167], v[204:207], 0
	v_mfma_f32_16x16x32_bf16 v[38:41], v[172:175], v[204:207], 0
	v_mfma_f32_16x16x32_bf16 v[30:33], v[164:167], v[212:215], 0
	v_mfma_f32_16x16x32_bf16 v[22:25], v[172:175], v[212:215], 0
	v_mfma_f32_16x16x32_bf16 v[14:17], v[164:167], v[220:223], 0
	v_mfma_f32_16x16x32_bf16 v[6:9], v[172:175], v[220:223], 0
	v_mfma_f32_16x16x32_bf16 v[62:65], v[168:171], v[200:203], v[62:65]
	v_mfma_f32_16x16x32_bf16 v[54:57], v[176:179], v[200:203], v[54:57]
	v_mfma_f32_16x16x32_bf16 v[46:49], v[168:171], v[208:211], v[46:49]
	v_mfma_f32_16x16x32_bf16 v[38:41], v[176:179], v[208:211], v[38:41]
	v_mfma_f32_16x16x32_bf16 v[30:33], v[168:171], v[216:219], v[30:33]
	v_mfma_f32_16x16x32_bf16 v[22:25], v[176:179], v[216:219], v[22:25]
	v_mfma_f32_16x16x32_bf16 v[14:17], v[168:171], v[224:227], v[14:17]
	v_mfma_f32_16x16x32_bf16 v[6:9], v[176:179], v[224:227], v[6:9]
	s_setprio 0
	s_setprio 1
	v_mfma_f32_16x16x32_bf16 v[58:61], v[180:183], v[196:199], 0
	v_mfma_f32_16x16x32_bf16 v[50:53], v[188:191], v[196:199], 0
	v_mfma_f32_16x16x32_bf16 v[42:45], v[180:183], v[204:207], 0
	v_mfma_f32_16x16x32_bf16 v[34:37], v[188:191], v[204:207], 0
	v_mfma_f32_16x16x32_bf16 v[26:29], v[180:183], v[212:215], 0
	v_mfma_f32_16x16x32_bf16 v[18:21], v[188:191], v[212:215], 0
	v_mfma_f32_16x16x32_bf16 v[10:13], v[180:183], v[220:223], 0
	v_mfma_f32_16x16x32_bf16 v[2:5], v[188:191], v[220:223], 0
	v_mfma_f32_16x16x32_bf16 v[58:61], v[184:187], v[200:203], v[58:61]
	v_mfma_f32_16x16x32_bf16 v[50:53], v[192:195], v[200:203], v[50:53]
	v_mfma_f32_16x16x32_bf16 v[42:45], v[184:187], v[208:211], v[42:45]
	v_mfma_f32_16x16x32_bf16 v[34:37], v[192:195], v[208:211], v[34:37]
	v_mfma_f32_16x16x32_bf16 v[26:29], v[184:187], v[216:219], v[26:29]
	v_mfma_f32_16x16x32_bf16 v[18:21], v[192:195], v[216:219], v[18:21]
	v_mfma_f32_16x16x32_bf16 v[10:13], v[184:187], v[224:227], v[10:13]
	v_mfma_f32_16x16x32_bf16 v[2:5], v[192:195], v[224:227], v[2:5]
	s_barrier
	s_setprio 0
	s_add_u32 s98, s94, 0x40000
	s_addc_u32 s99, s95, 0
	s_add_i32 s7, 0, 0x18000
	s_add_i32 s47, 0, 0x1c000
	s_mov_b32 m0, s59
	s_nop 0
	global_load_lds_dwordx4 v130, s[98:99]
	s_mov_b32 m0, s60
	s_nop 0
	global_load_lds_dwordx4 v134, s[98:99]
	ds_read_b128 v[164:167], v232
	ds_read_b128 v[168:171], v232 offset:1024
	ds_read_b128 v[172:175], v232 offset:2048
	ds_read_b128 v[176:179], v232 offset:3072
	ds_read_b128 v[180:183], v233
	ds_read_b128 v[184:187], v233 offset:1024
	ds_read_b128 v[188:191], v233 offset:2048
	ds_read_b128 v[192:195], v233 offset:3072
	ds_read_b128 v[196:199], v160 offset:32768
	ds_read_b128 v[200:203], v160 offset:33792
	ds_read_b128 v[204:207], v160 offset:34816
	ds_read_b128 v[208:211], v160 offset:35840
	ds_read_b128 v[212:215], v160 offset:36864
	ds_read_b128 v[216:219], v160 offset:37888
	ds_read_b128 v[220:223], v160 offset:38912
	ds_read_b128 v[224:227], v160 offset:39936
	s_waitcnt vmcnt(8)
	s_waitcnt lgkmcnt(0)
	s_setprio 1
	s_barrier
	v_mfma_f32_16x16x32_bf16 v[122:125], v[164:167], v[196:199], v[122:125]
	v_mfma_f32_16x16x32_bf16 v[118:121], v[172:175], v[196:199], v[118:121]
	v_mfma_f32_16x16x32_bf16 v[110:113], v[164:167], v[204:207], v[110:113]
	v_mfma_f32_16x16x32_bf16 v[102:105], v[172:175], v[204:207], v[102:105]
	v_mfma_f32_16x16x32_bf16 v[94:97], v[164:167], v[212:215], v[94:97]
	v_mfma_f32_16x16x32_bf16 v[86:89], v[172:175], v[212:215], v[86:89]
	v_mfma_f32_16x16x32_bf16 v[78:81], v[164:167], v[220:223], v[78:81]
	v_mfma_f32_16x16x32_bf16 v[70:73], v[172:175], v[220:223], v[70:73]
	v_mfma_f32_16x16x32_bf16 v[122:125], v[168:171], v[200:203], v[122:125]
	v_mfma_f32_16x16x32_bf16 v[118:121], v[176:179], v[200:203], v[118:121]
	v_mfma_f32_16x16x32_bf16 v[110:113], v[168:171], v[208:211], v[110:113]
	v_mfma_f32_16x16x32_bf16 v[102:105], v[176:179], v[208:211], v[102:105]
	v_mfma_f32_16x16x32_bf16 v[94:97], v[168:171], v[216:219], v[94:97]
	v_mfma_f32_16x16x32_bf16 v[86:89], v[176:179], v[216:219], v[86:89]
	v_mfma_f32_16x16x32_bf16 v[78:81], v[168:171], v[224:227], v[78:81]
	v_mfma_f32_16x16x32_bf16 v[70:73], v[176:179], v[224:227], v[70:73]
	s_setprio 0
	s_setprio 1
	v_mfma_f32_16x16x32_bf16 v[126:129], v[180:183], v[196:199], v[126:129]
	v_mfma_f32_16x16x32_bf16 v[114:117], v[188:191], v[196:199], v[114:117]
	v_mfma_f32_16x16x32_bf16 v[106:109], v[180:183], v[204:207], v[106:109]
	v_mfma_f32_16x16x32_bf16 v[98:101], v[188:191], v[204:207], v[98:101]
	v_mfma_f32_16x16x32_bf16 v[90:93], v[180:183], v[212:215], v[90:93]
	v_mfma_f32_16x16x32_bf16 v[82:85], v[188:191], v[212:215], v[82:85]
	v_mfma_f32_16x16x32_bf16 v[74:77], v[180:183], v[220:223], v[74:77]
	v_mfma_f32_16x16x32_bf16 v[66:69], v[188:191], v[220:223], v[66:69]
	v_mfma_f32_16x16x32_bf16 v[126:129], v[184:187], v[200:203], v[126:129]
	v_mfma_f32_16x16x32_bf16 v[114:117], v[192:195], v[200:203], v[114:117]
	v_mfma_f32_16x16x32_bf16 v[106:109], v[184:187], v[208:211], v[106:109]
	v_mfma_f32_16x16x32_bf16 v[98:101], v[192:195], v[208:211], v[98:101]
	v_mfma_f32_16x16x32_bf16 v[90:93], v[184:187], v[216:219], v[90:93]
	v_mfma_f32_16x16x32_bf16 v[82:85], v[192:195], v[216:219], v[82:85]
	v_mfma_f32_16x16x32_bf16 v[74:77], v[184:187], v[224:227], v[74:77]
	v_mfma_f32_16x16x32_bf16 v[66:69], v[192:195], v[224:227], v[66:69]
	s_barrier
	s_setprio 0
	s_add_u32 s96, s96, 0x80
	s_addc_u32 s97, s97, 0
	s_add_u32 s98, s96, 0x40000
	s_addc_u32 s99, s97, 0
	s_add_u32 s94, s94, 0x80
	s_addc_u32 s95, s95, 0
	s_add_i32 s7, s7, s25
	s_mov_b32 m0, s7
	s_nop 0
	global_load_lds_dwordx4 v132, s[96:97]
	s_add_i32 m0, s7, 0x2000
	s_add_i32 s7, s47, s25
	global_load_lds_dwordx4 v136, s[96:97]
	s_mov_b32 m0, s7
	s_nop 0
	global_load_lds_dwordx4 v132, s[98:99]
	s_add_i32 m0, s7, 0x2000
	s_nop 0
	global_load_lds_dwordx4 v136, s[98:99]
	s_mov_b32 m0, s66
	s_nop 0
	global_load_lds_dwordx4 v130, s[94:95]
	s_mov_b32 m0, s67
	s_nop 0
	global_load_lds_dwordx4 v134, s[94:95]
	ds_read_b128 v[196:199], v160 offset:49152
	ds_read_b128 v[200:203], v160 offset:50176
	ds_read_b128 v[204:207], v160 offset:51200
	ds_read_b128 v[208:211], v160 offset:52224
	ds_read_b128 v[212:215], v160 offset:53248
	ds_read_b128 v[216:219], v160 offset:54272
	ds_read_b128 v[220:223], v160 offset:55296
	ds_read_b128 v[224:227], v160 offset:56320
	s_waitcnt vmcnt(8)
	s_waitcnt lgkmcnt(0)
	s_setprio 1
	s_barrier
	v_mfma_f32_16x16x32_bf16 v[62:65], v[164:167], v[196:199], v[62:65]
	v_mfma_f32_16x16x32_bf16 v[54:57], v[172:175], v[196:199], v[54:57]
	v_mfma_f32_16x16x32_bf16 v[46:49], v[164:167], v[204:207], v[46:49]
	v_mfma_f32_16x16x32_bf16 v[38:41], v[172:175], v[204:207], v[38:41]
	v_mfma_f32_16x16x32_bf16 v[30:33], v[164:167], v[212:215], v[30:33]
	v_mfma_f32_16x16x32_bf16 v[22:25], v[172:175], v[212:215], v[22:25]
	v_mfma_f32_16x16x32_bf16 v[14:17], v[164:167], v[220:223], v[14:17]
	v_mfma_f32_16x16x32_bf16 v[6:9], v[172:175], v[220:223], v[6:9]
	v_mfma_f32_16x16x32_bf16 v[62:65], v[168:171], v[200:203], v[62:65]
	v_mfma_f32_16x16x32_bf16 v[54:57], v[176:179], v[200:203], v[54:57]
	v_mfma_f32_16x16x32_bf16 v[46:49], v[168:171], v[208:211], v[46:49]
	v_mfma_f32_16x16x32_bf16 v[38:41], v[176:179], v[208:211], v[38:41]
	v_mfma_f32_16x16x32_bf16 v[30:33], v[168:171], v[216:219], v[30:33]
	v_mfma_f32_16x16x32_bf16 v[22:25], v[176:179], v[216:219], v[22:25]
	v_mfma_f32_16x16x32_bf16 v[14:17], v[168:171], v[224:227], v[14:17]
	v_mfma_f32_16x16x32_bf16 v[6:9], v[176:179], v[224:227], v[6:9]
	s_setprio 0
	s_setprio 1
	v_mfma_f32_16x16x32_bf16 v[58:61], v[180:183], v[196:199], v[58:61]
	v_mfma_f32_16x16x32_bf16 v[50:53], v[188:191], v[196:199], v[50:53]
	v_mfma_f32_16x16x32_bf16 v[42:45], v[180:183], v[204:207], v[42:45]
	v_mfma_f32_16x16x32_bf16 v[34:37], v[188:191], v[204:207], v[34:37]
	v_mfma_f32_16x16x32_bf16 v[26:29], v[180:183], v[212:215], v[26:29]
	v_mfma_f32_16x16x32_bf16 v[18:21], v[188:191], v[212:215], v[18:21]
	v_mfma_f32_16x16x32_bf16 v[10:13], v[180:183], v[220:223], v[10:13]
	v_mfma_f32_16x16x32_bf16 v[2:5], v[188:191], v[220:223], v[2:5]
	v_mfma_f32_16x16x32_bf16 v[58:61], v[184:187], v[200:203], v[58:61]
	v_mfma_f32_16x16x32_bf16 v[50:53], v[192:195], v[200:203], v[50:53]
	v_mfma_f32_16x16x32_bf16 v[42:45], v[184:187], v[208:211], v[42:45]
	v_mfma_f32_16x16x32_bf16 v[34:37], v[192:195], v[208:211], v[34:37]
	v_mfma_f32_16x16x32_bf16 v[26:29], v[184:187], v[216:219], v[26:29]
	v_mfma_f32_16x16x32_bf16 v[18:21], v[192:195], v[216:219], v[18:21]
	v_mfma_f32_16x16x32_bf16 v[10:13], v[184:187], v[224:227], v[10:13]
	v_mfma_f32_16x16x32_bf16 v[2:5], v[192:195], v[224:227], v[2:5]
	s_barrier
	s_setprio 0
	s_mov_b32 s7, s45
	s_add_u32 s88, s88, 0x100
	s_addc_u32 s89, s89, 0
	s_add_u32 s86, s86, 0x100
	s_addc_u32 s87, s87, 0
	s_cmp_ge_i32 s45, s101
	s_cbranch_scc1 .Lmy_kexit_3

.LBB0_947:
	v_cmp_gt_i32_e32 vcc, 1, v138
	s_cbranch_vccnz .LBB0_1009
	v_lshl_add_u64 v[152:153], v[2:3], 0, s[18:19]
	v_add_u32_e32 v154, -2, v138
	s_waitcnt lgkmcnt(0)
	v_lshl_add_u64 v[150:151], v[4:5], 0, s[22:23]
	s_mov_b32 s7, 0
	s_cmp_eq_u32 s32, 1
	s_cbranch_scc0 .Lmy_nb_4
	s_mov_b32 s32, 0
	s_barrier
.Lmy_nb_4:
	s_nop 0
	v_readfirstlane_b32 s86, v152
	v_readfirstlane_b32 s87, v153
	v_readfirstlane_b32 s88, v150
	v_readfirstlane_b32 s89, v151
	v_readfirstlane_b32 s90, v146
	v_readfirstlane_b32 s91, v147
	v_readfirstlane_b32 s92, v148
	v_readfirstlane_b32 s93, v149
	v_readfirstlane_b32 s100, v154
	v_readfirstlane_b32 s101, v138
	v_add_u32_e32 v230, s74, v141
	v_add_u32_e32 v231, s75, v141
	v_add_u32_e32 v232, 0x18000, v141
	v_add_u32_e32 v233, 0x1c000, v141
	s_add_u32 s98, s86, 0xfffc0080
	s_addc_u32 s99, s87, -1
	s_cmp_eq_u32 s7, s100
	s_cselect_b64 s[94:95], s[90:91], s[98:99]
	s_cselect_b64 s[96:97], s[92:93], s[88:89]
	s_add_i32 s47, s7, 2
	s_nop 0
	s_mov_b32 m0, s76
	s_nop 0
	global_load_lds_dwordx4 v144, s[86:87]
	s_mov_b32 m0, s77
	s_nop 0
	global_load_lds_dwordx4 v142, s[86:87]
	ds_read_b128 v[164:167], v230
	ds_read_b128 v[168:171], v230 offset:1024
	ds_read_b128 v[172:175], v230 offset:2048
	ds_read_b128 v[176:179], v230 offset:3072
	ds_read_b128 v[180:183], v231
	ds_read_b128 v[184:187], v231 offset:1024
	ds_read_b128 v[188:191], v231 offset:2048
	ds_read_b128 v[192:195], v231 offset:3072
	ds_read_b128 v[196:199], v160
	ds_read_b128 v[200:203], v160 offset:1024
	ds_read_b128 v[204:207], v160 offset:2048
	ds_read_b128 v[208:211], v160 offset:3072
	ds_read_b128 v[212:215], v160 offset:4096
	ds_read_b128 v[216:219], v160 offset:5120
	ds_read_b128 v[220:223], v160 offset:6144
	ds_read_b128 v[224:227], v160 offset:7168
	s_waitcnt vmcnt(8)
	s_waitcnt lgkmcnt(0)
	s_setprio 1
	s_barrier
	v_mfma_f32_16x16x32_bf16 v[122:125], v[164:167], v[196:199], 0
	v_mfma_f32_16x16x32_bf16 v[118:121], v[172:175], v[196:199], 0
	v_mfma_f32_16x16x32_bf16 v[110:113], v[164:167], v[204:207], 0
	v_mfma_f32_16x16x32_bf16 v[102:105], v[172:175], v[204:207], 0
	v_mfma_f32_16x16x32_bf16 v[94:97], v[164:167], v[212:215], 0
	v_mfma_f32_16x16x32_bf16 v[86:89], v[172:175], v[212:215], 0
	v_mfma_f32_16x16x32_bf16 v[78:81], v[164:167], v[220:223], 0
	v_mfma_f32_16x16x32_bf16 v[70:73], v[172:175], v[220:223], 0
	v_mfma_f32_16x16x32_bf16 v[122:125], v[168:171], v[200:203], v[122:125]
	v_mfma_f32_16x16x32_bf16 v[118:121], v[176:179], v[200:203], v[118:121]
	v_mfma_f32_16x16x32_bf16 v[110:113], v[168:171], v[208:211], v[110:113]
	v_mfma_f32_16x16x32_bf16 v[102:105], v[176:179], v[208:211], v[102:105]
	v_mfma_f32_16x16x32_bf16 v[94:97], v[168:171], v[216:219], v[94:97]
	v_mfma_f32_16x16x32_bf16 v[86:89], v[176:179], v[216:219], v[86:89]
	v_mfma_f32_16x16x32_bf16 v[78:81], v[168:171], v[224:227], v[78:81]
	v_mfma_f32_16x16x32_bf16 v[70:73], v[176:179], v[224:227], v[70:73]
	s_setprio 0
	s_setprio 1
	v_mfma_f32_16x16x32_bf16 v[126:129], v[180:183], v[196:199], 0
	v_mfma_f32_16x16x32_bf16 v[114:117], v[188:191], v[196:199], 0
	v_mfma_f32_16x16x32_bf16 v[106:109], v[180:183], v[204:207], 0
	v_mfma_f32_16x16x32_bf16 v[98:101], v[188:191], v[204:207], 0
	v_mfma_f32_16x16x32_bf16 v[90:93], v[180:183], v[212:215], 0
	v_mfma_f32_16x16x32_bf16 v[82:85], v[188:191], v[212:215], 0
	v_mfma_f32_16x16x32_bf16 v[74:77], v[180:183], v[220:223], 0
	v_mfma_f32_16x16x32_bf16 v[66:69], v[188:191], v[220:223], 0
	v_mfma_f32_16x16x32_bf16 v[126:129], v[184:187], v[200:203], v[126:129]
	v_mfma_f32_16x16x32_bf16 v[114:117], v[192:195], v[200:203], v[114:117]
	v_mfma_f32_16x16x32_bf16 v[106:109], v[184:187], v[208:211], v[106:109]
	v_mfma_f32_16x16x32_bf16 v[98:101], v[192:195], v[208:211], v[98:101]
	v_mfma_f32_16x16x32_bf16 v[90:93], v[184:187], v[216:219], v[90:93]
	v_mfma_f32_16x16x32_bf16 v[82:85], v[192:195], v[216:219], v[82:85]
	v_mfma_f32_16x16x32_bf16 v[74:77], v[184:187], v[224:227], v[74:77]
	v_mfma_f32_16x16x32_bf16 v[66:69], v[192:195], v[224:227], v[66:69]
	s_barrier
	s_setprio 0
	s_add_u32 s98, s96, 0x40000
	s_addc_u32 s99, s97, 0
	s_mov_b32 m0, s78
	s_nop 0
	global_load_lds_dwordx4 v132, s[96:97]
	s_mov_b32 m0, s79
	s_add_i32 s7, s75, s29
	global_load_lds_dwordx4 v136, s[96:97]
	s_mov_b32 m0, s7
	s_nop 0
	global_load_lds_dwordx4 v132, s[98:99]
	s_add_i32 m0, s7, 0x2000
	s_nop 0
	global_load_lds_dwordx4 v136, s[98:99]
	s_mov_b32 m0, s51
	s_nop 0
	global_load_lds_dwordx4 v130, s[94:95]
	s_mov_b32 m0, s60
	s_nop 0
	global_load_lds_dwordx4 v134, s[94:95]
	ds_read_b128 v[196:199], v160 offset:16384
	ds_read_b128 v[200:203], v160 offset:17408
	ds_read_b128 v[204:207], v160 offset:18432
	ds_read_b128 v[208:211], v160 offset:19456
	ds_read_b128 v[212:215], v160 offset:20480
	ds_read_b128 v[216:219], v160 offset:21504
	ds_read_b128 v[220:223], v160 offset:22528
	ds_read_b128 v[224:227], v160 offset:23552
	s_waitcnt vmcnt(8)
	s_waitcnt lgkmcnt(0)
	s_setprio 1
	s_barrier
	v_mfma_f32_16x16x32_bf16 v[62:65], v[164:167], v[196:199], 0
	v_mfma_f32_16x16x32_bf16 v[54:57], v[172:175], v[196:199], 0
	v_mfma_f32_16x16x32_bf16 v[46:49], v[164:167], v[204:207], 0
	v_mfma_f32_16x16x32_bf16 v[38:41], v[172:175], v[204:207], 0
	v_mfma_f32_16x16x32_bf16 v[30:33], v[164:167], v[212:215], 0
	v_mfma_f32_16x16x32_bf16 v[22:25], v[172:175], v[212:215], 0
	v_mfma_f32_16x16x32_bf16 v[14:17], v[164:167], v[220:223], 0
	v_mfma_f32_16x16x32_bf16 v[6:9], v[172:175], v[220:223], 0
	v_mfma_f32_16x16x32_bf16 v[62:65], v[168:171], v[200:203], v[62:65]
	v_mfma_f32_16x16x32_bf16 v[54:57], v[176:179], v[200:203], v[54:57]
	v_mfma_f32_16x16x32_bf16 v[46:49], v[168:171], v[208:211], v[46:49]
	v_mfma_f32_16x16x32_bf16 v[38:41], v[176:179], v[208:211], v[38:41]
	v_mfma_f32_16x16x32_bf16 v[30:33], v[168:171], v[216:219], v[30:33]
	v_mfma_f32_16x16x32_bf16 v[22:25], v[176:179], v[216:219], v[22:25]
	v_mfma_f32_16x16x32_bf16 v[14:17], v[168:171], v[224:227], v[14:17]
	v_mfma_f32_16x16x32_bf16 v[6:9], v[176:179], v[224:227], v[6:9]
	s_setprio 0
	s_setprio 1
	v_mfma_f32_16x16x32_bf16 v[58:61], v[180:183], v[196:199], 0
	v_mfma_f32_16x16x32_bf16 v[50:53], v[188:191], v[196:199], 0
	v_mfma_f32_16x16x32_bf16 v[42:45], v[180:183], v[204:207], 0
	v_mfma_f32_16x16x32_bf16 v[34:37], v[188:191], v[204:207], 0
	v_mfma_f32_16x16x32_bf16 v[26:29], v[180:183], v[212:215], 0
	v_mfma_f32_16x16x32_bf16 v[18:21], v[188:191], v[212:215], 0
	v_mfma_f32_16x16x32_bf16 v[10:13], v[180:183], v[220:223], 0
	v_mfma_f32_16x16x32_bf16 v[2:5], v[188:191], v[220:223], 0
	v_mfma_f32_16x16x32_bf16 v[58:61], v[184:187], v[200:203], v[58:61]
	v_mfma_f32_16x16x32_bf16 v[50:53], v[192:195], v[200:203], v[50:53]
	v_mfma_f32_16x16x32_bf16 v[42:45], v[184:187], v[208:211], v[42:45]
	v_mfma_f32_16x16x32_bf16 v[34:37], v[192:195], v[208:211], v[34:37]
	v_mfma_f32_16x16x32_bf16 v[26:29], v[184:187], v[216:219], v[26:29]
	v_mfma_f32_16x16x32_bf16 v[18:21], v[192:195], v[216:219], v[18:21]
	v_mfma_f32_16x16x32_bf16 v[10:13], v[184:187], v[224:227], v[10:13]
	v_mfma_f32_16x16x32_bf16 v[2:5], v[192:195], v[224:227], v[2:5]
	s_barrier
	s_setprio 0
	s_add_u32 s98, s94, 0x40000
	s_addc_u32 s99, s95, 0
	s_add_i32 s7, 0, 0x18000
	s_add_i32 s49, 0, 0x1c000
	s_mov_b32 m0, s61
	s_nop 0
	global_load_lds_dwordx4 v130, s[98:99]
	s_mov_b32 m0, s62
	s_nop 0
	global_load_lds_dwordx4 v134, s[98:99]
	ds_read_b128 v[164:167], v232
	ds_read_b128 v[168:171], v232 offset:1024
	ds_read_b128 v[172:175], v232 offset:2048
	ds_read_b128 v[176:179], v232 offset:3072
	ds_read_b128 v[180:183], v233
	ds_read_b128 v[184:187], v233 offset:1024
	ds_read_b128 v[188:191], v233 offset:2048
	ds_read_b128 v[192:195], v233 offset:3072
	ds_read_b128 v[196:199], v160 offset:32768
	ds_read_b128 v[200:203], v160 offset:33792
	ds_read_b128 v[204:207], v160 offset:34816
	ds_read_b128 v[208:211], v160 offset:35840
	ds_read_b128 v[212:215], v160 offset:36864
	ds_read_b128 v[216:219], v160 offset:37888
	ds_read_b128 v[220:223], v160 offset:38912
	ds_read_b128 v[224:227], v160 offset:39936
	s_waitcnt vmcnt(8)
	s_waitcnt lgkmcnt(0)
	s_setprio 1
	s_barrier
	v_mfma_f32_16x16x32_bf16 v[122:125], v[164:167], v[196:199], v[122:125]
	v_mfma_f32_16x16x32_bf16 v[118:121], v[172:175], v[196:199], v[118:121]
	v_mfma_f32_16x16x32_bf16 v[110:113], v[164:167], v[204:207], v[110:113]
	v_mfma_f32_16x16x32_bf16 v[102:105], v[172:175], v[204:207], v[102:105]
	v_mfma_f32_16x16x32_bf16 v[94:97], v[164:167], v[212:215], v[94:97]
	v_mfma_f32_16x16x32_bf16 v[86:89], v[172:175], v[212:215], v[86:89]
	v_mfma_f32_16x16x32_bf16 v[78:81], v[164:167], v[220:223], v[78:81]
	v_mfma_f32_16x16x32_bf16 v[70:73], v[172:175], v[220:223], v[70:73]
	v_mfma_f32_16x16x32_bf16 v[122:125], v[168:171], v[200:203], v[122:125]
	v_mfma_f32_16x16x32_bf16 v[118:121], v[176:179], v[200:203], v[118:121]
	v_mfma_f32_16x16x32_bf16 v[110:113], v[168:171], v[208:211], v[110:113]
	v_mfma_f32_16x16x32_bf16 v[102:105], v[176:179], v[208:211], v[102:105]
	v_mfma_f32_16x16x32_bf16 v[94:97], v[168:171], v[216:219], v[94:97]
	v_mfma_f32_16x16x32_bf16 v[86:89], v[176:179], v[216:219], v[86:89]
	v_mfma_f32_16x16x32_bf16 v[78:81], v[168:171], v[224:227], v[78:81]
	v_mfma_f32_16x16x32_bf16 v[70:73], v[176:179], v[224:227], v[70:73]
	s_setprio 0
	s_setprio 1
	v_mfma_f32_16x16x32_bf16 v[126:129], v[180:183], v[196:199], v[126:129]
	v_mfma_f32_16x16x32_bf16 v[114:117], v[188:191], v[196:199], v[114:117]
	v_mfma_f32_16x16x32_bf16 v[106:109], v[180:183], v[204:207], v[106:109]
	v_mfma_f32_16x16x32_bf16 v[98:101], v[188:191], v[204:207], v[98:101]
	v_mfma_f32_16x16x32_bf16 v[90:93], v[180:183], v[212:215], v[90:93]
	v_mfma_f32_16x16x32_bf16 v[82:85], v[188:191], v[212:215], v[82:85]
	v_mfma_f32_16x16x32_bf16 v[74:77], v[180:183], v[220:223], v[74:77]
	v_mfma_f32_16x16x32_bf16 v[66:69], v[188:191], v[220:223], v[66:69]
	v_mfma_f32_16x16x32_bf16 v[126:129], v[184:187], v[200:203], v[126:129]
	v_mfma_f32_16x16x32_bf16 v[114:117], v[192:195], v[200:203], v[114:117]
	v_mfma_f32_16x16x32_bf16 v[106:109], v[184:187], v[208:211], v[106:109]
	v_mfma_f32_16x16x32_bf16 v[98:101], v[192:195], v[208:211], v[98:101]
	v_mfma_f32_16x16x32_bf16 v[90:93], v[184:187], v[216:219], v[90:93]
	v_mfma_f32_16x16x32_bf16 v[82:85], v[192:195], v[216:219], v[82:85]
	v_mfma_f32_16x16x32_bf16 v[74:77], v[184:187], v[224:227], v[74:77]
	v_mfma_f32_16x16x32_bf16 v[66:69], v[192:195], v[224:227], v[66:69]
	s_barrier
	s_setprio 0
	s_add_u32 s96, s96, 0x80
	s_addc_u32 s97, s97, 0
	s_add_u32 s98, s96, 0x40000
	s_addc_u32 s99, s97, 0
	s_add_u32 s94, s94, 0x80
	s_addc_u32 s95, s95, 0
	s_add_i32 s7, s7, s29
	s_mov_b32 m0, s7
	s_nop 0
	global_load_lds_dwordx4 v132, s[96:97]
	s_add_i32 m0, s7, 0x2000
	s_add_i32 s7, s49, s29
	global_load_lds_dwordx4 v136, s[96:97]
	s_mov_b32 m0, s7
	s_nop 0
	global_load_lds_dwordx4 v132, s[98:99]
	s_add_i32 m0, s7, 0x2000
	s_nop 0
	global_load_lds_dwordx4 v136, s[98:99]
	s_mov_b32 m0, s63
	s_nop 0
	global_load_lds_dwordx4 v130, s[94:95]
	s_mov_b32 m0, s64
	s_nop 0
	global_load_lds_dwordx4 v134, s[94:95]
	ds_read_b128 v[196:199], v160 offset:49152
	ds_read_b128 v[200:203], v160 offset:50176
	ds_read_b128 v[204:207], v160 offset:51200
	ds_read_b128 v[208:211], v160 offset:52224
	ds_read_b128 v[212:215], v160 offset:53248
	ds_read_b128 v[216:219], v160 offset:54272
	ds_read_b128 v[220:223], v160 offset:55296
	ds_read_b128 v[224:227], v160 offset:56320
	s_waitcnt vmcnt(8)
	s_waitcnt lgkmcnt(0)
	s_setprio 1
	s_barrier
	v_mfma_f32_16x16x32_bf16 v[62:65], v[164:167], v[196:199], v[62:65]
	v_mfma_f32_16x16x32_bf16 v[54:57], v[172:175], v[196:199], v[54:57]
	v_mfma_f32_16x16x32_bf16 v[46:49], v[164:167], v[204:207], v[46:49]
	v_mfma_f32_16x16x32_bf16 v[38:41], v[172:175], v[204:207], v[38:41]
	v_mfma_f32_16x16x32_bf16 v[30:33], v[164:167], v[212:215], v[30:33]
	v_mfma_f32_16x16x32_bf16 v[22:25], v[172:175], v[212:215], v[22:25]
	v_mfma_f32_16x16x32_bf16 v[14:17], v[164:167], v[220:223], v[14:17]
	v_mfma_f32_16x16x32_bf16 v[6:9], v[172:175], v[220:223], v[6:9]
	v_mfma_f32_16x16x32_bf16 v[62:65], v[168:171], v[200:203], v[62:65]
	v_mfma_f32_16x16x32_bf16 v[54:57], v[176:179], v[200:203], v[54:57]
	v_mfma_f32_16x16x32_bf16 v[46:49], v[168:171], v[208:211], v[46:49]
	v_mfma_f32_16x16x32_bf16 v[38:41], v[176:179], v[208:211], v[38:41]
	v_mfma_f32_16x16x32_bf16 v[30:33], v[168:171], v[216:219], v[30:33]
	v_mfma_f32_16x16x32_bf16 v[22:25], v[176:179], v[216:219], v[22:25]
	v_mfma_f32_16x16x32_bf16 v[14:17], v[168:171], v[224:227], v[14:17]
	v_mfma_f32_16x16x32_bf16 v[6:9], v[176:179], v[224:227], v[6:9]
	s_setprio 0
	s_setprio 1
	v_mfma_f32_16x16x32_bf16 v[58:61], v[180:183], v[196:199], v[58:61]
	v_mfma_f32_16x16x32_bf16 v[50:53], v[188:191], v[196:199], v[50:53]
	v_mfma_f32_16x16x32_bf16 v[42:45], v[180:183], v[204:207], v[42:45]
	v_mfma_f32_16x16x32_bf16 v[34:37], v[188:191], v[204:207], v[34:37]
	v_mfma_f32_16x16x32_bf16 v[26:29], v[180:183], v[212:215], v[26:29]
	v_mfma_f32_16x16x32_bf16 v[18:21], v[188:191], v[212:215], v[18:21]
	v_mfma_f32_16x16x32_bf16 v[10:13], v[180:183], v[220:223], v[10:13]
	v_mfma_f32_16x16x32_bf16 v[2:5], v[188:191], v[220:223], v[2:5]
	v_mfma_f32_16x16x32_bf16 v[58:61], v[184:187], v[200:203], v[58:61]
	v_mfma_f32_16x16x32_bf16 v[50:53], v[192:195], v[200:203], v[50:53]
	v_mfma_f32_16x16x32_bf16 v[42:45], v[184:187], v[208:211], v[42:45]
	v_mfma_f32_16x16x32_bf16 v[34:37], v[192:195], v[208:211], v[34:37]
	v_mfma_f32_16x16x32_bf16 v[26:29], v[184:187], v[216:219], v[26:29]
	v_mfma_f32_16x16x32_bf16 v[18:21], v[192:195], v[216:219], v[18:21]
	v_mfma_f32_16x16x32_bf16 v[10:13], v[184:187], v[224:227], v[10:13]
	v_mfma_f32_16x16x32_bf16 v[2:5], v[192:195], v[224:227], v[2:5]
	s_barrier
	s_setprio 0
	s_mov_b32 s7, s47
	s_add_u32 s88, s88, 0x100
	s_addc_u32 s89, s89, 0
	s_add_u32 s86, s86, 0x100
	s_addc_u32 s87, s87, 0
	s_cmp_ge_i32 s47, s101
	s_cbranch_scc1 .Lmy_kexit_4

.LBB0_1007:
	s_andn2_b64 vcc, exec, s[14:15]
	s_cbranch_vccnz .LBB0_943
	s_mov_b32 s32, 1
	s_branch .LBB0_943

.LBB0_1078:
	v_cmp_gt_i32_e32 vcc, 1, v156
	s_cbranch_vccnz .LBB0_1140
	v_lshl_add_u64 v[152:153], v[2:3], 0, s[20:21]
	v_add_u32_e32 v138, -2, v156
	s_mov_b32 s6, 0
	s_cmp_eq_u32 s32, 1
	s_cbranch_scc0 .Lmy_nb_5
	s_mov_b32 s32, 0
	s_barrier
.Lmy_nb_5:
	s_nop 0
	v_readfirstlane_b32 s86, v150
	v_readfirstlane_b32 s87, v151
	v_readfirstlane_b32 s88, v152
	v_readfirstlane_b32 s89, v153
	v_readfirstlane_b32 s90, v146
	v_readfirstlane_b32 s91, v147
	v_readfirstlane_b32 s92, v148
	v_readfirstlane_b32 s93, v149
	v_readfirstlane_b32 s100, v138
	v_readfirstlane_b32 s101, v156
	v_add_u32_e32 v230, s67, v141
	v_add_u32_e32 v231, s68, v141
	v_add_u32_e32 v232, 0x18000, v141
	v_add_u32_e32 v233, 0x1c000, v141
	s_add_u32 s98, s86, 0x100
	s_addc_u32 s99, s87, 0
	s_cmp_eq_u32 s6, s100
	s_cselect_b64 s[94:95], s[90:91], s[98:99]
	s_cselect_b64 s[96:97], s[92:93], s[88:89]
	s_add_i32 s7, s6, 2
	s_nop 0
	s_add_i32 m0, s46, 0xc000
	s_nop 0
	global_load_lds_dwordx4 v144, s[86:87]
	s_add_i32 m0, s46, 0xe000
	s_nop 0
	global_load_lds_dwordx4 v142, s[86:87]
	ds_read_b128 v[164:167], v230
	ds_read_b128 v[168:171], v230 offset:1024
	ds_read_b128 v[172:175], v230 offset:2048
	ds_read_b128 v[176:179], v230 offset:3072
	ds_read_b128 v[180:183], v231
	ds_read_b128 v[184:187], v231 offset:1024
	ds_read_b128 v[188:191], v231 offset:2048
	ds_read_b128 v[192:195], v231 offset:3072
	ds_read_b128 v[196:199], v160
	ds_read_b128 v[200:203], v160 offset:1024
	ds_read_b128 v[204:207], v160 offset:2048
	ds_read_b128 v[208:211], v160 offset:3072
	ds_read_b128 v[212:215], v160 offset:4096
	ds_read_b128 v[216:219], v160 offset:5120
	ds_read_b128 v[220:223], v160 offset:6144
	ds_read_b128 v[224:227], v160 offset:7168
	s_waitcnt vmcnt(8)
	s_waitcnt lgkmcnt(0)
	s_setprio 1
	s_barrier
	v_mfma_f32_16x16x32_bf16 v[122:125], v[164:167], v[196:199], 0
	v_mfma_f32_16x16x32_bf16 v[118:121], v[172:175], v[196:199], 0
	v_mfma_f32_16x16x32_bf16 v[110:113], v[164:167], v[204:207], 0
	v_mfma_f32_16x16x32_bf16 v[102:105], v[172:175], v[204:207], 0
	v_mfma_f32_16x16x32_bf16 v[94:97], v[164:167], v[212:215], 0
	v_mfma_f32_16x16x32_bf16 v[86:89], v[172:175], v[212:215], 0
	v_mfma_f32_16x16x32_bf16 v[78:81], v[164:167], v[220:223], 0
	v_mfma_f32_16x16x32_bf16 v[70:73], v[172:175], v[220:223], 0
	v_mfma_f32_16x16x32_bf16 v[122:125], v[168:171], v[200:203], v[122:125]
	v_mfma_f32_16x16x32_bf16 v[118:121], v[176:179], v[200:203], v[118:121]
	v_mfma_f32_16x16x32_bf16 v[110:113], v[168:171], v[208:211], v[110:113]
	v_mfma_f32_16x16x32_bf16 v[102:105], v[176:179], v[208:211], v[102:105]
	v_mfma_f32_16x16x32_bf16 v[94:97], v[168:171], v[216:219], v[94:97]
	v_mfma_f32_16x16x32_bf16 v[86:89], v[176:179], v[216:219], v[86:89]
	v_mfma_f32_16x16x32_bf16 v[78:81], v[168:171], v[224:227], v[78:81]
	v_mfma_f32_16x16x32_bf16 v[70:73], v[176:179], v[224:227], v[70:73]
	s_setprio 0
	s_setprio 1
	v_mfma_f32_16x16x32_bf16 v[126:129], v[180:183], v[196:199], 0
	v_mfma_f32_16x16x32_bf16 v[114:117], v[188:191], v[196:199], 0
	v_mfma_f32_16x16x32_bf16 v[106:109], v[180:183], v[204:207], 0
	v_mfma_f32_16x16x32_bf16 v[98:101], v[188:191], v[204:207], 0
	v_mfma_f32_16x16x32_bf16 v[90:93], v[180:183], v[212:215], 0
	v_mfma_f32_16x16x32_bf16 v[82:85], v[188:191], v[212:215], 0
	v_mfma_f32_16x16x32_bf16 v[74:77], v[180:183], v[220:223], 0
	v_mfma_f32_16x16x32_bf16 v[66:69], v[188:191], v[220:223], 0
	v_mfma_f32_16x16x32_bf16 v[126:129], v[184:187], v[200:203], v[126:129]
	v_mfma_f32_16x16x32_bf16 v[114:117], v[192:195], v[200:203], v[114:117]
	v_mfma_f32_16x16x32_bf16 v[106:109], v[184:187], v[208:211], v[106:109]
	v_mfma_f32_16x16x32_bf16 v[98:101], v[192:195], v[208:211], v[98:101]
	v_mfma_f32_16x16x32_bf16 v[90:93], v[184:187], v[216:219], v[90:93]
	v_mfma_f32_16x16x32_bf16 v[82:85], v[192:195], v[216:219], v[82:85]
	v_mfma_f32_16x16x32_bf16 v[74:77], v[184:187], v[224:227], v[74:77]
	v_mfma_f32_16x16x32_bf16 v[66:69], v[192:195], v[224:227], v[66:69]
	s_barrier
	s_setprio 0
	s_add_u32 s98, s96, 0xb0000
	s_addc_u32 s99, s97, 0
	s_add_i32 s6, s67, s23
	s_mov_b32 m0, s6
	s_nop 0
	global_load_lds_dwordx4 v132, s[96:97]
	s_add_i32 m0, s6, 0x2000
	s_add_i32 s6, s68, s23
	global_load_lds_dwordx4 v136, s[96:97]
	s_mov_b32 m0, s6
	s_nop 0
	global_load_lds_dwordx4 v132, s[98:99]
	s_add_i32 m0, s6, 0x2000
	s_nop 0
	global_load_lds_dwordx4 v136, s[98:99]
	s_mov_b32 m0, s46
	s_nop 0
	global_load_lds_dwordx4 v130, s[94:95]
	s_mov_b32 m0, s47
	s_nop 0
	global_load_lds_dwordx4 v134, s[94:95]
	ds_read_b128 v[196:199], v160 offset:16384
	ds_read_b128 v[200:203], v160 offset:17408
	ds_read_b128 v[204:207], v160 offset:18432
	ds_read_b128 v[208:211], v160 offset:19456
	ds_read_b128 v[212:215], v160 offset:20480
	ds_read_b128 v[216:219], v160 offset:21504
	ds_read_b128 v[220:223], v160 offset:22528
	ds_read_b128 v[224:227], v160 offset:23552
	s_waitcnt vmcnt(8)
	s_waitcnt lgkmcnt(0)
	s_setprio 1
	s_barrier
	v_mfma_f32_16x16x32_bf16 v[62:65], v[164:167], v[196:199], 0
	v_mfma_f32_16x16x32_bf16 v[54:57], v[172:175], v[196:199], 0
	v_mfma_f32_16x16x32_bf16 v[46:49], v[164:167], v[204:207], 0
	v_mfma_f32_16x16x32_bf16 v[38:41], v[172:175], v[204:207], 0
	v_mfma_f32_16x16x32_bf16 v[30:33], v[164:167], v[212:215], 0
	v_mfma_f32_16x16x32_bf16 v[22:25], v[172:175], v[212:215], 0
	v_mfma_f32_16x16x32_bf16 v[14:17], v[164:167], v[220:223], 0
	v_mfma_f32_16x16x32_bf16 v[6:9], v[172:175], v[220:223], 0
	v_mfma_f32_16x16x32_bf16 v[62:65], v[168:171], v[200:203], v[62:65]
	v_mfma_f32_16x16x32_bf16 v[54:57], v[176:179], v[200:203], v[54:57]
	v_mfma_f32_16x16x32_bf16 v[46:49], v[168:171], v[208:211], v[46:49]
	v_mfma_f32_16x16x32_bf16 v[38:41], v[176:179], v[208:211], v[38:41]
	v_mfma_f32_16x16x32_bf16 v[30:33], v[168:171], v[216:219], v[30:33]
	v_mfma_f32_16x16x32_bf16 v[22:25], v[176:179], v[216:219], v[22:25]
	v_mfma_f32_16x16x32_bf16 v[14:17], v[168:171], v[224:227], v[14:17]
	v_mfma_f32_16x16x32_bf16 v[6:9], v[176:179], v[224:227], v[6:9]
	s_setprio 0
	s_setprio 1
	v_mfma_f32_16x16x32_bf16 v[58:61], v[180:183], v[196:199], 0
	v_mfma_f32_16x16x32_bf16 v[50:53], v[188:191], v[196:199], 0
	v_mfma_f32_16x16x32_bf16 v[42:45], v[180:183], v[204:207], 0
	v_mfma_f32_16x16x32_bf16 v[34:37], v[188:191], v[204:207], 0
	v_mfma_f32_16x16x32_bf16 v[26:29], v[180:183], v[212:215], 0
	v_mfma_f32_16x16x32_bf16 v[18:21], v[188:191], v[212:215], 0
	v_mfma_f32_16x16x32_bf16 v[10:13], v[180:183], v[220:223], 0
	v_mfma_f32_16x16x32_bf16 v[2:5], v[188:191], v[220:223], 0
	v_mfma_f32_16x16x32_bf16 v[58:61], v[184:187], v[200:203], v[58:61]
	v_mfma_f32_16x16x32_bf16 v[50:53], v[192:195], v[200:203], v[50:53]
	v_mfma_f32_16x16x32_bf16 v[42:45], v[184:187], v[208:211], v[42:45]
	v_mfma_f32_16x16x32_bf16 v[34:37], v[192:195], v[208:211], v[34:37]
	v_mfma_f32_16x16x32_bf16 v[26:29], v[184:187], v[216:219], v[26:29]
	v_mfma_f32_16x16x32_bf16 v[18:21], v[192:195], v[216:219], v[18:21]
	v_mfma_f32_16x16x32_bf16 v[10:13], v[184:187], v[224:227], v[10:13]
	v_mfma_f32_16x16x32_bf16 v[2:5], v[192:195], v[224:227], v[2:5]
	s_barrier
	s_setprio 0
	s_add_u32 s98, s94, 0xb0000
	s_addc_u32 s99, s95, 0
	s_add_i32 s6, 0, 0x18000
	s_add_i32 s29, 0, 0x1c000
	s_mov_b32 m0, s48
	s_nop 0
	global_load_lds_dwordx4 v130, s[98:99]
	s_mov_b32 m0, s49
	s_nop 0
	global_load_lds_dwordx4 v134, s[98:99]
	ds_read_b128 v[164:167], v232
	ds_read_b128 v[168:171], v232 offset:1024
	ds_read_b128 v[172:175], v232 offset:2048
	ds_read_b128 v[176:179], v232 offset:3072
	ds_read_b128 v[180:183], v233
	ds_read_b128 v[184:187], v233 offset:1024
	ds_read_b128 v[188:191], v233 offset:2048
	ds_read_b128 v[192:195], v233 offset:3072
	ds_read_b128 v[196:199], v160 offset:32768
	ds_read_b128 v[200:203], v160 offset:33792
	ds_read_b128 v[204:207], v160 offset:34816
	ds_read_b128 v[208:211], v160 offset:35840
	ds_read_b128 v[212:215], v160 offset:36864
	ds_read_b128 v[216:219], v160 offset:37888
	ds_read_b128 v[220:223], v160 offset:38912
	ds_read_b128 v[224:227], v160 offset:39936
	s_waitcnt vmcnt(8)
	s_waitcnt lgkmcnt(0)
	s_setprio 1
	s_barrier
	v_mfma_f32_16x16x32_bf16 v[122:125], v[164:167], v[196:199], v[122:125]
	v_mfma_f32_16x16x32_bf16 v[118:121], v[172:175], v[196:199], v[118:121]
	v_mfma_f32_16x16x32_bf16 v[110:113], v[164:167], v[204:207], v[110:113]
	v_mfma_f32_16x16x32_bf16 v[102:105], v[172:175], v[204:207], v[102:105]
	v_mfma_f32_16x16x32_bf16 v[94:97], v[164:167], v[212:215], v[94:97]
	v_mfma_f32_16x16x32_bf16 v[86:89], v[172:175], v[212:215], v[86:89]
	v_mfma_f32_16x16x32_bf16 v[78:81], v[164:167], v[220:223], v[78:81]
	v_mfma_f32_16x16x32_bf16 v[70:73], v[172:175], v[220:223], v[70:73]
	v_mfma_f32_16x16x32_bf16 v[122:125], v[168:171], v[200:203], v[122:125]
	v_mfma_f32_16x16x32_bf16 v[118:121], v[176:179], v[200:203], v[118:121]
	v_mfma_f32_16x16x32_bf16 v[110:113], v[168:171], v[208:211], v[110:113]
	v_mfma_f32_16x16x32_bf16 v[102:105], v[176:179], v[208:211], v[102:105]
	v_mfma_f32_16x16x32_bf16 v[94:97], v[168:171], v[216:219], v[94:97]
	v_mfma_f32_16x16x32_bf16 v[86:89], v[176:179], v[216:219], v[86:89]
	v_mfma_f32_16x16x32_bf16 v[78:81], v[168:171], v[224:227], v[78:81]
	v_mfma_f32_16x16x32_bf16 v[70:73], v[176:179], v[224:227], v[70:73]
	s_setprio 0
	s_setprio 1
	v_mfma_f32_16x16x32_bf16 v[126:129], v[180:183], v[196:199], v[126:129]
	v_mfma_f32_16x16x32_bf16 v[114:117], v[188:191], v[196:199], v[114:117]
	v_mfma_f32_16x16x32_bf16 v[106:109], v[180:183], v[204:207], v[106:109]
	v_mfma_f32_16x16x32_bf16 v[98:101], v[188:191], v[204:207], v[98:101]
	v_mfma_f32_16x16x32_bf16 v[90:93], v[180:183], v[212:215], v[90:93]
	v_mfma_f32_16x16x32_bf16 v[82:85], v[188:191], v[212:215], v[82:85]
	v_mfma_f32_16x16x32_bf16 v[74:77], v[180:183], v[220:223], v[74:77]
	v_mfma_f32_16x16x32_bf16 v[66:69], v[188:191], v[220:223], v[66:69]
	v_mfma_f32_16x16x32_bf16 v[126:129], v[184:187], v[200:203], v[126:129]
	v_mfma_f32_16x16x32_bf16 v[114:117], v[192:195], v[200:203], v[114:117]
	v_mfma_f32_16x16x32_bf16 v[106:109], v[184:187], v[208:211], v[106:109]
	v_mfma_f32_16x16x32_bf16 v[98:101], v[192:195], v[208:211], v[98:101]
	v_mfma_f32_16x16x32_bf16 v[90:93], v[184:187], v[216:219], v[90:93]
	v_mfma_f32_16x16x32_bf16 v[82:85], v[192:195], v[216:219], v[82:85]
	v_mfma_f32_16x16x32_bf16 v[74:77], v[184:187], v[224:227], v[74:77]
	v_mfma_f32_16x16x32_bf16 v[66:69], v[192:195], v[224:227], v[66:69]
	s_barrier
	s_setprio 0
	s_add_u32 s96, s96, 0x80
	s_addc_u32 s97, s97, 0
	s_add_u32 s98, s96, 0xb0000
	s_addc_u32 s99, s97, 0
	s_add_u32 s94, s94, 0x80
	s_addc_u32 s95, s95, 0
	s_add_i32 s6, s6, s23
	s_mov_b32 m0, s6
	s_nop 0
	global_load_lds_dwordx4 v132, s[96:97]
	s_add_i32 m0, s6, 0x2000
	s_add_i32 s6, s29, s23
	global_load_lds_dwordx4 v136, s[96:97]
	s_mov_b32 m0, s6
	s_nop 0
	global_load_lds_dwordx4 v132, s[98:99]
	s_add_i32 m0, s6, 0x2000
	s_nop 0
	global_load_lds_dwordx4 v136, s[98:99]
	s_mov_b32 m0, s59
	s_nop 0
	global_load_lds_dwordx4 v130, s[94:95]
	s_mov_b32 m0, s60
	s_nop 0
	global_load_lds_dwordx4 v134, s[94:95]
	ds_read_b128 v[196:199], v160 offset:49152
	ds_read_b128 v[200:203], v160 offset:50176
	ds_read_b128 v[204:207], v160 offset:51200
	ds_read_b128 v[208:211], v160 offset:52224
	ds_read_b128 v[212:215], v160 offset:53248
	ds_read_b128 v[216:219], v160 offset:54272
	ds_read_b128 v[220:223], v160 offset:55296
	ds_read_b128 v[224:227], v160 offset:56320
	s_waitcnt vmcnt(8)
	s_waitcnt lgkmcnt(0)
	s_setprio 1
	s_barrier
	v_mfma_f32_16x16x32_bf16 v[62:65], v[164:167], v[196:199], v[62:65]
	v_mfma_f32_16x16x32_bf16 v[54:57], v[172:175], v[196:199], v[54:57]
	v_mfma_f32_16x16x32_bf16 v[46:49], v[164:167], v[204:207], v[46:49]
	v_mfma_f32_16x16x32_bf16 v[38:41], v[172:175], v[204:207], v[38:41]
	v_mfma_f32_16x16x32_bf16 v[30:33], v[164:167], v[212:215], v[30:33]
	v_mfma_f32_16x16x32_bf16 v[22:25], v[172:175], v[212:215], v[22:25]
	v_mfma_f32_16x16x32_bf16 v[14:17], v[164:167], v[220:223], v[14:17]
	v_mfma_f32_16x16x32_bf16 v[6:9], v[172:175], v[220:223], v[6:9]
	v_mfma_f32_16x16x32_bf16 v[62:65], v[168:171], v[200:203], v[62:65]
	v_mfma_f32_16x16x32_bf16 v[54:57], v[176:179], v[200:203], v[54:57]
	v_mfma_f32_16x16x32_bf16 v[46:49], v[168:171], v[208:211], v[46:49]
	v_mfma_f32_16x16x32_bf16 v[38:41], v[176:179], v[208:211], v[38:41]
	v_mfma_f32_16x16x32_bf16 v[30:33], v[168:171], v[216:219], v[30:33]
	v_mfma_f32_16x16x32_bf16 v[22:25], v[176:179], v[216:219], v[22:25]
	v_mfma_f32_16x16x32_bf16 v[14:17], v[168:171], v[224:227], v[14:17]
	v_mfma_f32_16x16x32_bf16 v[6:9], v[176:179], v[224:227], v[6:9]
	s_setprio 0
	s_setprio 1
	v_mfma_f32_16x16x32_bf16 v[58:61], v[180:183], v[196:199], v[58:61]
	v_mfma_f32_16x16x32_bf16 v[50:53], v[188:191], v[196:199], v[50:53]
	v_mfma_f32_16x16x32_bf16 v[42:45], v[180:183], v[204:207], v[42:45]
	v_mfma_f32_16x16x32_bf16 v[34:37], v[188:191], v[204:207], v[34:37]
	v_mfma_f32_16x16x32_bf16 v[26:29], v[180:183], v[212:215], v[26:29]
	v_mfma_f32_16x16x32_bf16 v[18:21], v[188:191], v[212:215], v[18:21]
	v_mfma_f32_16x16x32_bf16 v[10:13], v[180:183], v[220:223], v[10:13]
	v_mfma_f32_16x16x32_bf16 v[2:5], v[188:191], v[220:223], v[2:5]
	v_mfma_f32_16x16x32_bf16 v[58:61], v[184:187], v[200:203], v[58:61]
	v_mfma_f32_16x16x32_bf16 v[50:53], v[192:195], v[200:203], v[50:53]
	v_mfma_f32_16x16x32_bf16 v[42:45], v[184:187], v[208:211], v[42:45]
	v_mfma_f32_16x16x32_bf16 v[34:37], v[192:195], v[208:211], v[34:37]
	v_mfma_f32_16x16x32_bf16 v[26:29], v[184:187], v[216:219], v[26:29]
	v_mfma_f32_16x16x32_bf16 v[18:21], v[192:195], v[216:219], v[18:21]
	v_mfma_f32_16x16x32_bf16 v[10:13], v[184:187], v[224:227], v[10:13]
	v_mfma_f32_16x16x32_bf16 v[2:5], v[192:195], v[224:227], v[2:5]
	s_barrier
	s_setprio 0
	s_mov_b32 s6, s7
	s_add_u32 s88, s88, 0x100
	s_addc_u32 s89, s89, 0
	s_add_u32 s86, s86, 0x100
	s_addc_u32 s87, s87, 0
	s_cmp_ge_i32 s7, s101
	s_cbranch_scc1 .Lmy_kexit_5

.Lmy_nb_7:
	s_nop 0
	v_readfirstlane_b32 s86, v150
	v_readfirstlane_b32 s87, v151
	v_readfirstlane_b32 s88, v152
	v_readfirstlane_b32 s89, v153
	v_readfirstlane_b32 s90, v146
	v_readfirstlane_b32 s91, v147
	v_readfirstlane_b32 s92, v148
	v_readfirstlane_b32 s93, v149
	v_readfirstlane_b32 s100, v138
	v_readfirstlane_b32 s101, v156
	v_add_u32_e32 v230, s67, v141
	v_add_u32_e32 v231, s70, v141
	v_add_u32_e32 v232, 0x18000, v141
	v_add_u32_e32 v233, 0x1c000, v141
	s_add_u32 s98, s86, 0x100
	s_addc_u32 s99, s87, 0
	s_cmp_eq_u32 s6, s100
	s_cselect_b64 s[94:95], s[90:91], s[98:99]
	s_cselect_b64 s[96:97], s[92:93], s[88:89]
	s_add_i32 s7, s6, 2
	s_nop 0
	s_add_i32 m0, s46, 0xc000
	s_nop 0
	global_load_lds_dwordx4 v144, s[86:87]
	s_add_i32 m0, s46, 0xe000
	s_nop 0
	global_load_lds_dwordx4 v142, s[86:87]
	ds_read_b128 v[164:167], v230
	ds_read_b128 v[168:171], v230 offset:1024
	ds_read_b128 v[172:175], v230 offset:2048
	ds_read_b128 v[176:179], v230 offset:3072
	ds_read_b128 v[180:183], v231
	ds_read_b128 v[184:187], v231 offset:1024
	ds_read_b128 v[188:191], v231 offset:2048
	ds_read_b128 v[192:195], v231 offset:3072
	ds_read_b128 v[196:199], v160
	ds_read_b128 v[200:203], v160 offset:1024
	ds_read_b128 v[204:207], v160 offset:2048
	ds_read_b128 v[208:211], v160 offset:3072
	ds_read_b128 v[212:215], v160 offset:4096
	ds_read_b128 v[216:219], v160 offset:5120
	ds_read_b128 v[220:223], v160 offset:6144
	ds_read_b128 v[224:227], v160 offset:7168
	s_waitcnt vmcnt(8)
	s_waitcnt lgkmcnt(0)
	s_setprio 1
	s_barrier
	v_mfma_f32_16x16x32_bf16 v[122:125], v[164:167], v[196:199], 0
	v_mfma_f32_16x16x32_bf16 v[118:121], v[172:175], v[196:199], 0
	v_mfma_f32_16x16x32_bf16 v[110:113], v[164:167], v[204:207], 0
	v_mfma_f32_16x16x32_bf16 v[102:105], v[172:175], v[204:207], 0
	v_mfma_f32_16x16x32_bf16 v[94:97], v[164:167], v[212:215], 0
	v_mfma_f32_16x16x32_bf16 v[86:89], v[172:175], v[212:215], 0
	v_mfma_f32_16x16x32_bf16 v[78:81], v[164:167], v[220:223], 0
	v_mfma_f32_16x16x32_bf16 v[70:73], v[172:175], v[220:223], 0
	v_mfma_f32_16x16x32_bf16 v[122:125], v[168:171], v[200:203], v[122:125]
	v_mfma_f32_16x16x32_bf16 v[118:121], v[176:179], v[200:203], v[118:121]
	v_mfma_f32_16x16x32_bf16 v[110:113], v[168:171], v[208:211], v[110:113]
	v_mfma_f32_16x16x32_bf16 v[102:105], v[176:179], v[208:211], v[102:105]
	v_mfma_f32_16x16x32_bf16 v[94:97], v[168:171], v[216:219], v[94:97]
	v_mfma_f32_16x16x32_bf16 v[86:89], v[176:179], v[216:219], v[86:89]
	v_mfma_f32_16x16x32_bf16 v[78:81], v[168:171], v[224:227], v[78:81]
	v_mfma_f32_16x16x32_bf16 v[70:73], v[176:179], v[224:227], v[70:73]
	s_setprio 0
	s_setprio 1
	v_mfma_f32_16x16x32_bf16 v[126:129], v[180:183], v[196:199], 0
	v_mfma_f32_16x16x32_bf16 v[114:117], v[188:191], v[196:199], 0
	v_mfma_f32_16x16x32_bf16 v[106:109], v[180:183], v[204:207], 0
	v_mfma_f32_16x16x32_bf16 v[98:101], v[188:191], v[204:207], 0
	v_mfma_f32_16x16x32_bf16 v[90:93], v[180:183], v[212:215], 0
	v_mfma_f32_16x16x32_bf16 v[82:85], v[188:191], v[212:215], 0
	v_mfma_f32_16x16x32_bf16 v[74:77], v[180:183], v[220:223], 0
	v_mfma_f32_16x16x32_bf16 v[66:69], v[188:191], v[220:223], 0
	v_mfma_f32_16x16x32_bf16 v[126:129], v[184:187], v[200:203], v[126:129]
	v_mfma_f32_16x16x32_bf16 v[114:117], v[192:195], v[200:203], v[114:117]
	v_mfma_f32_16x16x32_bf16 v[106:109], v[184:187], v[208:211], v[106:109]
	v_mfma_f32_16x16x32_bf16 v[98:101], v[192:195], v[208:211], v[98:101]
	v_mfma_f32_16x16x32_bf16 v[90:93], v[184:187], v[216:219], v[90:93]
	v_mfma_f32_16x16x32_bf16 v[82:85], v[192:195], v[216:219], v[82:85]
	v_mfma_f32_16x16x32_bf16 v[74:77], v[184:187], v[224:227], v[74:77]
	v_mfma_f32_16x16x32_bf16 v[66:69], v[192:195], v[224:227], v[66:69]
	s_barrier
	s_setprio 0
	s_add_u32 s98, s96, 0xb0000
	s_addc_u32 s99, s97, 0
	s_add_i32 s6, s67, s23
	s_mov_b32 m0, s6
	s_nop 0
	global_load_lds_dwordx4 v132, s[96:97]
	s_add_i32 m0, s6, 0x2000
	s_add_i32 s6, s70, s23
	global_load_lds_dwordx4 v136, s[96:97]
	s_mov_b32 m0, s6
	s_nop 0
	global_load_lds_dwordx4 v132, s[98:99]
	s_add_i32 m0, s6, 0x2000
	s_nop 0
	global_load_lds_dwordx4 v136, s[98:99]
	s_mov_b32 m0, s46
	s_nop 0
	global_load_lds_dwordx4 v130, s[94:95]
	s_mov_b32 m0, s47
	s_nop 0
	global_load_lds_dwordx4 v134, s[94:95]
	ds_read_b128 v[196:199], v160 offset:16384
	ds_read_b128 v[200:203], v160 offset:17408
	ds_read_b128 v[204:207], v160 offset:18432
	ds_read_b128 v[208:211], v160 offset:19456
	ds_read_b128 v[212:215], v160 offset:20480
	ds_read_b128 v[216:219], v160 offset:21504
	ds_read_b128 v[220:223], v160 offset:22528
	ds_read_b128 v[224:227], v160 offset:23552
	s_waitcnt vmcnt(8)
	s_waitcnt lgkmcnt(0)
	s_setprio 1
	s_barrier
	v_mfma_f32_16x16x32_bf16 v[62:65], v[164:167], v[196:199], 0
	v_mfma_f32_16x16x32_bf16 v[54:57], v[172:175], v[196:199], 0
	v_mfma_f32_16x16x32_bf16 v[46:49], v[164:167], v[204:207], 0
	v_mfma_f32_16x16x32_bf16 v[38:41], v[172:175], v[204:207], 0
	v_mfma_f32_16x16x32_bf16 v[30:33], v[164:167], v[212:215], 0
	v_mfma_f32_16x16x32_bf16 v[22:25], v[172:175], v[212:215], 0
	v_mfma_f32_16x16x32_bf16 v[14:17], v[164:167], v[220:223], 0
	v_mfma_f32_16x16x32_bf16 v[6:9], v[172:175], v[220:223], 0
	v_mfma_f32_16x16x32_bf16 v[62:65], v[168:171], v[200:203], v[62:65]
	v_mfma_f32_16x16x32_bf16 v[54:57], v[176:179], v[200:203], v[54:57]
	v_mfma_f32_16x16x32_bf16 v[46:49], v[168:171], v[208:211], v[46:49]
	v_mfma_f32_16x16x32_bf16 v[38:41], v[176:179], v[208:211], v[38:41]
	v_mfma_f32_16x16x32_bf16 v[30:33], v[168:171], v[216:219], v[30:33]
	v_mfma_f32_16x16x32_bf16 v[22:25], v[176:179], v[216:219], v[22:25]
	v_mfma_f32_16x16x32_bf16 v[14:17], v[168:171], v[224:227], v[14:17]
	v_mfma_f32_16x16x32_bf16 v[6:9], v[176:179], v[224:227], v[6:9]
	s_setprio 0
	s_setprio 1
	v_mfma_f32_16x16x32_bf16 v[58:61], v[180:183], v[196:199], 0
	v_mfma_f32_16x16x32_bf16 v[50:53], v[188:191], v[196:199], 0
	v_mfma_f32_16x16x32_bf16 v[42:45], v[180:183], v[204:207], 0
	v_mfma_f32_16x16x32_bf16 v[34:37], v[188:191], v[204:207], 0
	v_mfma_f32_16x16x32_bf16 v[26:29], v[180:183], v[212:215], 0
	v_mfma_f32_16x16x32_bf16 v[18:21], v[188:191], v[212:215], 0
	v_mfma_f32_16x16x32_bf16 v[10:13], v[180:183], v[220:223], 0
	v_mfma_f32_16x16x32_bf16 v[2:5], v[188:191], v[220:223], 0
	v_mfma_f32_16x16x32_bf16 v[58:61], v[184:187], v[200:203], v[58:61]
	v_mfma_f32_16x16x32_bf16 v[50:53], v[192:195], v[200:203], v[50:53]
	v_mfma_f32_16x16x32_bf16 v[42:45], v[184:187], v[208:211], v[42:45]
	v_mfma_f32_16x16x32_bf16 v[34:37], v[192:195], v[208:211], v[34:37]
	v_mfma_f32_16x16x32_bf16 v[26:29], v[184:187], v[216:219], v[26:29]
	v_mfma_f32_16x16x32_bf16 v[18:21], v[192:195], v[216:219], v[18:21]
	v_mfma_f32_16x16x32_bf16 v[10:13], v[184:187], v[224:227], v[10:13]
	v_mfma_f32_16x16x32_bf16 v[2:5], v[192:195], v[224:227], v[2:5]
	s_barrier
	s_setprio 0
	s_add_u32 s98, s94, 0xb0000
	s_addc_u32 s99, s95, 0
	s_add_i32 s6, 0, 0x18000
	s_add_i32 s29, 0, 0x1c000
	s_mov_b32 m0, s48
	s_nop 0
	global_load_lds_dwordx4 v130, s[98:99]
	s_mov_b32 m0, s49
	s_nop 0
	global_load_lds_dwordx4 v134, s[98:99]
	ds_read_b128 v[164:167], v232
	ds_read_b128 v[168:171], v232 offset:1024
	ds_read_b128 v[172:175], v232 offset:2048
	ds_read_b128 v[176:179], v232 offset:3072
	ds_read_b128 v[180:183], v233
	ds_read_b128 v[184:187], v233 offset:1024
	ds_read_b128 v[188:191], v233 offset:2048
	ds_read_b128 v[192:195], v233 offset:3072
	ds_read_b128 v[196:199], v160 offset:32768
	ds_read_b128 v[200:203], v160 offset:33792
	ds_read_b128 v[204:207], v160 offset:34816
	ds_read_b128 v[208:211], v160 offset:35840
	ds_read_b128 v[212:215], v160 offset:36864
	ds_read_b128 v[216:219], v160 offset:37888
	ds_read_b128 v[220:223], v160 offset:38912
	ds_read_b128 v[224:227], v160 offset:39936
	s_waitcnt vmcnt(8)
	s_waitcnt lgkmcnt(0)
	s_setprio 1
	s_barrier
	v_mfma_f32_16x16x32_bf16 v[122:125], v[164:167], v[196:199], v[122:125]
	v_mfma_f32_16x16x32_bf16 v[118:121], v[172:175], v[196:199], v[118:121]
	v_mfma_f32_16x16x32_bf16 v[110:113], v[164:167], v[204:207], v[110:113]
	v_mfma_f32_16x16x32_bf16 v[102:105], v[172:175], v[204:207], v[102:105]
	v_mfma_f32_16x16x32_bf16 v[94:97], v[164:167], v[212:215], v[94:97]
	v_mfma_f32_16x16x32_bf16 v[86:89], v[172:175], v[212:215], v[86:89]
	v_mfma_f32_16x16x32_bf16 v[78:81], v[164:167], v[220:223], v[78:81]
	v_mfma_f32_16x16x32_bf16 v[70:73], v[172:175], v[220:223], v[70:73]
	v_mfma_f32_16x16x32_bf16 v[122:125], v[168:171], v[200:203], v[122:125]
	v_mfma_f32_16x16x32_bf16 v[118:121], v[176:179], v[200:203], v[118:121]
	v_mfma_f32_16x16x32_bf16 v[110:113], v[168:171], v[208:211], v[110:113]
	v_mfma_f32_16x16x32_bf16 v[102:105], v[176:179], v[208:211], v[102:105]
	v_mfma_f32_16x16x32_bf16 v[94:97], v[168:171], v[216:219], v[94:97]
	v_mfma_f32_16x16x32_bf16 v[86:89], v[176:179], v[216:219], v[86:89]
	v_mfma_f32_16x16x32_bf16 v[78:81], v[168:171], v[224:227], v[78:81]
	v_mfma_f32_16x16x32_bf16 v[70:73], v[176:179], v[224:227], v[70:73]
	s_setprio 0
	s_setprio 1
	v_mfma_f32_16x16x32_bf16 v[126:129], v[180:183], v[196:199], v[126:129]
	v_mfma_f32_16x16x32_bf16 v[114:117], v[188:191], v[196:199], v[114:117]
	v_mfma_f32_16x16x32_bf16 v[106:109], v[180:183], v[204:207], v[106:109]
	v_mfma_f32_16x16x32_bf16 v[98:101], v[188:191], v[204:207], v[98:101]
	v_mfma_f32_16x16x32_bf16 v[90:93], v[180:183], v[212:215], v[90:93]
	v_mfma_f32_16x16x32_bf16 v[82:85], v[188:191], v[212:215], v[82:85]
	v_mfma_f32_16x16x32_bf16 v[74:77], v[180:183], v[220:223], v[74:77]
	v_mfma_f32_16x16x32_bf16 v[66:69], v[188:191], v[220:223], v[66:69]
	v_mfma_f32_16x16x32_bf16 v[126:129], v[184:187], v[200:203], v[126:129]
	v_mfma_f32_16x16x32_bf16 v[114:117], v[192:195], v[200:203], v[114:117]
	v_mfma_f32_16x16x32_bf16 v[106:109], v[184:187], v[208:211], v[106:109]
	v_mfma_f32_16x16x32_bf16 v[98:101], v[192:195], v[208:211], v[98:101]
	v_mfma_f32_16x16x32_bf16 v[90:93], v[184:187], v[216:219], v[90:93]
	v_mfma_f32_16x16x32_bf16 v[82:85], v[192:195], v[216:219], v[82:85]
	v_mfma_f32_16x16x32_bf16 v[74:77], v[184:187], v[224:227], v[74:77]
	v_mfma_f32_16x16x32_bf16 v[66:69], v[192:195], v[224:227], v[66:69]
	s_barrier
	s_setprio 0
	s_add_u32 s96, s96, 0x80
	s_addc_u32 s97, s97, 0
	s_add_u32 s98, s96, 0xb0000
	s_addc_u32 s99, s97, 0
	s_add_u32 s94, s94, 0x80
	s_addc_u32 s95, s95, 0
	s_add_i32 s6, s6, s23
	s_mov_b32 m0, s6
	s_nop 0
	global_load_lds_dwordx4 v132, s[96:97]
	s_add_i32 m0, s6, 0x2000
	s_add_i32 s6, s29, s23
	global_load_lds_dwordx4 v136, s[96:97]
	s_mov_b32 m0, s6
	s_nop 0
	global_load_lds_dwordx4 v132, s[98:99]
	s_add_i32 m0, s6, 0x2000
	s_nop 0
	global_load_lds_dwordx4 v136, s[98:99]
	s_mov_b32 m0, s59
	s_nop 0
	global_load_lds_dwordx4 v130, s[94:95]
	s_mov_b32 m0, s60
	s_nop 0
	global_load_lds_dwordx4 v134, s[94:95]
	ds_read_b128 v[196:199], v160 offset:49152
	ds_read_b128 v[200:203], v160 offset:50176
	ds_read_b128 v[204:207], v160 offset:51200
	ds_read_b128 v[208:211], v160 offset:52224
	ds_read_b128 v[212:215], v160 offset:53248
	ds_read_b128 v[216:219], v160 offset:54272
	ds_read_b128 v[220:223], v160 offset:55296
	ds_read_b128 v[224:227], v160 offset:56320
	s_waitcnt vmcnt(8)
	s_waitcnt lgkmcnt(0)
	s_setprio 1
	s_barrier
	v_mfma_f32_16x16x32_bf16 v[62:65], v[164:167], v[196:199], v[62:65]
	v_mfma_f32_16x16x32_bf16 v[54:57], v[172:175], v[196:199], v[54:57]
	v_mfma_f32_16x16x32_bf16 v[46:49], v[164:167], v[204:207], v[46:49]
	v_mfma_f32_16x16x32_bf16 v[38:41], v[172:175], v[204:207], v[38:41]
	v_mfma_f32_16x16x32_bf16 v[30:33], v[164:167], v[212:215], v[30:33]
	v_mfma_f32_16x16x32_bf16 v[22:25], v[172:175], v[212:215], v[22:25]
	v_mfma_f32_16x16x32_bf16 v[14:17], v[164:167], v[220:223], v[14:17]
	v_mfma_f32_16x16x32_bf16 v[6:9], v[172:175], v[220:223], v[6:9]
	v_mfma_f32_16x16x32_bf16 v[62:65], v[168:171], v[200:203], v[62:65]
	v_mfma_f32_16x16x32_bf16 v[54:57], v[176:179], v[200:203], v[54:57]
	v_mfma_f32_16x16x32_bf16 v[46:49], v[168:171], v[208:211], v[46:49]
	v_mfma_f32_16x16x32_bf16 v[38:41], v[176:179], v[208:211], v[38:41]
	v_mfma_f32_16x16x32_bf16 v[30:33], v[168:171], v[216:219], v[30:33]
	v_mfma_f32_16x16x32_bf16 v[22:25], v[176:179], v[216:219], v[22:25]
	v_mfma_f32_16x16x32_bf16 v[14:17], v[168:171], v[224:227], v[14:17]
	v_mfma_f32_16x16x32_bf16 v[6:9], v[176:179], v[224:227], v[6:9]
	s_setprio 0
	s_setprio 1
	v_mfma_f32_16x16x32_bf16 v[58:61], v[180:183], v[196:199], v[58:61]
	v_mfma_f32_16x16x32_bf16 v[50:53], v[188:191], v[196:199], v[50:53]
	v_mfma_f32_16x16x32_bf16 v[42:45], v[180:183], v[204:207], v[42:45]
	v_mfma_f32_16x16x32_bf16 v[34:37], v[188:191], v[204:207], v[34:37]
	v_mfma_f32_16x16x32_bf16 v[26:29], v[180:183], v[212:215], v[26:29]
	v_mfma_f32_16x16x32_bf16 v[18:21], v[188:191], v[212:215], v[18:21]
	v_mfma_f32_16x16x32_bf16 v[10:13], v[180:183], v[220:223], v[10:13]
	v_mfma_f32_16x16x32_bf16 v[2:5], v[188:191], v[220:223], v[2:5]
	v_mfma_f32_16x16x32_bf16 v[58:61], v[184:187], v[200:203], v[58:61]
	v_mfma_f32_16x16x32_bf16 v[50:53], v[192:195], v[200:203], v[50:53]
	v_mfma_f32_16x16x32_bf16 v[42:45], v[184:187], v[208:211], v[42:45]
	v_mfma_f32_16x16x32_bf16 v[34:37], v[192:195], v[208:211], v[34:37]
	v_mfma_f32_16x16x32_bf16 v[26:29], v[184:187], v[216:219], v[26:29]
	v_mfma_f32_16x16x32_bf16 v[18:21], v[192:195], v[216:219], v[18:21]
	v_mfma_f32_16x16x32_bf16 v[10:13], v[184:187], v[224:227], v[10:13]
	v_mfma_f32_16x16x32_bf16 v[2:5], v[192:195], v[224:227], v[2:5]
	s_barrier
	s_setprio 0
	s_mov_b32 s6, s7
	s_add_u32 s88, s88, 0x100
	s_addc_u32 s89, s89, 0
	s_add_u32 s86, s86, 0x100
	s_addc_u32 s87, s87, 0
	s_cmp_ge_i32 s7, s101
	s_cbranch_scc1 .Lmy_kexit_7

.LBB0_1571:
	v_cmp_gt_i32_e32 vcc, 1, v141
	s_cbranch_vccnz .LBB0_1633
	v_lshl_add_u64 v[154:155], v[2:3], 0, s[18:19]
	v_add_u32_e32 v138, -2, v141
	v_lshl_add_u64 v[152:153], v[4:5], 0, s[22:23]
	s_mov_b32 s7, 0
	s_cmp_eq_u32 s32, 1
	s_cbranch_scc0 .Lmy_nb_8
	s_mov_b32 s32, 0
	s_barrier
.Lmy_nb_8:
	s_nop 0
	v_readfirstlane_b32 s86, v154
	v_readfirstlane_b32 s87, v155
	v_readfirstlane_b32 s88, v152
	v_readfirstlane_b32 s89, v153
	v_readfirstlane_b32 s90, v148
	v_readfirstlane_b32 s91, v149
	v_readfirstlane_b32 s92, v150
	v_readfirstlane_b32 s93, v151
	v_readfirstlane_b32 s100, v138
	v_readfirstlane_b32 s101, v141
	v_add_u32_e32 v230, s71, v160
	v_add_u32_e32 v231, s72, v160
	v_add_u32_e32 v232, 0x18000, v160
	v_add_u32_e32 v233, 0x1c000, v160
	s_add_u32 s98, s86, 0xfffc0080
	s_addc_u32 s99, s87, -1
	s_cmp_eq_u32 s7, s100
	s_cselect_b64 s[94:95], s[90:91], s[98:99]
	s_cselect_b64 s[96:97], s[92:93], s[88:89]
	s_add_i32 s47, s7, 2
	s_nop 0
	s_mov_b32 m0, s74
	s_nop 0
	global_load_lds_dwordx4 v144, s[86:87]
	s_mov_b32 m0, s75
	s_nop 0
	global_load_lds_dwordx4 v142, s[86:87]
	ds_read_b128 v[156:159], v230
	ds_read_b128 v[166:169], v230 offset:1024
	ds_read_b128 v[170:173], v230 offset:2048
	ds_read_b128 v[174:177], v230 offset:3072
	ds_read_b128 v[178:181], v231
	ds_read_b128 v[182:185], v231 offset:1024
	ds_read_b128 v[186:189], v231 offset:2048
	ds_read_b128 v[190:193], v231 offset:3072
	ds_read_b128 v[194:197], v163
	ds_read_b128 v[198:201], v163 offset:1024
	ds_read_b128 v[202:205], v163 offset:2048
	ds_read_b128 v[206:209], v163 offset:3072
	ds_read_b128 v[210:213], v163 offset:4096
	ds_read_b128 v[214:217], v163 offset:5120
	ds_read_b128 v[218:221], v163 offset:6144
	ds_read_b128 v[222:225], v163 offset:7168
	s_waitcnt vmcnt(8)
	s_waitcnt lgkmcnt(0)
	s_setprio 1
	s_barrier
	v_mfma_f32_16x16x32_bf16 v[122:125], v[156:159], v[194:197], 0
	v_mfma_f32_16x16x32_bf16 v[118:121], v[170:173], v[194:197], 0
	v_mfma_f32_16x16x32_bf16 v[110:113], v[156:159], v[202:205], 0
	v_mfma_f32_16x16x32_bf16 v[102:105], v[170:173], v[202:205], 0
	v_mfma_f32_16x16x32_bf16 v[94:97], v[156:159], v[210:213], 0
	v_mfma_f32_16x16x32_bf16 v[86:89], v[170:173], v[210:213], 0
	v_mfma_f32_16x16x32_bf16 v[78:81], v[156:159], v[218:221], 0
	v_mfma_f32_16x16x32_bf16 v[70:73], v[170:173], v[218:221], 0
	v_mfma_f32_16x16x32_bf16 v[122:125], v[166:169], v[198:201], v[122:125]
	v_mfma_f32_16x16x32_bf16 v[118:121], v[174:177], v[198:201], v[118:121]
	v_mfma_f32_16x16x32_bf16 v[110:113], v[166:169], v[206:209], v[110:113]
	v_mfma_f32_16x16x32_bf16 v[102:105], v[174:177], v[206:209], v[102:105]
	v_mfma_f32_16x16x32_bf16 v[94:97], v[166:169], v[214:217], v[94:97]
	v_mfma_f32_16x16x32_bf16 v[86:89], v[174:177], v[214:217], v[86:89]
	v_mfma_f32_16x16x32_bf16 v[78:81], v[166:169], v[222:225], v[78:81]
	v_mfma_f32_16x16x32_bf16 v[70:73], v[174:177], v[222:225], v[70:73]
	s_setprio 0
	s_setprio 1
	v_mfma_f32_16x16x32_bf16 v[126:129], v[178:181], v[194:197], 0
	v_mfma_f32_16x16x32_bf16 v[114:117], v[186:189], v[194:197], 0
	v_mfma_f32_16x16x32_bf16 v[106:109], v[178:181], v[202:205], 0
	v_mfma_f32_16x16x32_bf16 v[98:101], v[186:189], v[202:205], 0
	v_mfma_f32_16x16x32_bf16 v[90:93], v[178:181], v[210:213], 0
	v_mfma_f32_16x16x32_bf16 v[82:85], v[186:189], v[210:213], 0
	v_mfma_f32_16x16x32_bf16 v[74:77], v[178:181], v[218:221], 0
	v_mfma_f32_16x16x32_bf16 v[66:69], v[186:189], v[218:221], 0
	v_mfma_f32_16x16x32_bf16 v[126:129], v[182:185], v[198:201], v[126:129]
	v_mfma_f32_16x16x32_bf16 v[114:117], v[190:193], v[198:201], v[114:117]
	v_mfma_f32_16x16x32_bf16 v[106:109], v[182:185], v[206:209], v[106:109]
	v_mfma_f32_16x16x32_bf16 v[98:101], v[190:193], v[206:209], v[98:101]
	v_mfma_f32_16x16x32_bf16 v[90:93], v[182:185], v[214:217], v[90:93]
	v_mfma_f32_16x16x32_bf16 v[82:85], v[190:193], v[214:217], v[82:85]
	v_mfma_f32_16x16x32_bf16 v[74:77], v[182:185], v[222:225], v[74:77]
	v_mfma_f32_16x16x32_bf16 v[66:69], v[190:193], v[222:225], v[66:69]
	s_barrier
	s_setprio 0
	s_add_u32 s98, s96, 0x40000
	s_addc_u32 s99, s97, 0
	s_add_i32 s7, s71, s29
	s_mov_b32 m0, s7
	s_nop 0
	global_load_lds_dwordx4 v132, s[96:97]
	s_add_i32 m0, s7, 0x2000
	s_add_i32 s7, s72, s29
	global_load_lds_dwordx4 v136, s[96:97]
	s_mov_b32 m0, s7
	s_nop 0
	global_load_lds_dwordx4 v132, s[98:99]
	s_add_i32 m0, s7, 0x2000
	s_nop 0
	global_load_lds_dwordx4 v136, s[98:99]
	s_mov_b32 m0, s51
	s_nop 0
	global_load_lds_dwordx4 v130, s[94:95]
	s_mov_b32 m0, s60
	s_nop 0
	global_load_lds_dwordx4 v134, s[94:95]
	ds_read_b128 v[194:197], v163 offset:16384
	ds_read_b128 v[198:201], v163 offset:17408
	ds_read_b128 v[202:205], v163 offset:18432
	ds_read_b128 v[206:209], v163 offset:19456
	ds_read_b128 v[210:213], v163 offset:20480
	ds_read_b128 v[214:217], v163 offset:21504
	ds_read_b128 v[218:221], v163 offset:22528
	ds_read_b128 v[222:225], v163 offset:23552
	s_waitcnt vmcnt(8)
	s_waitcnt lgkmcnt(0)
	s_setprio 1
	s_barrier
	v_mfma_f32_16x16x32_bf16 v[62:65], v[156:159], v[194:197], 0
	v_mfma_f32_16x16x32_bf16 v[54:57], v[170:173], v[194:197], 0
	v_mfma_f32_16x16x32_bf16 v[46:49], v[156:159], v[202:205], 0
	v_mfma_f32_16x16x32_bf16 v[38:41], v[170:173], v[202:205], 0
	v_mfma_f32_16x16x32_bf16 v[30:33], v[156:159], v[210:213], 0
	v_mfma_f32_16x16x32_bf16 v[22:25], v[170:173], v[210:213], 0
	v_mfma_f32_16x16x32_bf16 v[14:17], v[156:159], v[218:221], 0
	v_mfma_f32_16x16x32_bf16 v[6:9], v[170:173], v[218:221], 0
	v_mfma_f32_16x16x32_bf16 v[62:65], v[166:169], v[198:201], v[62:65]
	v_mfma_f32_16x16x32_bf16 v[54:57], v[174:177], v[198:201], v[54:57]
	v_mfma_f32_16x16x32_bf16 v[46:49], v[166:169], v[206:209], v[46:49]
	v_mfma_f32_16x16x32_bf16 v[38:41], v[174:177], v[206:209], v[38:41]
	v_mfma_f32_16x16x32_bf16 v[30:33], v[166:169], v[214:217], v[30:33]
	v_mfma_f32_16x16x32_bf16 v[22:25], v[174:177], v[214:217], v[22:25]
	v_mfma_f32_16x16x32_bf16 v[14:17], v[166:169], v[222:225], v[14:17]
	v_mfma_f32_16x16x32_bf16 v[6:9], v[174:177], v[222:225], v[6:9]
	s_setprio 0
	s_setprio 1
	v_mfma_f32_16x16x32_bf16 v[58:61], v[178:181], v[194:197], 0
	v_mfma_f32_16x16x32_bf16 v[50:53], v[186:189], v[194:197], 0
	v_mfma_f32_16x16x32_bf16 v[42:45], v[178:181], v[202:205], 0
	v_mfma_f32_16x16x32_bf16 v[34:37], v[186:189], v[202:205], 0
	v_mfma_f32_16x16x32_bf16 v[26:29], v[178:181], v[210:213], 0
	v_mfma_f32_16x16x32_bf16 v[18:21], v[186:189], v[210:213], 0
	v_mfma_f32_16x16x32_bf16 v[10:13], v[178:181], v[218:221], 0
	v_mfma_f32_16x16x32_bf16 v[2:5], v[186:189], v[218:221], 0
	v_mfma_f32_16x16x32_bf16 v[58:61], v[182:185], v[198:201], v[58:61]
	v_mfma_f32_16x16x32_bf16 v[50:53], v[190:193], v[198:201], v[50:53]
	v_mfma_f32_16x16x32_bf16 v[42:45], v[182:185], v[206:209], v[42:45]
	v_mfma_f32_16x16x32_bf16 v[34:37], v[190:193], v[206:209], v[34:37]
	v_mfma_f32_16x16x32_bf16 v[26:29], v[182:185], v[214:217], v[26:29]
	v_mfma_f32_16x16x32_bf16 v[18:21], v[190:193], v[214:217], v[18:21]
	v_mfma_f32_16x16x32_bf16 v[10:13], v[182:185], v[222:225], v[10:13]
	v_mfma_f32_16x16x32_bf16 v[2:5], v[190:193], v[222:225], v[2:5]
	s_barrier
	s_setprio 0
	s_add_u32 s98, s94, 0x40000
	s_addc_u32 s99, s95, 0
	s_add_i32 s7, 0, 0x18000
	s_add_i32 s49, 0, 0x1c000
	s_mov_b32 m0, s61
	s_nop 0
	global_load_lds_dwordx4 v130, s[98:99]
	s_mov_b32 m0, s62
	s_nop 0
	global_load_lds_dwordx4 v134, s[98:99]
	ds_read_b128 v[156:159], v232
	ds_read_b128 v[166:169], v232 offset:1024
	ds_read_b128 v[170:173], v232 offset:2048
	ds_read_b128 v[174:177], v232 offset:3072
	ds_read_b128 v[178:181], v233
	ds_read_b128 v[182:185], v233 offset:1024
	ds_read_b128 v[186:189], v233 offset:2048
	ds_read_b128 v[190:193], v233 offset:3072
	ds_read_b128 v[194:197], v163 offset:32768
	ds_read_b128 v[198:201], v163 offset:33792
	ds_read_b128 v[202:205], v163 offset:34816
	ds_read_b128 v[206:209], v163 offset:35840
	ds_read_b128 v[210:213], v163 offset:36864
	ds_read_b128 v[214:217], v163 offset:37888
	ds_read_b128 v[218:221], v163 offset:38912
	ds_read_b128 v[222:225], v163 offset:39936
	s_waitcnt vmcnt(8)
	s_waitcnt lgkmcnt(0)
	s_setprio 1
	s_barrier
	v_mfma_f32_16x16x32_bf16 v[122:125], v[156:159], v[194:197], v[122:125]
	v_mfma_f32_16x16x32_bf16 v[118:121], v[170:173], v[194:197], v[118:121]
	v_mfma_f32_16x16x32_bf16 v[110:113], v[156:159], v[202:205], v[110:113]
	v_mfma_f32_16x16x32_bf16 v[102:105], v[170:173], v[202:205], v[102:105]
	v_mfma_f32_16x16x32_bf16 v[94:97], v[156:159], v[210:213], v[94:97]
	v_mfma_f32_16x16x32_bf16 v[86:89], v[170:173], v[210:213], v[86:89]
	v_mfma_f32_16x16x32_bf16 v[78:81], v[156:159], v[218:221], v[78:81]
	v_mfma_f32_16x16x32_bf16 v[70:73], v[170:173], v[218:221], v[70:73]
	v_mfma_f32_16x16x32_bf16 v[122:125], v[166:169], v[198:201], v[122:125]
	v_mfma_f32_16x16x32_bf16 v[118:121], v[174:177], v[198:201], v[118:121]
	v_mfma_f32_16x16x32_bf16 v[110:113], v[166:169], v[206:209], v[110:113]
	v_mfma_f32_16x16x32_bf16 v[102:105], v[174:177], v[206:209], v[102:105]
	v_mfma_f32_16x16x32_bf16 v[94:97], v[166:169], v[214:217], v[94:97]
	v_mfma_f32_16x16x32_bf16 v[86:89], v[174:177], v[214:217], v[86:89]
	v_mfma_f32_16x16x32_bf16 v[78:81], v[166:169], v[222:225], v[78:81]
	v_mfma_f32_16x16x32_bf16 v[70:73], v[174:177], v[222:225], v[70:73]
	s_setprio 0
	s_setprio 1
	v_mfma_f32_16x16x32_bf16 v[126:129], v[178:181], v[194:197], v[126:129]
	v_mfma_f32_16x16x32_bf16 v[114:117], v[186:189], v[194:197], v[114:117]
	v_mfma_f32_16x16x32_bf16 v[106:109], v[178:181], v[202:205], v[106:109]
	v_mfma_f32_16x16x32_bf16 v[98:101], v[186:189], v[202:205], v[98:101]
	v_mfma_f32_16x16x32_bf16 v[90:93], v[178:181], v[210:213], v[90:93]
	v_mfma_f32_16x16x32_bf16 v[82:85], v[186:189], v[210:213], v[82:85]
	v_mfma_f32_16x16x32_bf16 v[74:77], v[178:181], v[218:221], v[74:77]
	v_mfma_f32_16x16x32_bf16 v[66:69], v[186:189], v[218:221], v[66:69]
	v_mfma_f32_16x16x32_bf16 v[126:129], v[182:185], v[198:201], v[126:129]
	v_mfma_f32_16x16x32_bf16 v[114:117], v[190:193], v[198:201], v[114:117]
	v_mfma_f32_16x16x32_bf16 v[106:109], v[182:185], v[206:209], v[106:109]
	v_mfma_f32_16x16x32_bf16 v[98:101], v[190:193], v[206:209], v[98:101]
	v_mfma_f32_16x16x32_bf16 v[90:93], v[182:185], v[214:217], v[90:93]
	v_mfma_f32_16x16x32_bf16 v[82:85], v[190:193], v[214:217], v[82:85]
	v_mfma_f32_16x16x32_bf16 v[74:77], v[182:185], v[222:225], v[74:77]
	v_mfma_f32_16x16x32_bf16 v[66:69], v[190:193], v[222:225], v[66:69]
	s_barrier
	s_setprio 0
	s_add_u32 s96, s96, 0x80
	s_addc_u32 s97, s97, 0
	s_add_u32 s98, s96, 0x40000
	s_addc_u32 s99, s97, 0
	s_add_u32 s94, s94, 0x80
	s_addc_u32 s95, s95, 0
	s_add_i32 s7, s7, s29
	s_mov_b32 m0, s7
	s_nop 0
	global_load_lds_dwordx4 v132, s[96:97]
	s_add_i32 m0, s7, 0x2000
	s_add_i32 s7, s49, s29
	global_load_lds_dwordx4 v136, s[96:97]
	s_mov_b32 m0, s7
	s_nop 0
	global_load_lds_dwordx4 v132, s[98:99]
	s_add_i32 m0, s7, 0x2000
	s_nop 0
	global_load_lds_dwordx4 v136, s[98:99]
	s_mov_b32 m0, s63
	s_nop 0
	global_load_lds_dwordx4 v130, s[94:95]
	s_mov_b32 m0, s64
	s_nop 0
	global_load_lds_dwordx4 v134, s[94:95]
	ds_read_b128 v[194:197], v163 offset:49152
	ds_read_b128 v[198:201], v163 offset:50176
	ds_read_b128 v[202:205], v163 offset:51200
	ds_read_b128 v[206:209], v163 offset:52224
	ds_read_b128 v[210:213], v163 offset:53248
	ds_read_b128 v[214:217], v163 offset:54272
	ds_read_b128 v[218:221], v163 offset:55296
	ds_read_b128 v[222:225], v163 offset:56320
	s_waitcnt vmcnt(8)
	s_waitcnt lgkmcnt(0)
	s_setprio 1
	s_barrier
	v_mfma_f32_16x16x32_bf16 v[62:65], v[156:159], v[194:197], v[62:65]
	v_mfma_f32_16x16x32_bf16 v[54:57], v[170:173], v[194:197], v[54:57]
	v_mfma_f32_16x16x32_bf16 v[46:49], v[156:159], v[202:205], v[46:49]
	v_mfma_f32_16x16x32_bf16 v[38:41], v[170:173], v[202:205], v[38:41]
	v_mfma_f32_16x16x32_bf16 v[30:33], v[156:159], v[210:213], v[30:33]
	v_mfma_f32_16x16x32_bf16 v[22:25], v[170:173], v[210:213], v[22:25]
	v_mfma_f32_16x16x32_bf16 v[14:17], v[156:159], v[218:221], v[14:17]
	v_mfma_f32_16x16x32_bf16 v[6:9], v[170:173], v[218:221], v[6:9]
	v_mfma_f32_16x16x32_bf16 v[62:65], v[166:169], v[198:201], v[62:65]
	v_mfma_f32_16x16x32_bf16 v[54:57], v[174:177], v[198:201], v[54:57]
	v_mfma_f32_16x16x32_bf16 v[46:49], v[166:169], v[206:209], v[46:49]
	v_mfma_f32_16x16x32_bf16 v[38:41], v[174:177], v[206:209], v[38:41]
	v_mfma_f32_16x16x32_bf16 v[30:33], v[166:169], v[214:217], v[30:33]
	v_mfma_f32_16x16x32_bf16 v[22:25], v[174:177], v[214:217], v[22:25]
	v_mfma_f32_16x16x32_bf16 v[14:17], v[166:169], v[222:225], v[14:17]
	v_mfma_f32_16x16x32_bf16 v[6:9], v[174:177], v[222:225], v[6:9]
	s_setprio 0
	s_setprio 1
	v_mfma_f32_16x16x32_bf16 v[58:61], v[178:181], v[194:197], v[58:61]
	v_mfma_f32_16x16x32_bf16 v[50:53], v[186:189], v[194:197], v[50:53]
	v_mfma_f32_16x16x32_bf16 v[42:45], v[178:181], v[202:205], v[42:45]
	v_mfma_f32_16x16x32_bf16 v[34:37], v[186:189], v[202:205], v[34:37]
	v_mfma_f32_16x16x32_bf16 v[26:29], v[178:181], v[210:213], v[26:29]
	v_mfma_f32_16x16x32_bf16 v[18:21], v[186:189], v[210:213], v[18:21]
	v_mfma_f32_16x16x32_bf16 v[10:13], v[178:181], v[218:221], v[10:13]
	v_mfma_f32_16x16x32_bf16 v[2:5], v[186:189], v[218:221], v[2:5]
	v_mfma_f32_16x16x32_bf16 v[58:61], v[182:185], v[198:201], v[58:61]
	v_mfma_f32_16x16x32_bf16 v[50:53], v[190:193], v[198:201], v[50:53]
	v_mfma_f32_16x16x32_bf16 v[42:45], v[182:185], v[206:209], v[42:45]
	v_mfma_f32_16x16x32_bf16 v[34:37], v[190:193], v[206:209], v[34:37]
	v_mfma_f32_16x16x32_bf16 v[26:29], v[182:185], v[214:217], v[26:29]
	v_mfma_f32_16x16x32_bf16 v[18:21], v[190:193], v[214:217], v[18:21]
	v_mfma_f32_16x16x32_bf16 v[10:13], v[182:185], v[222:225], v[10:13]
	v_mfma_f32_16x16x32_bf16 v[2:5], v[190:193], v[222:225], v[2:5]
	s_barrier
	s_setprio 0
	s_mov_b32 s7, s47
	s_add_u32 s88, s88, 0x100
	s_addc_u32 s89, s89, 0
	s_add_u32 s86, s86, 0x100
	s_addc_u32 s87, s87, 0
	s_cmp_ge_i32 s47, s101
	s_cbranch_scc1 .Lmy_kexit_8

.LBB0_1761:
	v_cmp_gt_i32_e32 vcc, 1, v138
	s_cbranch_vccnz .LBB0_1823
	v_lshl_add_u64 v[152:153], v[2:3], 0, s[14:15]
	v_add_u32_e32 v154, -2, v138
	s_waitcnt lgkmcnt(0)
	v_lshl_add_u64 v[150:151], v[4:5], 0, s[18:19]
	s_mov_b32 s5, 0
	s_cmp_eq_u32 s32, 1
	s_cbranch_scc0 .Lmy_nb_9
	s_mov_b32 s32, 0
	s_barrier
.Lmy_nb_9:
	s_nop 0
	v_readfirstlane_b32 s86, v152
	v_readfirstlane_b32 s87, v153
	v_readfirstlane_b32 s88, v150
	v_readfirstlane_b32 s89, v151
	v_readfirstlane_b32 s90, v146
	v_readfirstlane_b32 s91, v147
	v_readfirstlane_b32 s92, v148
	v_readfirstlane_b32 s93, v149
	v_readfirstlane_b32 s100, v154
	v_readfirstlane_b32 s101, v138
	v_add_u32_e32 v230, s74, v141
	v_add_u32_e32 v231, s75, v141
	v_add_u32_e32 v232, 0x18000, v141
	v_add_u32_e32 v233, 0x1c000, v141
	s_add_u32 s98, s86, 0xfffc0080
	s_addc_u32 s99, s87, -1
	s_cmp_eq_u32 s5, s100
	s_cselect_b64 s[94:95], s[90:91], s[98:99]
	s_cselect_b64 s[96:97], s[92:93], s[88:89]
	s_add_i32 s29, s5, 2
	s_nop 0
	s_add_i32 m0, s47, 0xc000
	s_nop 0
	global_load_lds_dwordx4 v144, s[86:87]
	s_add_i32 m0, s47, 0xe000
	s_nop 0
	global_load_lds_dwordx4 v142, s[86:87]
	ds_read_b128 v[164:167], v230
	ds_read_b128 v[168:171], v230 offset:1024
	ds_read_b128 v[172:175], v230 offset:2048
	ds_read_b128 v[176:179], v230 offset:3072
	ds_read_b128 v[180:183], v231
	ds_read_b128 v[184:187], v231 offset:1024
	ds_read_b128 v[188:191], v231 offset:2048
	ds_read_b128 v[192:195], v231 offset:3072
	ds_read_b128 v[196:199], v160
	ds_read_b128 v[200:203], v160 offset:1024
	ds_read_b128 v[204:207], v160 offset:2048
	ds_read_b128 v[208:211], v160 offset:3072
	ds_read_b128 v[212:215], v160 offset:4096
	ds_read_b128 v[216:219], v160 offset:5120
	ds_read_b128 v[220:223], v160 offset:6144
	ds_read_b128 v[224:227], v160 offset:7168
	s_waitcnt vmcnt(8)
	s_waitcnt lgkmcnt(0)
	s_setprio 1
	s_barrier
	v_mfma_f32_16x16x32_bf16 v[122:125], v[164:167], v[196:199], 0
	v_mfma_f32_16x16x32_bf16 v[118:121], v[172:175], v[196:199], 0
	v_mfma_f32_16x16x32_bf16 v[110:113], v[164:167], v[204:207], 0
	v_mfma_f32_16x16x32_bf16 v[102:105], v[172:175], v[204:207], 0
	v_mfma_f32_16x16x32_bf16 v[94:97], v[164:167], v[212:215], 0
	v_mfma_f32_16x16x32_bf16 v[86:89], v[172:175], v[212:215], 0
	v_mfma_f32_16x16x32_bf16 v[78:81], v[164:167], v[220:223], 0
	v_mfma_f32_16x16x32_bf16 v[70:73], v[172:175], v[220:223], 0
	v_mfma_f32_16x16x32_bf16 v[122:125], v[168:171], v[200:203], v[122:125]
	v_mfma_f32_16x16x32_bf16 v[118:121], v[176:179], v[200:203], v[118:121]
	v_mfma_f32_16x16x32_bf16 v[110:113], v[168:171], v[208:211], v[110:113]
	v_mfma_f32_16x16x32_bf16 v[102:105], v[176:179], v[208:211], v[102:105]
	v_mfma_f32_16x16x32_bf16 v[94:97], v[168:171], v[216:219], v[94:97]
	v_mfma_f32_16x16x32_bf16 v[86:89], v[176:179], v[216:219], v[86:89]
	v_mfma_f32_16x16x32_bf16 v[78:81], v[168:171], v[224:227], v[78:81]
	v_mfma_f32_16x16x32_bf16 v[70:73], v[176:179], v[224:227], v[70:73]
	s_setprio 0
	s_setprio 1
	v_mfma_f32_16x16x32_bf16 v[126:129], v[180:183], v[196:199], 0
	v_mfma_f32_16x16x32_bf16 v[114:117], v[188:191], v[196:199], 0
	v_mfma_f32_16x16x32_bf16 v[106:109], v[180:183], v[204:207], 0
	v_mfma_f32_16x16x32_bf16 v[98:101], v[188:191], v[204:207], 0
	v_mfma_f32_16x16x32_bf16 v[90:93], v[180:183], v[212:215], 0
	v_mfma_f32_16x16x32_bf16 v[82:85], v[188:191], v[212:215], 0
	v_mfma_f32_16x16x32_bf16 v[74:77], v[180:183], v[220:223], 0
	v_mfma_f32_16x16x32_bf16 v[66:69], v[188:191], v[220:223], 0
	v_mfma_f32_16x16x32_bf16 v[126:129], v[184:187], v[200:203], v[126:129]
	v_mfma_f32_16x16x32_bf16 v[114:117], v[192:195], v[200:203], v[114:117]
	v_mfma_f32_16x16x32_bf16 v[106:109], v[184:187], v[208:211], v[106:109]
	v_mfma_f32_16x16x32_bf16 v[98:101], v[192:195], v[208:211], v[98:101]
	v_mfma_f32_16x16x32_bf16 v[90:93], v[184:187], v[216:219], v[90:93]
	v_mfma_f32_16x16x32_bf16 v[82:85], v[192:195], v[216:219], v[82:85]
	v_mfma_f32_16x16x32_bf16 v[74:77], v[184:187], v[224:227], v[74:77]
	v_mfma_f32_16x16x32_bf16 v[66:69], v[192:195], v[224:227], v[66:69]
	s_barrier
	s_setprio 0
	s_add_u32 s98, s96, 0x40000
	s_addc_u32 s99, s97, 0
	s_add_i32 s5, s74, s23
	s_mov_b32 m0, s5
	s_nop 0
	global_load_lds_dwordx4 v132, s[96:97]
	s_add_i32 m0, s5, 0x2000
	s_add_i32 s5, s75, s23
	global_load_lds_dwordx4 v136, s[96:97]
	s_mov_b32 m0, s5
	s_nop 0
	global_load_lds_dwordx4 v132, s[98:99]
	s_add_i32 m0, s5, 0x2000
	s_nop 0
	global_load_lds_dwordx4 v136, s[98:99]
	s_mov_b32 m0, s47
	s_nop 0
	global_load_lds_dwordx4 v130, s[94:95]
	s_mov_b32 m0, s56
	s_nop 0
	global_load_lds_dwordx4 v134, s[94:95]
	ds_read_b128 v[196:199], v160 offset:16384
	ds_read_b128 v[200:203], v160 offset:17408
	ds_read_b128 v[204:207], v160 offset:18432
	ds_read_b128 v[208:211], v160 offset:19456
	ds_read_b128 v[212:215], v160 offset:20480
	ds_read_b128 v[216:219], v160 offset:21504
	ds_read_b128 v[220:223], v160 offset:22528
	ds_read_b128 v[224:227], v160 offset:23552
	s_waitcnt vmcnt(8)
	s_waitcnt lgkmcnt(0)
	s_setprio 1
	s_barrier
	v_mfma_f32_16x16x32_bf16 v[62:65], v[164:167], v[196:199], 0
	v_mfma_f32_16x16x32_bf16 v[54:57], v[172:175], v[196:199], 0
	v_mfma_f32_16x16x32_bf16 v[46:49], v[164:167], v[204:207], 0
	v_mfma_f32_16x16x32_bf16 v[38:41], v[172:175], v[204:207], 0
	v_mfma_f32_16x16x32_bf16 v[30:33], v[164:167], v[212:215], 0
	v_mfma_f32_16x16x32_bf16 v[22:25], v[172:175], v[212:215], 0
	v_mfma_f32_16x16x32_bf16 v[14:17], v[164:167], v[220:223], 0
	v_mfma_f32_16x16x32_bf16 v[6:9], v[172:175], v[220:223], 0
	v_mfma_f32_16x16x32_bf16 v[62:65], v[168:171], v[200:203], v[62:65]
	v_mfma_f32_16x16x32_bf16 v[54:57], v[176:179], v[200:203], v[54:57]
	v_mfma_f32_16x16x32_bf16 v[46:49], v[168:171], v[208:211], v[46:49]
	v_mfma_f32_16x16x32_bf16 v[38:41], v[176:179], v[208:211], v[38:41]
	v_mfma_f32_16x16x32_bf16 v[30:33], v[168:171], v[216:219], v[30:33]
	v_mfma_f32_16x16x32_bf16 v[22:25], v[176:179], v[216:219], v[22:25]
	v_mfma_f32_16x16x32_bf16 v[14:17], v[168:171], v[224:227], v[14:17]
	v_mfma_f32_16x16x32_bf16 v[6:9], v[176:179], v[224:227], v[6:9]
	s_setprio 0
	s_setprio 1
	v_mfma_f32_16x16x32_bf16 v[58:61], v[180:183], v[196:199], 0
	v_mfma_f32_16x16x32_bf16 v[50:53], v[188:191], v[196:199], 0
	v_mfma_f32_16x16x32_bf16 v[42:45], v[180:183], v[204:207], 0
	v_mfma_f32_16x16x32_bf16 v[34:37], v[188:191], v[204:207], 0
	v_mfma_f32_16x16x32_bf16 v[26:29], v[180:183], v[212:215], 0
	v_mfma_f32_16x16x32_bf16 v[18:21], v[188:191], v[212:215], 0
	v_mfma_f32_16x16x32_bf16 v[10:13], v[180:183], v[220:223], 0
	v_mfma_f32_16x16x32_bf16 v[2:5], v[188:191], v[220:223], 0
	v_mfma_f32_16x16x32_bf16 v[58:61], v[184:187], v[200:203], v[58:61]
	v_mfma_f32_16x16x32_bf16 v[50:53], v[192:195], v[200:203], v[50:53]
	v_mfma_f32_16x16x32_bf16 v[42:45], v[184:187], v[208:211], v[42:45]
	v_mfma_f32_16x16x32_bf16 v[34:37], v[192:195], v[208:211], v[34:37]
	v_mfma_f32_16x16x32_bf16 v[26:29], v[184:187], v[216:219], v[26:29]
	v_mfma_f32_16x16x32_bf16 v[18:21], v[192:195], v[216:219], v[18:21]
	v_mfma_f32_16x16x32_bf16 v[10:13], v[184:187], v[224:227], v[10:13]
	v_mfma_f32_16x16x32_bf16 v[2:5], v[192:195], v[224:227], v[2:5]
	s_barrier
	s_setprio 0
	s_add_u32 s98, s94, 0x40000
	s_addc_u32 s99, s95, 0
	s_add_i32 s5, 0, 0x18000
	s_add_i32 s45, 0, 0x1c000
	s_mov_b32 m0, s57
	s_nop 0
	global_load_lds_dwordx4 v130, s[98:99]
	s_mov_b32 m0, s58
	s_nop 0
	global_load_lds_dwordx4 v134, s[98:99]
	ds_read_b128 v[164:167], v232
	ds_read_b128 v[168:171], v232 offset:1024
	ds_read_b128 v[172:175], v232 offset:2048
	ds_read_b128 v[176:179], v232 offset:3072
	ds_read_b128 v[180:183], v233
	ds_read_b128 v[184:187], v233 offset:1024
	ds_read_b128 v[188:191], v233 offset:2048
	ds_read_b128 v[192:195], v233 offset:3072
	ds_read_b128 v[196:199], v160 offset:32768
	ds_read_b128 v[200:203], v160 offset:33792
	ds_read_b128 v[204:207], v160 offset:34816
	ds_read_b128 v[208:211], v160 offset:35840
	ds_read_b128 v[212:215], v160 offset:36864
	ds_read_b128 v[216:219], v160 offset:37888
	ds_read_b128 v[220:223], v160 offset:38912
	ds_read_b128 v[224:227], v160 offset:39936
	s_waitcnt vmcnt(8)
	s_waitcnt lgkmcnt(0)
	s_setprio 1
	s_barrier
	v_mfma_f32_16x16x32_bf16 v[122:125], v[164:167], v[196:199], v[122:125]
	v_mfma_f32_16x16x32_bf16 v[118:121], v[172:175], v[196:199], v[118:121]
	v_mfma_f32_16x16x32_bf16 v[110:113], v[164:167], v[204:207], v[110:113]
	v_mfma_f32_16x16x32_bf16 v[102:105], v[172:175], v[204:207], v[102:105]
	v_mfma_f32_16x16x32_bf16 v[94:97], v[164:167], v[212:215], v[94:97]
	v_mfma_f32_16x16x32_bf16 v[86:89], v[172:175], v[212:215], v[86:89]
	v_mfma_f32_16x16x32_bf16 v[78:81], v[164:167], v[220:223], v[78:81]
	v_mfma_f32_16x16x32_bf16 v[70:73], v[172:175], v[220:223], v[70:73]
	v_mfma_f32_16x16x32_bf16 v[122:125], v[168:171], v[200:203], v[122:125]
	v_mfma_f32_16x16x32_bf16 v[118:121], v[176:179], v[200:203], v[118:121]
	v_mfma_f32_16x16x32_bf16 v[110:113], v[168:171], v[208:211], v[110:113]
	v_mfma_f32_16x16x32_bf16 v[102:105], v[176:179], v[208:211], v[102:105]
	v_mfma_f32_16x16x32_bf16 v[94:97], v[168:171], v[216:219], v[94:97]
	v_mfma_f32_16x16x32_bf16 v[86:89], v[176:179], v[216:219], v[86:89]
	v_mfma_f32_16x16x32_bf16 v[78:81], v[168:171], v[224:227], v[78:81]
	v_mfma_f32_16x16x32_bf16 v[70:73], v[176:179], v[224:227], v[70:73]
	s_setprio 0
	s_setprio 1
	v_mfma_f32_16x16x32_bf16 v[126:129], v[180:183], v[196:199], v[126:129]
	v_mfma_f32_16x16x32_bf16 v[114:117], v[188:191], v[196:199], v[114:117]
	v_mfma_f32_16x16x32_bf16 v[106:109], v[180:183], v[204:207], v[106:109]
	v_mfma_f32_16x16x32_bf16 v[98:101], v[188:191], v[204:207], v[98:101]
	v_mfma_f32_16x16x32_bf16 v[90:93], v[180:183], v[212:215], v[90:93]
	v_mfma_f32_16x16x32_bf16 v[82:85], v[188:191], v[212:215], v[82:85]
	v_mfma_f32_16x16x32_bf16 v[74:77], v[180:183], v[220:223], v[74:77]
	v_mfma_f32_16x16x32_bf16 v[66:69], v[188:191], v[220:223], v[66:69]
	v_mfma_f32_16x16x32_bf16 v[126:129], v[184:187], v[200:203], v[126:129]
	v_mfma_f32_16x16x32_bf16 v[114:117], v[192:195], v[200:203], v[114:117]
	v_mfma_f32_16x16x32_bf16 v[106:109], v[184:187], v[208:211], v[106:109]
	v_mfma_f32_16x16x32_bf16 v[98:101], v[192:195], v[208:211], v[98:101]
	v_mfma_f32_16x16x32_bf16 v[90:93], v[184:187], v[216:219], v[90:93]
	v_mfma_f32_16x16x32_bf16 v[82:85], v[192:195], v[216:219], v[82:85]
	v_mfma_f32_16x16x32_bf16 v[74:77], v[184:187], v[224:227], v[74:77]
	v_mfma_f32_16x16x32_bf16 v[66:69], v[192:195], v[224:227], v[66:69]
	s_barrier
	s_setprio 0
	s_add_u32 s96, s96, 0x80
	s_addc_u32 s97, s97, 0
	s_add_u32 s98, s96, 0x40000
	s_addc_u32 s99, s97, 0
	s_add_u32 s94, s94, 0x80
	s_addc_u32 s95, s95, 0
	s_add_i32 s5, s5, s23
	s_mov_b32 m0, s5
	s_nop 0
	global_load_lds_dwordx4 v132, s[96:97]
	s_add_i32 m0, s5, 0x2000
	s_add_i32 s5, s45, s23
	global_load_lds_dwordx4 v136, s[96:97]
	s_mov_b32 m0, s5
	s_nop 0
	global_load_lds_dwordx4 v132, s[98:99]
	s_add_i32 m0, s5, 0x2000
	s_nop 0
	global_load_lds_dwordx4 v136, s[98:99]
	s_mov_b32 m0, s64
	s_nop 0
	global_load_lds_dwordx4 v130, s[94:95]
	s_mov_b32 m0, s65
	s_nop 0
	global_load_lds_dwordx4 v134, s[94:95]
	ds_read_b128 v[196:199], v160 offset:49152
	ds_read_b128 v[200:203], v160 offset:50176
	ds_read_b128 v[204:207], v160 offset:51200
	ds_read_b128 v[208:211], v160 offset:52224
	ds_read_b128 v[212:215], v160 offset:53248
	ds_read_b128 v[216:219], v160 offset:54272
	ds_read_b128 v[220:223], v160 offset:55296
	ds_read_b128 v[224:227], v160 offset:56320
	s_waitcnt vmcnt(8)
	s_waitcnt lgkmcnt(0)
	s_setprio 1
	s_barrier
	v_mfma_f32_16x16x32_bf16 v[62:65], v[164:167], v[196:199], v[62:65]
	v_mfma_f32_16x16x32_bf16 v[54:57], v[172:175], v[196:199], v[54:57]
	v_mfma_f32_16x16x32_bf16 v[46:49], v[164:167], v[204:207], v[46:49]
	v_mfma_f32_16x16x32_bf16 v[38:41], v[172:175], v[204:207], v[38:41]
	v_mfma_f32_16x16x32_bf16 v[30:33], v[164:167], v[212:215], v[30:33]
	v_mfma_f32_16x16x32_bf16 v[22:25], v[172:175], v[212:215], v[22:25]
	v_mfma_f32_16x16x32_bf16 v[14:17], v[164:167], v[220:223], v[14:17]
	v_mfma_f32_16x16x32_bf16 v[6:9], v[172:175], v[220:223], v[6:9]
	v_mfma_f32_16x16x32_bf16 v[62:65], v[168:171], v[200:203], v[62:65]
	v_mfma_f32_16x16x32_bf16 v[54:57], v[176:179], v[200:203], v[54:57]
	v_mfma_f32_16x16x32_bf16 v[46:49], v[168:171], v[208:211], v[46:49]
	v_mfma_f32_16x16x32_bf16 v[38:41], v[176:179], v[208:211], v[38:41]
	v_mfma_f32_16x16x32_bf16 v[30:33], v[168:171], v[216:219], v[30:33]
	v_mfma_f32_16x16x32_bf16 v[22:25], v[176:179], v[216:219], v[22:25]
	v_mfma_f32_16x16x32_bf16 v[14:17], v[168:171], v[224:227], v[14:17]
	v_mfma_f32_16x16x32_bf16 v[6:9], v[176:179], v[224:227], v[6:9]
	s_setprio 0
	s_setprio 1
	v_mfma_f32_16x16x32_bf16 v[58:61], v[180:183], v[196:199], v[58:61]
	v_mfma_f32_16x16x32_bf16 v[50:53], v[188:191], v[196:199], v[50:53]
	v_mfma_f32_16x16x32_bf16 v[42:45], v[180:183], v[204:207], v[42:45]
	v_mfma_f32_16x16x32_bf16 v[34:37], v[188:191], v[204:207], v[34:37]
	v_mfma_f32_16x16x32_bf16 v[26:29], v[180:183], v[212:215], v[26:29]
	v_mfma_f32_16x16x32_bf16 v[18:21], v[188:191], v[212:215], v[18:21]
	v_mfma_f32_16x16x32_bf16 v[10:13], v[180:183], v[220:223], v[10:13]
	v_mfma_f32_16x16x32_bf16 v[2:5], v[188:191], v[220:223], v[2:5]
	v_mfma_f32_16x16x32_bf16 v[58:61], v[184:187], v[200:203], v[58:61]
	v_mfma_f32_16x16x32_bf16 v[50:53], v[192:195], v[200:203], v[50:53]
	v_mfma_f32_16x16x32_bf16 v[42:45], v[184:187], v[208:211], v[42:45]
	v_mfma_f32_16x16x32_bf16 v[34:37], v[192:195], v[208:211], v[34:37]
	v_mfma_f32_16x16x32_bf16 v[26:29], v[184:187], v[216:219], v[26:29]
	v_mfma_f32_16x16x32_bf16 v[18:21], v[192:195], v[216:219], v[18:21]
	v_mfma_f32_16x16x32_bf16 v[10:13], v[184:187], v[224:227], v[10:13]
	v_mfma_f32_16x16x32_bf16 v[2:5], v[192:195], v[224:227], v[2:5]
	s_barrier
	s_setprio 0
	s_mov_b32 s5, s29
	s_add_u32 s88, s88, 0x100
	s_addc_u32 s89, s89, 0
	s_add_u32 s86, s86, 0x100
	s_addc_u32 s87, s87, 0
	s_cmp_ge_i32 s29, s101
	s_cbranch_scc1 .Lmy_kexit_9

.LBB0_1821:
	s_andn2_b64 vcc, exec, s[10:11]
	s_cbranch_vccnz .LBB0_1753
	s_mov_b32 s32, 1
	s_branch .LBB0_1753

.LBB0_1942:
	v_cmp_gt_i32_e32 vcc, 1, v138
	s_cbranch_vccnz .LBB0_2004
	v_lshl_add_u64 v[152:153], v[2:3], 0, s[16:17]
	v_add_u32_e32 v154, -2, v138
	s_waitcnt lgkmcnt(0)
	v_lshl_add_u64 v[150:151], v[4:5], 0, s[20:21]
	s_mov_b32 s5, 0
	s_cmp_eq_u32 s32, 1
	s_cbranch_scc0 .Lmy_nb_10
	s_mov_b32 s32, 0
	s_barrier
.Lmy_nb_10:
	s_nop 0
	v_readfirstlane_b32 s86, v152
	v_readfirstlane_b32 s87, v153
	v_readfirstlane_b32 s88, v150
	v_readfirstlane_b32 s89, v151
	v_readfirstlane_b32 s90, v146
	v_readfirstlane_b32 s91, v147
	v_readfirstlane_b32 s92, v148
	v_readfirstlane_b32 s93, v149
	v_readfirstlane_b32 s100, v154
	v_readfirstlane_b32 s101, v138
	v_add_u32_e32 v230, s72, v141
	v_add_u32_e32 v231, s73, v141
	v_add_u32_e32 v232, 0x18000, v141
	v_add_u32_e32 v233, 0x1c000, v141
	s_add_u32 s98, s86, 0xfffc0080
	s_addc_u32 s99, s87, -1
	s_cmp_eq_u32 s5, s100
	s_cselect_b64 s[94:95], s[90:91], s[98:99]
	s_cselect_b64 s[96:97], s[92:93], s[88:89]
	s_add_i32 s45, s5, 2
	s_nop 0
	s_mov_b32 m0, s74
	s_nop 0
	global_load_lds_dwordx4 v144, s[86:87]
	s_mov_b32 m0, s75
	s_nop 0
	global_load_lds_dwordx4 v142, s[86:87]
	ds_read_b128 v[164:167], v230
	ds_read_b128 v[168:171], v230 offset:1024
	ds_read_b128 v[172:175], v230 offset:2048
	ds_read_b128 v[176:179], v230 offset:3072
	ds_read_b128 v[180:183], v231
	ds_read_b128 v[184:187], v231 offset:1024
	ds_read_b128 v[188:191], v231 offset:2048
	ds_read_b128 v[192:195], v231 offset:3072
	ds_read_b128 v[196:199], v160
	ds_read_b128 v[200:203], v160 offset:1024
	ds_read_b128 v[204:207], v160 offset:2048
	ds_read_b128 v[208:211], v160 offset:3072
	ds_read_b128 v[212:215], v160 offset:4096
	ds_read_b128 v[216:219], v160 offset:5120
	ds_read_b128 v[220:223], v160 offset:6144
	ds_read_b128 v[224:227], v160 offset:7168
	s_waitcnt vmcnt(8)
	s_waitcnt lgkmcnt(0)
	s_setprio 1
	s_barrier
	v_mfma_f32_16x16x32_bf16 v[122:125], v[164:167], v[196:199], 0
	v_mfma_f32_16x16x32_bf16 v[118:121], v[172:175], v[196:199], 0
	v_mfma_f32_16x16x32_bf16 v[110:113], v[164:167], v[204:207], 0
	v_mfma_f32_16x16x32_bf16 v[102:105], v[172:175], v[204:207], 0
	v_mfma_f32_16x16x32_bf16 v[94:97], v[164:167], v[212:215], 0
	v_mfma_f32_16x16x32_bf16 v[86:89], v[172:175], v[212:215], 0
	v_mfma_f32_16x16x32_bf16 v[78:81], v[164:167], v[220:223], 0
	v_mfma_f32_16x16x32_bf16 v[70:73], v[172:175], v[220:223], 0
	v_mfma_f32_16x16x32_bf16 v[122:125], v[168:171], v[200:203], v[122:125]
	v_mfma_f32_16x16x32_bf16 v[118:121], v[176:179], v[200:203], v[118:121]
	v_mfma_f32_16x16x32_bf16 v[110:113], v[168:171], v[208:211], v[110:113]
	v_mfma_f32_16x16x32_bf16 v[102:105], v[176:179], v[208:211], v[102:105]
	v_mfma_f32_16x16x32_bf16 v[94:97], v[168:171], v[216:219], v[94:97]
	v_mfma_f32_16x16x32_bf16 v[86:89], v[176:179], v[216:219], v[86:89]
	v_mfma_f32_16x16x32_bf16 v[78:81], v[168:171], v[224:227], v[78:81]
	v_mfma_f32_16x16x32_bf16 v[70:73], v[176:179], v[224:227], v[70:73]
	s_setprio 0
	s_setprio 1
	v_mfma_f32_16x16x32_bf16 v[126:129], v[180:183], v[196:199], 0
	v_mfma_f32_16x16x32_bf16 v[114:117], v[188:191], v[196:199], 0
	v_mfma_f32_16x16x32_bf16 v[106:109], v[180:183], v[204:207], 0
	v_mfma_f32_16x16x32_bf16 v[98:101], v[188:191], v[204:207], 0
	v_mfma_f32_16x16x32_bf16 v[90:93], v[180:183], v[212:215], 0
	v_mfma_f32_16x16x32_bf16 v[82:85], v[188:191], v[212:215], 0
	v_mfma_f32_16x16x32_bf16 v[74:77], v[180:183], v[220:223], 0
	v_mfma_f32_16x16x32_bf16 v[66:69], v[188:191], v[220:223], 0
	v_mfma_f32_16x16x32_bf16 v[126:129], v[184:187], v[200:203], v[126:129]
	v_mfma_f32_16x16x32_bf16 v[114:117], v[192:195], v[200:203], v[114:117]
	v_mfma_f32_16x16x32_bf16 v[106:109], v[184:187], v[208:211], v[106:109]
	v_mfma_f32_16x16x32_bf16 v[98:101], v[192:195], v[208:211], v[98:101]
	v_mfma_f32_16x16x32_bf16 v[90:93], v[184:187], v[216:219], v[90:93]
	v_mfma_f32_16x16x32_bf16 v[82:85], v[192:195], v[216:219], v[82:85]
	v_mfma_f32_16x16x32_bf16 v[74:77], v[184:187], v[224:227], v[74:77]
	v_mfma_f32_16x16x32_bf16 v[66:69], v[192:195], v[224:227], v[66:69]
	s_barrier
	s_setprio 0
	s_add_u32 s98, s96, 0x40000
	s_addc_u32 s99, s97, 0
	s_mov_b32 m0, s76
	s_nop 0
	global_load_lds_dwordx4 v132, s[96:97]
	s_mov_b32 m0, s77
	s_add_i32 s5, s73, s25
	global_load_lds_dwordx4 v136, s[96:97]
	s_mov_b32 m0, s5
	s_nop 0
	global_load_lds_dwordx4 v132, s[98:99]
	s_add_i32 m0, s5, 0x2000
	s_nop 0
	global_load_lds_dwordx4 v136, s[98:99]
	s_mov_b32 m0, s49
	s_nop 0
	global_load_lds_dwordx4 v130, s[94:95]
	s_mov_b32 m0, s58
	s_nop 0
	global_load_lds_dwordx4 v134, s[94:95]
	ds_read_b128 v[196:199], v160 offset:16384
	ds_read_b128 v[200:203], v160 offset:17408
	ds_read_b128 v[204:207], v160 offset:18432
	ds_read_b128 v[208:211], v160 offset:19456
	ds_read_b128 v[212:215], v160 offset:20480
	ds_read_b128 v[216:219], v160 offset:21504
	ds_read_b128 v[220:223], v160 offset:22528
	ds_read_b128 v[224:227], v160 offset:23552
	s_waitcnt vmcnt(8)
	s_waitcnt lgkmcnt(0)
	s_setprio 1
	s_barrier
	v_mfma_f32_16x16x32_bf16 v[62:65], v[164:167], v[196:199], 0
	v_mfma_f32_16x16x32_bf16 v[54:57], v[172:175], v[196:199], 0
	v_mfma_f32_16x16x32_bf16 v[46:49], v[164:167], v[204:207], 0
	v_mfma_f32_16x16x32_bf16 v[38:41], v[172:175], v[204:207], 0
	v_mfma_f32_16x16x32_bf16 v[30:33], v[164:167], v[212:215], 0
	v_mfma_f32_16x16x32_bf16 v[22:25], v[172:175], v[212:215], 0
	v_mfma_f32_16x16x32_bf16 v[14:17], v[164:167], v[220:223], 0
	v_mfma_f32_16x16x32_bf16 v[6:9], v[172:175], v[220:223], 0
	v_mfma_f32_16x16x32_bf16 v[62:65], v[168:171], v[200:203], v[62:65]
	v_mfma_f32_16x16x32_bf16 v[54:57], v[176:179], v[200:203], v[54:57]
	v_mfma_f32_16x16x32_bf16 v[46:49], v[168:171], v[208:211], v[46:49]
	v_mfma_f32_16x16x32_bf16 v[38:41], v[176:179], v[208:211], v[38:41]
	v_mfma_f32_16x16x32_bf16 v[30:33], v[168:171], v[216:219], v[30:33]
	v_mfma_f32_16x16x32_bf16 v[22:25], v[176:179], v[216:219], v[22:25]
	v_mfma_f32_16x16x32_bf16 v[14:17], v[168:171], v[224:227], v[14:17]
	v_mfma_f32_16x16x32_bf16 v[6:9], v[176:179], v[224:227], v[6:9]
	s_setprio 0
	s_setprio 1
	v_mfma_f32_16x16x32_bf16 v[58:61], v[180:183], v[196:199], 0
	v_mfma_f32_16x16x32_bf16 v[50:53], v[188:191], v[196:199], 0
	v_mfma_f32_16x16x32_bf16 v[42:45], v[180:183], v[204:207], 0
	v_mfma_f32_16x16x32_bf16 v[34:37], v[188:191], v[204:207], 0
	v_mfma_f32_16x16x32_bf16 v[26:29], v[180:183], v[212:215], 0
	v_mfma_f32_16x16x32_bf16 v[18:21], v[188:191], v[212:215], 0
	v_mfma_f32_16x16x32_bf16 v[10:13], v[180:183], v[220:223], 0
	v_mfma_f32_16x16x32_bf16 v[2:5], v[188:191], v[220:223], 0
	v_mfma_f32_16x16x32_bf16 v[58:61], v[184:187], v[200:203], v[58:61]
	v_mfma_f32_16x16x32_bf16 v[50:53], v[192:195], v[200:203], v[50:53]
	v_mfma_f32_16x16x32_bf16 v[42:45], v[184:187], v[208:211], v[42:45]
	v_mfma_f32_16x16x32_bf16 v[34:37], v[192:195], v[208:211], v[34:37]
	v_mfma_f32_16x16x32_bf16 v[26:29], v[184:187], v[216:219], v[26:29]
	v_mfma_f32_16x16x32_bf16 v[18:21], v[192:195], v[216:219], v[18:21]
	v_mfma_f32_16x16x32_bf16 v[10:13], v[184:187], v[224:227], v[10:13]
	v_mfma_f32_16x16x32_bf16 v[2:5], v[192:195], v[224:227], v[2:5]
	s_barrier
	s_setprio 0
	s_add_u32 s98, s94, 0x40000
	s_addc_u32 s99, s95, 0
	s_add_i32 s5, 0, 0x18000
	s_add_i32 s47, 0, 0x1c000
	s_mov_b32 m0, s59
	s_nop 0
	global_load_lds_dwordx4 v130, s[98:99]
	s_mov_b32 m0, s60
	s_nop 0
	global_load_lds_dwordx4 v134, s[98:99]
	ds_read_b128 v[164:167], v232
	ds_read_b128 v[168:171], v232 offset:1024
	ds_read_b128 v[172:175], v232 offset:2048
	ds_read_b128 v[176:179], v232 offset:3072
	ds_read_b128 v[180:183], v233
	ds_read_b128 v[184:187], v233 offset:1024
	ds_read_b128 v[188:191], v233 offset:2048
	ds_read_b128 v[192:195], v233 offset:3072
	ds_read_b128 v[196:199], v160 offset:32768
	ds_read_b128 v[200:203], v160 offset:33792
	ds_read_b128 v[204:207], v160 offset:34816
	ds_read_b128 v[208:211], v160 offset:35840
	ds_read_b128 v[212:215], v160 offset:36864
	ds_read_b128 v[216:219], v160 offset:37888
	ds_read_b128 v[220:223], v160 offset:38912
	ds_read_b128 v[224:227], v160 offset:39936
	s_waitcnt vmcnt(8)
	s_waitcnt lgkmcnt(0)
	s_setprio 1
	s_barrier
	v_mfma_f32_16x16x32_bf16 v[122:125], v[164:167], v[196:199], v[122:125]
	v_mfma_f32_16x16x32_bf16 v[118:121], v[172:175], v[196:199], v[118:121]
	v_mfma_f32_16x16x32_bf16 v[110:113], v[164:167], v[204:207], v[110:113]
	v_mfma_f32_16x16x32_bf16 v[102:105], v[172:175], v[204:207], v[102:105]
	v_mfma_f32_16x16x32_bf16 v[94:97], v[164:167], v[212:215], v[94:97]
	v_mfma_f32_16x16x32_bf16 v[86:89], v[172:175], v[212:215], v[86:89]
	v_mfma_f32_16x16x32_bf16 v[78:81], v[164:167], v[220:223], v[78:81]
	v_mfma_f32_16x16x32_bf16 v[70:73], v[172:175], v[220:223], v[70:73]
	v_mfma_f32_16x16x32_bf16 v[122:125], v[168:171], v[200:203], v[122:125]
	v_mfma_f32_16x16x32_bf16 v[118:121], v[176:179], v[200:203], v[118:121]
	v_mfma_f32_16x16x32_bf16 v[110:113], v[168:171], v[208:211], v[110:113]
	v_mfma_f32_16x16x32_bf16 v[102:105], v[176:179], v[208:211], v[102:105]
	v_mfma_f32_16x16x32_bf16 v[94:97], v[168:171], v[216:219], v[94:97]
	v_mfma_f32_16x16x32_bf16 v[86:89], v[176:179], v[216:219], v[86:89]
	v_mfma_f32_16x16x32_bf16 v[78:81], v[168:171], v[224:227], v[78:81]
	v_mfma_f32_16x16x32_bf16 v[70:73], v[176:179], v[224:227], v[70:73]
	s_setprio 0
	s_setprio 1
	v_mfma_f32_16x16x32_bf16 v[126:129], v[180:183], v[196:199], v[126:129]
	v_mfma_f32_16x16x32_bf16 v[114:117], v[188:191], v[196:199], v[114:117]
	v_mfma_f32_16x16x32_bf16 v[106:109], v[180:183], v[204:207], v[106:109]
	v_mfma_f32_16x16x32_bf16 v[98:101], v[188:191], v[204:207], v[98:101]
	v_mfma_f32_16x16x32_bf16 v[90:93], v[180:183], v[212:215], v[90:93]
	v_mfma_f32_16x16x32_bf16 v[82:85], v[188:191], v[212:215], v[82:85]
	v_mfma_f32_16x16x32_bf16 v[74:77], v[180:183], v[220:223], v[74:77]
	v_mfma_f32_16x16x32_bf16 v[66:69], v[188:191], v[220:223], v[66:69]
	v_mfma_f32_16x16x32_bf16 v[126:129], v[184:187], v[200:203], v[126:129]
	v_mfma_f32_16x16x32_bf16 v[114:117], v[192:195], v[200:203], v[114:117]
	v_mfma_f32_16x16x32_bf16 v[106:109], v[184:187], v[208:211], v[106:109]
	v_mfma_f32_16x16x32_bf16 v[98:101], v[192:195], v[208:211], v[98:101]
	v_mfma_f32_16x16x32_bf16 v[90:93], v[184:187], v[216:219], v[90:93]
	v_mfma_f32_16x16x32_bf16 v[82:85], v[192:195], v[216:219], v[82:85]
	v_mfma_f32_16x16x32_bf16 v[74:77], v[184:187], v[224:227], v[74:77]
	v_mfma_f32_16x16x32_bf16 v[66:69], v[192:195], v[224:227], v[66:69]
	s_barrier
	s_setprio 0
	s_add_u32 s96, s96, 0x80
	s_addc_u32 s97, s97, 0
	s_add_u32 s98, s96, 0x40000
	s_addc_u32 s99, s97, 0
	s_add_u32 s94, s94, 0x80
	s_addc_u32 s95, s95, 0
	s_add_i32 s5, s5, s25
	s_mov_b32 m0, s5
	s_nop 0
	global_load_lds_dwordx4 v132, s[96:97]
	s_add_i32 m0, s5, 0x2000
	s_add_i32 s5, s47, s25
	global_load_lds_dwordx4 v136, s[96:97]
	s_mov_b32 m0, s5
	s_nop 0
	global_load_lds_dwordx4 v132, s[98:99]
	s_add_i32 m0, s5, 0x2000
	s_nop 0
	global_load_lds_dwordx4 v136, s[98:99]
	s_mov_b32 m0, s61
	s_nop 0
	global_load_lds_dwordx4 v130, s[94:95]
	s_mov_b32 m0, s62
	s_nop 0
	global_load_lds_dwordx4 v134, s[94:95]
	ds_read_b128 v[196:199], v160 offset:49152
	ds_read_b128 v[200:203], v160 offset:50176
	ds_read_b128 v[204:207], v160 offset:51200
	ds_read_b128 v[208:211], v160 offset:52224
	ds_read_b128 v[212:215], v160 offset:53248
	ds_read_b128 v[216:219], v160 offset:54272
	ds_read_b128 v[220:223], v160 offset:55296
	ds_read_b128 v[224:227], v160 offset:56320
	s_waitcnt vmcnt(8)
	s_waitcnt lgkmcnt(0)
	s_setprio 1
	s_barrier
	v_mfma_f32_16x16x32_bf16 v[62:65], v[164:167], v[196:199], v[62:65]
	v_mfma_f32_16x16x32_bf16 v[54:57], v[172:175], v[196:199], v[54:57]
	v_mfma_f32_16x16x32_bf16 v[46:49], v[164:167], v[204:207], v[46:49]
	v_mfma_f32_16x16x32_bf16 v[38:41], v[172:175], v[204:207], v[38:41]
	v_mfma_f32_16x16x32_bf16 v[30:33], v[164:167], v[212:215], v[30:33]
	v_mfma_f32_16x16x32_bf16 v[22:25], v[172:175], v[212:215], v[22:25]
	v_mfma_f32_16x16x32_bf16 v[14:17], v[164:167], v[220:223], v[14:17]
	v_mfma_f32_16x16x32_bf16 v[6:9], v[172:175], v[220:223], v[6:9]
	v_mfma_f32_16x16x32_bf16 v[62:65], v[168:171], v[200:203], v[62:65]
	v_mfma_f32_16x16x32_bf16 v[54:57], v[176:179], v[200:203], v[54:57]
	v_mfma_f32_16x16x32_bf16 v[46:49], v[168:171], v[208:211], v[46:49]
	v_mfma_f32_16x16x32_bf16 v[38:41], v[176:179], v[208:211], v[38:41]
	v_mfma_f32_16x16x32_bf16 v[30:33], v[168:171], v[216:219], v[30:33]
	v_mfma_f32_16x16x32_bf16 v[22:25], v[176:179], v[216:219], v[22:25]
	v_mfma_f32_16x16x32_bf16 v[14:17], v[168:171], v[224:227], v[14:17]
	v_mfma_f32_16x16x32_bf16 v[6:9], v[176:179], v[224:227], v[6:9]
	s_setprio 0
	s_setprio 1
	v_mfma_f32_16x16x32_bf16 v[58:61], v[180:183], v[196:199], v[58:61]
	v_mfma_f32_16x16x32_bf16 v[50:53], v[188:191], v[196:199], v[50:53]
	v_mfma_f32_16x16x32_bf16 v[42:45], v[180:183], v[204:207], v[42:45]
	v_mfma_f32_16x16x32_bf16 v[34:37], v[188:191], v[204:207], v[34:37]
	v_mfma_f32_16x16x32_bf16 v[26:29], v[180:183], v[212:215], v[26:29]
	v_mfma_f32_16x16x32_bf16 v[18:21], v[188:191], v[212:215], v[18:21]
	v_mfma_f32_16x16x32_bf16 v[10:13], v[180:183], v[220:223], v[10:13]
	v_mfma_f32_16x16x32_bf16 v[2:5], v[188:191], v[220:223], v[2:5]
	v_mfma_f32_16x16x32_bf16 v[58:61], v[184:187], v[200:203], v[58:61]
	v_mfma_f32_16x16x32_bf16 v[50:53], v[192:195], v[200:203], v[50:53]
	v_mfma_f32_16x16x32_bf16 v[42:45], v[184:187], v[208:211], v[42:45]
	v_mfma_f32_16x16x32_bf16 v[34:37], v[192:195], v[208:211], v[34:37]
	v_mfma_f32_16x16x32_bf16 v[26:29], v[184:187], v[216:219], v[26:29]
	v_mfma_f32_16x16x32_bf16 v[18:21], v[192:195], v[216:219], v[18:21]
	v_mfma_f32_16x16x32_bf16 v[10:13], v[184:187], v[224:227], v[10:13]
	v_mfma_f32_16x16x32_bf16 v[2:5], v[192:195], v[224:227], v[2:5]
	s_barrier
	s_setprio 0
	s_mov_b32 s5, s45
	s_add_u32 s88, s88, 0x100
	s_addc_u32 s89, s89, 0
	s_add_u32 s86, s86, 0x100
	s_addc_u32 s87, s87, 0
	s_cmp_ge_i32 s45, s101
	s_cbranch_scc1 .Lmy_kexit_10

.LBB0_2073:
	v_cmp_gt_i32_e32 vcc, 1, v156
	s_cbranch_vccnz .LBB0_2135
	v_lshl_add_u64 v[152:153], v[2:3], 0, s[18:19]
	v_add_u32_e32 v138, -2, v156
	s_mov_b32 s4, 0
	s_cmp_eq_u32 s32, 1
	s_cbranch_scc0 .Lmy_nb_11
	s_mov_b32 s32, 0
	s_barrier
.Lmy_nb_11:
	s_nop 0
	v_readfirstlane_b32 s86, v150
	v_readfirstlane_b32 s87, v151
	v_readfirstlane_b32 s88, v152
	v_readfirstlane_b32 s89, v153
	v_readfirstlane_b32 s90, v146
	v_readfirstlane_b32 s91, v147
	v_readfirstlane_b32 s92, v148
	v_readfirstlane_b32 s93, v149
	v_readfirstlane_b32 s100, v138
	v_readfirstlane_b32 s101, v156
	v_add_u32_e32 v230, s65, v141
	v_add_u32_e32 v231, s66, v141
	v_add_u32_e32 v232, 0x18000, v141
	v_add_u32_e32 v233, 0x1c000, v141
	s_add_u32 s98, s86, 0x100
	s_addc_u32 s99, s87, 0
	s_cmp_eq_u32 s4, s100
	s_cselect_b64 s[94:95], s[90:91], s[98:99]
	s_cselect_b64 s[96:97], s[92:93], s[88:89]
	s_add_i32 s5, s4, 2
	s_nop 0
	s_add_i32 m0, s44, 0xc000
	s_nop 0
	global_load_lds_dwordx4 v144, s[86:87]
	s_add_i32 m0, s44, 0xe000
	s_nop 0
	global_load_lds_dwordx4 v142, s[86:87]
	ds_read_b128 v[164:167], v230
	ds_read_b128 v[168:171], v230 offset:1024
	ds_read_b128 v[172:175], v230 offset:2048
	ds_read_b128 v[176:179], v230 offset:3072
	ds_read_b128 v[180:183], v231
	ds_read_b128 v[184:187], v231 offset:1024
	ds_read_b128 v[188:191], v231 offset:2048
	ds_read_b128 v[192:195], v231 offset:3072
	ds_read_b128 v[196:199], v160
	ds_read_b128 v[200:203], v160 offset:1024
	ds_read_b128 v[204:207], v160 offset:2048
	ds_read_b128 v[208:211], v160 offset:3072
	ds_read_b128 v[212:215], v160 offset:4096
	ds_read_b128 v[216:219], v160 offset:5120
	ds_read_b128 v[220:223], v160 offset:6144
	ds_read_b128 v[224:227], v160 offset:7168
	s_waitcnt vmcnt(8)
	s_waitcnt lgkmcnt(0)
	s_setprio 1
	s_barrier
	v_mfma_f32_16x16x32_bf16 v[122:125], v[164:167], v[196:199], 0
	v_mfma_f32_16x16x32_bf16 v[118:121], v[172:175], v[196:199], 0
	v_mfma_f32_16x16x32_bf16 v[110:113], v[164:167], v[204:207], 0
	v_mfma_f32_16x16x32_bf16 v[102:105], v[172:175], v[204:207], 0
	v_mfma_f32_16x16x32_bf16 v[94:97], v[164:167], v[212:215], 0
	v_mfma_f32_16x16x32_bf16 v[86:89], v[172:175], v[212:215], 0
	v_mfma_f32_16x16x32_bf16 v[78:81], v[164:167], v[220:223], 0
	v_mfma_f32_16x16x32_bf16 v[70:73], v[172:175], v[220:223], 0
	v_mfma_f32_16x16x32_bf16 v[122:125], v[168:171], v[200:203], v[122:125]
	v_mfma_f32_16x16x32_bf16 v[118:121], v[176:179], v[200:203], v[118:121]
	v_mfma_f32_16x16x32_bf16 v[110:113], v[168:171], v[208:211], v[110:113]
	v_mfma_f32_16x16x32_bf16 v[102:105], v[176:179], v[208:211], v[102:105]
	v_mfma_f32_16x16x32_bf16 v[94:97], v[168:171], v[216:219], v[94:97]
	v_mfma_f32_16x16x32_bf16 v[86:89], v[176:179], v[216:219], v[86:89]
	v_mfma_f32_16x16x32_bf16 v[78:81], v[168:171], v[224:227], v[78:81]
	v_mfma_f32_16x16x32_bf16 v[70:73], v[176:179], v[224:227], v[70:73]
	s_setprio 0
	s_setprio 1
	v_mfma_f32_16x16x32_bf16 v[126:129], v[180:183], v[196:199], 0
	v_mfma_f32_16x16x32_bf16 v[114:117], v[188:191], v[196:199], 0
	v_mfma_f32_16x16x32_bf16 v[106:109], v[180:183], v[204:207], 0
	v_mfma_f32_16x16x32_bf16 v[98:101], v[188:191], v[204:207], 0
	v_mfma_f32_16x16x32_bf16 v[90:93], v[180:183], v[212:215], 0
	v_mfma_f32_16x16x32_bf16 v[82:85], v[188:191], v[212:215], 0
	v_mfma_f32_16x16x32_bf16 v[74:77], v[180:183], v[220:223], 0
	v_mfma_f32_16x16x32_bf16 v[66:69], v[188:191], v[220:223], 0
	v_mfma_f32_16x16x32_bf16 v[126:129], v[184:187], v[200:203], v[126:129]
	v_mfma_f32_16x16x32_bf16 v[114:117], v[192:195], v[200:203], v[114:117]
	v_mfma_f32_16x16x32_bf16 v[106:109], v[184:187], v[208:211], v[106:109]
	v_mfma_f32_16x16x32_bf16 v[98:101], v[192:195], v[208:211], v[98:101]
	v_mfma_f32_16x16x32_bf16 v[90:93], v[184:187], v[216:219], v[90:93]
	v_mfma_f32_16x16x32_bf16 v[82:85], v[192:195], v[216:219], v[82:85]
	v_mfma_f32_16x16x32_bf16 v[74:77], v[184:187], v[224:227], v[74:77]
	v_mfma_f32_16x16x32_bf16 v[66:69], v[192:195], v[224:227], v[66:69]
	s_barrier
	s_setprio 0
	s_add_u32 s98, s96, 0xb0000
	s_addc_u32 s99, s97, 0
	s_add_i32 s4, s65, s21
	s_mov_b32 m0, s4
	s_nop 0
	global_load_lds_dwordx4 v132, s[96:97]
	s_add_i32 m0, s4, 0x2000
	s_add_i32 s4, s66, s21
	global_load_lds_dwordx4 v136, s[96:97]
	s_mov_b32 m0, s4
	s_nop 0
	global_load_lds_dwordx4 v132, s[98:99]
	s_add_i32 m0, s4, 0x2000
	s_nop 0
	global_load_lds_dwordx4 v136, s[98:99]
	s_mov_b32 m0, s44
	s_nop 0
	global_load_lds_dwordx4 v130, s[94:95]
	s_mov_b32 m0, s45
	s_nop 0
	global_load_lds_dwordx4 v134, s[94:95]
	ds_read_b128 v[196:199], v160 offset:16384
	ds_read_b128 v[200:203], v160 offset:17408
	ds_read_b128 v[204:207], v160 offset:18432
	ds_read_b128 v[208:211], v160 offset:19456
	ds_read_b128 v[212:215], v160 offset:20480
	ds_read_b128 v[216:219], v160 offset:21504
	ds_read_b128 v[220:223], v160 offset:22528
	ds_read_b128 v[224:227], v160 offset:23552
	s_waitcnt vmcnt(8)
	s_waitcnt lgkmcnt(0)
	s_setprio 1
	s_barrier
	v_mfma_f32_16x16x32_bf16 v[62:65], v[164:167], v[196:199], 0
	v_mfma_f32_16x16x32_bf16 v[54:57], v[172:175], v[196:199], 0
	v_mfma_f32_16x16x32_bf16 v[46:49], v[164:167], v[204:207], 0
	v_mfma_f32_16x16x32_bf16 v[38:41], v[172:175], v[204:207], 0
	v_mfma_f32_16x16x32_bf16 v[30:33], v[164:167], v[212:215], 0
	v_mfma_f32_16x16x32_bf16 v[22:25], v[172:175], v[212:215], 0
	v_mfma_f32_16x16x32_bf16 v[14:17], v[164:167], v[220:223], 0
	v_mfma_f32_16x16x32_bf16 v[6:9], v[172:175], v[220:223], 0
	v_mfma_f32_16x16x32_bf16 v[62:65], v[168:171], v[200:203], v[62:65]
	v_mfma_f32_16x16x32_bf16 v[54:57], v[176:179], v[200:203], v[54:57]
	v_mfma_f32_16x16x32_bf16 v[46:49], v[168:171], v[208:211], v[46:49]
	v_mfma_f32_16x16x32_bf16 v[38:41], v[176:179], v[208:211], v[38:41]
	v_mfma_f32_16x16x32_bf16 v[30:33], v[168:171], v[216:219], v[30:33]
	v_mfma_f32_16x16x32_bf16 v[22:25], v[176:179], v[216:219], v[22:25]
	v_mfma_f32_16x16x32_bf16 v[14:17], v[168:171], v[224:227], v[14:17]
	v_mfma_f32_16x16x32_bf16 v[6:9], v[176:179], v[224:227], v[6:9]
	s_setprio 0
	s_setprio 1
	v_mfma_f32_16x16x32_bf16 v[58:61], v[180:183], v[196:199], 0
	v_mfma_f32_16x16x32_bf16 v[50:53], v[188:191], v[196:199], 0
	v_mfma_f32_16x16x32_bf16 v[42:45], v[180:183], v[204:207], 0
	v_mfma_f32_16x16x32_bf16 v[34:37], v[188:191], v[204:207], 0
	v_mfma_f32_16x16x32_bf16 v[26:29], v[180:183], v[212:215], 0
	v_mfma_f32_16x16x32_bf16 v[18:21], v[188:191], v[212:215], 0
	v_mfma_f32_16x16x32_bf16 v[10:13], v[180:183], v[220:223], 0
	v_mfma_f32_16x16x32_bf16 v[2:5], v[188:191], v[220:223], 0
	v_mfma_f32_16x16x32_bf16 v[58:61], v[184:187], v[200:203], v[58:61]
	v_mfma_f32_16x16x32_bf16 v[50:53], v[192:195], v[200:203], v[50:53]
	v_mfma_f32_16x16x32_bf16 v[42:45], v[184:187], v[208:211], v[42:45]
	v_mfma_f32_16x16x32_bf16 v[34:37], v[192:195], v[208:211], v[34:37]
	v_mfma_f32_16x16x32_bf16 v[26:29], v[184:187], v[216:219], v[26:29]
	v_mfma_f32_16x16x32_bf16 v[18:21], v[192:195], v[216:219], v[18:21]
	v_mfma_f32_16x16x32_bf16 v[10:13], v[184:187], v[224:227], v[10:13]
	v_mfma_f32_16x16x32_bf16 v[2:5], v[192:195], v[224:227], v[2:5]
	s_barrier
	s_setprio 0
	s_add_u32 s98, s94, 0xb0000
	s_addc_u32 s99, s95, 0
	s_add_i32 s4, 0, 0x18000
	s_add_i32 s25, 0, 0x1c000
	s_mov_b32 m0, s46
	s_nop 0
	global_load_lds_dwordx4 v130, s[98:99]
	s_mov_b32 m0, s47
	s_nop 0
	global_load_lds_dwordx4 v134, s[98:99]
	ds_read_b128 v[164:167], v232
	ds_read_b128 v[168:171], v232 offset:1024
	ds_read_b128 v[172:175], v232 offset:2048
	ds_read_b128 v[176:179], v232 offset:3072
	ds_read_b128 v[180:183], v233
	ds_read_b128 v[184:187], v233 offset:1024
	ds_read_b128 v[188:191], v233 offset:2048
	ds_read_b128 v[192:195], v233 offset:3072
	ds_read_b128 v[196:199], v160 offset:32768
	ds_read_b128 v[200:203], v160 offset:33792
	ds_read_b128 v[204:207], v160 offset:34816
	ds_read_b128 v[208:211], v160 offset:35840
	ds_read_b128 v[212:215], v160 offset:36864
	ds_read_b128 v[216:219], v160 offset:37888
	ds_read_b128 v[220:223], v160 offset:38912
	ds_read_b128 v[224:227], v160 offset:39936
	s_waitcnt vmcnt(8)
	s_waitcnt lgkmcnt(0)
	s_setprio 1
	s_barrier
	v_mfma_f32_16x16x32_bf16 v[122:125], v[164:167], v[196:199], v[122:125]
	v_mfma_f32_16x16x32_bf16 v[118:121], v[172:175], v[196:199], v[118:121]
	v_mfma_f32_16x16x32_bf16 v[110:113], v[164:167], v[204:207], v[110:113]
	v_mfma_f32_16x16x32_bf16 v[102:105], v[172:175], v[204:207], v[102:105]
	v_mfma_f32_16x16x32_bf16 v[94:97], v[164:167], v[212:215], v[94:97]
	v_mfma_f32_16x16x32_bf16 v[86:89], v[172:175], v[212:215], v[86:89]
	v_mfma_f32_16x16x32_bf16 v[78:81], v[164:167], v[220:223], v[78:81]
	v_mfma_f32_16x16x32_bf16 v[70:73], v[172:175], v[220:223], v[70:73]
	v_mfma_f32_16x16x32_bf16 v[122:125], v[168:171], v[200:203], v[122:125]
	v_mfma_f32_16x16x32_bf16 v[118:121], v[176:179], v[200:203], v[118:121]
	v_mfma_f32_16x16x32_bf16 v[110:113], v[168:171], v[208:211], v[110:113]
	v_mfma_f32_16x16x32_bf16 v[102:105], v[176:179], v[208:211], v[102:105]
	v_mfma_f32_16x16x32_bf16 v[94:97], v[168:171], v[216:219], v[94:97]
	v_mfma_f32_16x16x32_bf16 v[86:89], v[176:179], v[216:219], v[86:89]
	v_mfma_f32_16x16x32_bf16 v[78:81], v[168:171], v[224:227], v[78:81]
	v_mfma_f32_16x16x32_bf16 v[70:73], v[176:179], v[224:227], v[70:73]
	s_setprio 0
	s_setprio 1
	v_mfma_f32_16x16x32_bf16 v[126:129], v[180:183], v[196:199], v[126:129]
	v_mfma_f32_16x16x32_bf16 v[114:117], v[188:191], v[196:199], v[114:117]
	v_mfma_f32_16x16x32_bf16 v[106:109], v[180:183], v[204:207], v[106:109]
	v_mfma_f32_16x16x32_bf16 v[98:101], v[188:191], v[204:207], v[98:101]
	v_mfma_f32_16x16x32_bf16 v[90:93], v[180:183], v[212:215], v[90:93]
	v_mfma_f32_16x16x32_bf16 v[82:85], v[188:191], v[212:215], v[82:85]
	v_mfma_f32_16x16x32_bf16 v[74:77], v[180:183], v[220:223], v[74:77]
	v_mfma_f32_16x16x32_bf16 v[66:69], v[188:191], v[220:223], v[66:69]
	v_mfma_f32_16x16x32_bf16 v[126:129], v[184:187], v[200:203], v[126:129]
	v_mfma_f32_16x16x32_bf16 v[114:117], v[192:195], v[200:203], v[114:117]
	v_mfma_f32_16x16x32_bf16 v[106:109], v[184:187], v[208:211], v[106:109]
	v_mfma_f32_16x16x32_bf16 v[98:101], v[192:195], v[208:211], v[98:101]
	v_mfma_f32_16x16x32_bf16 v[90:93], v[184:187], v[216:219], v[90:93]
	v_mfma_f32_16x16x32_bf16 v[82:85], v[192:195], v[216:219], v[82:85]
	v_mfma_f32_16x16x32_bf16 v[74:77], v[184:187], v[224:227], v[74:77]
	v_mfma_f32_16x16x32_bf16 v[66:69], v[192:195], v[224:227], v[66:69]
	s_barrier
	s_setprio 0
	s_add_u32 s96, s96, 0x80
	s_addc_u32 s97, s97, 0
	s_add_u32 s98, s96, 0xb0000
	s_addc_u32 s99, s97, 0
	s_add_u32 s94, s94, 0x80
	s_addc_u32 s95, s95, 0
	s_add_i32 s4, s4, s21
	s_mov_b32 m0, s4
	s_nop 0
	global_load_lds_dwordx4 v132, s[96:97]
	s_add_i32 m0, s4, 0x2000
	s_add_i32 s4, s25, s21
	global_load_lds_dwordx4 v136, s[96:97]
	s_mov_b32 m0, s4
	s_nop 0
	global_load_lds_dwordx4 v132, s[98:99]
	s_add_i32 m0, s4, 0x2000
	s_nop 0
	global_load_lds_dwordx4 v136, s[98:99]
	s_mov_b32 m0, s57
	s_nop 0
	global_load_lds_dwordx4 v130, s[94:95]
	s_mov_b32 m0, s58
	s_nop 0
	global_load_lds_dwordx4 v134, s[94:95]
	ds_read_b128 v[196:199], v160 offset:49152
	ds_read_b128 v[200:203], v160 offset:50176
	ds_read_b128 v[204:207], v160 offset:51200
	ds_read_b128 v[208:211], v160 offset:52224
	ds_read_b128 v[212:215], v160 offset:53248
	ds_read_b128 v[216:219], v160 offset:54272
	ds_read_b128 v[220:223], v160 offset:55296
	ds_read_b128 v[224:227], v160 offset:56320
	s_waitcnt vmcnt(8)
	s_waitcnt lgkmcnt(0)
	s_setprio 1
	s_barrier
	v_mfma_f32_16x16x32_bf16 v[62:65], v[164:167], v[196:199], v[62:65]
	v_mfma_f32_16x16x32_bf16 v[54:57], v[172:175], v[196:199], v[54:57]
	v_mfma_f32_16x16x32_bf16 v[46:49], v[164:167], v[204:207], v[46:49]
	v_mfma_f32_16x16x32_bf16 v[38:41], v[172:175], v[204:207], v[38:41]
	v_mfma_f32_16x16x32_bf16 v[30:33], v[164:167], v[212:215], v[30:33]
	v_mfma_f32_16x16x32_bf16 v[22:25], v[172:175], v[212:215], v[22:25]
	v_mfma_f32_16x16x32_bf16 v[14:17], v[164:167], v[220:223], v[14:17]
	v_mfma_f32_16x16x32_bf16 v[6:9], v[172:175], v[220:223], v[6:9]
	v_mfma_f32_16x16x32_bf16 v[62:65], v[168:171], v[200:203], v[62:65]
	v_mfma_f32_16x16x32_bf16 v[54:57], v[176:179], v[200:203], v[54:57]
	v_mfma_f32_16x16x32_bf16 v[46:49], v[168:171], v[208:211], v[46:49]
	v_mfma_f32_16x16x32_bf16 v[38:41], v[176:179], v[208:211], v[38:41]
	v_mfma_f32_16x16x32_bf16 v[30:33], v[168:171], v[216:219], v[30:33]
	v_mfma_f32_16x16x32_bf16 v[22:25], v[176:179], v[216:219], v[22:25]
	v_mfma_f32_16x16x32_bf16 v[14:17], v[168:171], v[224:227], v[14:17]
	v_mfma_f32_16x16x32_bf16 v[6:9], v[176:179], v[224:227], v[6:9]
	s_setprio 0
	s_setprio 1
	v_mfma_f32_16x16x32_bf16 v[58:61], v[180:183], v[196:199], v[58:61]
	v_mfma_f32_16x16x32_bf16 v[50:53], v[188:191], v[196:199], v[50:53]
	v_mfma_f32_16x16x32_bf16 v[42:45], v[180:183], v[204:207], v[42:45]
	v_mfma_f32_16x16x32_bf16 v[34:37], v[188:191], v[204:207], v[34:37]
	v_mfma_f32_16x16x32_bf16 v[26:29], v[180:183], v[212:215], v[26:29]
	v_mfma_f32_16x16x32_bf16 v[18:21], v[188:191], v[212:215], v[18:21]
	v_mfma_f32_16x16x32_bf16 v[10:13], v[180:183], v[220:223], v[10:13]
	v_mfma_f32_16x16x32_bf16 v[2:5], v[188:191], v[220:223], v[2:5]
	v_mfma_f32_16x16x32_bf16 v[58:61], v[184:187], v[200:203], v[58:61]
	v_mfma_f32_16x16x32_bf16 v[50:53], v[192:195], v[200:203], v[50:53]
	v_mfma_f32_16x16x32_bf16 v[42:45], v[184:187], v[208:211], v[42:45]
	v_mfma_f32_16x16x32_bf16 v[34:37], v[192:195], v[208:211], v[34:37]
	v_mfma_f32_16x16x32_bf16 v[26:29], v[184:187], v[216:219], v[26:29]
	v_mfma_f32_16x16x32_bf16 v[18:21], v[192:195], v[216:219], v[18:21]
	v_mfma_f32_16x16x32_bf16 v[10:13], v[184:187], v[224:227], v[10:13]
	v_mfma_f32_16x16x32_bf16 v[2:5], v[192:195], v[224:227], v[2:5]
	s_barrier
	s_setprio 0
	s_mov_b32 s4, s5
	s_add_u32 s88, s88, 0x100
	s_addc_u32 s89, s89, 0
	s_add_u32 s86, s86, 0x100
	s_addc_u32 s87, s87, 0
	s_cmp_ge_i32 s5, s101
	s_cbranch_scc1 .Lmy_kexit_11
